# P4 out-projection: one hand-written 256x256 block (K=2048, LDS-DMA double-buffered MFMA loop) per workgroup instead of two 256x128 compiler tiles; residual epilogue with 8 loads in flight
# speedup vs baseline: 1.0161x; 1.0161x over previous
; DI int opaque_tid() { int t = threadIdx.x; asm volatile("" : "+v"(t)); return t; }
; template <bool SWAP, class Epi>
; DI void gemm_tile(const u16* __restrict__ A, int lda, const u16* __restrict__ Bw, int ldb, int K, char* lds, Epi epi) {
;   const int tid = opaque_tid(), lane = tid & 63, w = tid >> 6, r = lane & 31, h = lane >> 5;
;   const int wm = w & 3, wn = w >> 2;
;   f32x16 acc[2][2];
; #pragma unroll
;   for (int a = 0; a < 2; ++a)
; #pragma unroll
;     for (int b = 0; b < 2; ++b)
; #pragma unroll
;       for (int i = 0; i < 16; ++i) acc[a][b][i] = 0.f;
;   const int lrow = tid >> 3, lkc = tid & 7;
;   u32x4 ra0[4], rb0[2], ra1[4], rb1[2];
;   const u16* ap = A + (size_t)lrow * lda + lkc * 8;
;   const u16* bp = Bw + (size_t)lrow * ldb + lkc * 8;
;   const int nk = K >> 6;
;   auto gload = [&](int kt, u32x4* ra, u32x4* rb) {
; #pragma unroll
;     for (int j = 0; j < 4; ++j) ra[j] = *(const u32x4*)(ap + (size_t)(64 * j) * lda + kt * 64);
; #pragma unroll
;     for (int j = 0; j < 2; ++j) rb[j] = *(const u32x4*)(bp + (size_t)(64 * j) * ldb + kt * 64);
;   };
;   auto lstore = [&](int st, const u32x4* ra, const u32x4* rb) {
;     char* base = lds + st * GEMM_STAGE;
; #pragma unroll
;     for (int j = 0; j < 4; ++j) *(u32x4*)(base + ((lrow + 64 * j) * 72 + lkc * 8) * 2) = ra[j];
; #pragma unroll
;     for (int j = 0; j < 2; ++j) *(u32x4*)(base + 36864 + ((lrow + 64 * j) * 72 + lkc * 8) * 2) = rb[j];
;   };
;   auto compute = [&](int st) {
;     const char* as = lds + st * GEMM_STAGE;
;     const char* bs = as + 36864;
; #pragma unroll
;     for (int ks = 0; ks < 4; ++ks) {
;       bf16x8 af[2], bfr[2];
; #pragma unroll
;       for (int mi = 0; mi < 2; ++mi) af[mi] = *(const bf16x8*)(as + ((wm * 64 + mi * 32 + r) * 72 + ks * 16 + 8 * h) * 2);
; #pragma unroll
; DI void outproj_tile(const Params& p, int l, int mt, int nt, char* lds, int khalf) {
;   const int tid = opaque_tid(), lane = tid & 63, w = tid >> 6, r = lane & 31, h = lane >> 5;
;   const int wm = w & 3, wn = w >> 2;
;   const int m0 = mt * 256;
;   const int koff = khalf > 0 ? 512 * khalf : 0, klen = khalf < 0 ? 2048 : 512;
;   const u16* A = p.Mix + (size_t)m0 * 2048 + koff;
;   const u16* Bw = p.Wt_out + (size_t)(l & 1) * DM * 2048 + (size_t)nt * 128 * 2048 + koff;
;   if (khalf <= 0) {
;     gemm_tile<true>(A, 2048, Bw, 2048, klen, lds, [&](int mi, int ni, const f32x16& a) {
.LBB0_2481:
	s_or_b64 exec, exec, s[0:1]
	v_readlane_b32 s0, v239, 3
	v_readlane_b32 s1, v239, 4
	s_and_b64 vcc, exec, s[0:1]
	s_waitcnt lgkmcnt(0)
	s_barrier
	s_cbranch_vccz .LBB0_2492
	v_readlane_b32 s0, v238, 35
	v_readlane_b32 s1, v238, 36
	s_nop 0
	v_readlane_b32 s10, v241, 18
	v_cndmask_b32_e64 v0, 0, 1, s[0:1]
	s_lshl_b32 s0, s38, 22
	s_and_b32 s0, s0, 0x400000
	v_lshlrev_b32_e32 v2, 22, v0
	v_readlane_b32 s11, v241, 19
	s_add_u32 s6, s10, s0
	s_addc_u32 s7, s11, 0
	v_lshl_add_u64 v[0:1], s[10:11], 0, v[2:3]
	v_readlane_b32 s8, v238, 15
	v_readlane_b32 s17, v241, 25
	v_readlane_b32 s0, v238, 16
	s_and_b32 s2, s0, 3
	s_lshr_b32 s26, s0, 3
	s_lshl_b32 s26, s26, 1
	s_bfe_u32 s1, s0, 0x10002
	s_add_i32 s26, s26, s1
	v_readlane_b32 s4, v241, 28
	v_readlane_b32 s5, v241, 29
	v_readlane_b32 s24, v240, 15
	v_readlane_b32 s25, v240, 16
	v_lshrrev_b32_e32 v2, 6, v152
	v_and_b32_e32 v4, 63, v152
	s_lshl_b32 s0, s26, 20
	s_add_u32 s4, s4, s0
	s_addc_u32 s5, s5, 0
	s_lshl_b32 s0, s2, 20
	s_add_u32 s14, s6, s0
	s_addc_u32 s15, s7, 0
	v_readfirstlane_b32 s3, v2
	s_lshl_b32 s0, s3, 17
	s_add_u32 s68, s4, s0
	s_addc_u32 s69, s5, 0
	s_add_u32 s70, s68, 0x7c00
	s_addc_u32 s71, s69, 0
	s_add_u32 s72, s70, 0x7c00
	s_addc_u32 s73, s71, 0
	s_add_u32 s74, s72, 0x7c00
	s_addc_u32 s75, s73, 0
	s_add_u32 s76, s14, s0
	s_addc_u32 s77, s15, 0
	s_add_u32 s78, s76, 0x7c00
	s_addc_u32 s79, s77, 0
	s_add_u32 s80, s78, 0x7c00
	s_addc_u32 s81, s79, 0
	s_add_u32 s82, s80, 0x7c00
	s_addc_u32 s83, s81, 0
	s_lshl_b32 s40, s3, 12
	s_add_i32 s44, s40, 0
	s_add_i32 s45, s40, 0x8000
	s_add_i32 s46, s40, 0x10000
	s_add_i32 s47, s40, 0x18000
	v_lshrrev_b32_e32 v2, 4, v4
	v_and_b32_e32 v5, 7, v4
	v_xor_b32_e32 v2, v2, v5
	v_lshlrev_b32_e32 v2, 4, v2
	v_lshrrev_b32_e32 v5, 3, v4
	v_lshlrev_b32_e32 v5, 12, v5
	v_add_u32_e32 v178, v2, v5
	v_xor_b32_e32 v179, 64, v178
	s_mov_b32 m0, s44
	s_nop 0
	global_load_lds_dwordx4 v178, s[68:69]
	global_load_lds_dwordx4 v179, s[70:71] offset:1024
	global_load_lds_dwordx4 v178, s[72:73] offset:2048
	global_load_lds_dwordx4 v179, s[74:75] offset:3072
	s_mov_b32 m0, s46
	s_nop 0
	global_load_lds_dwordx4 v178, s[76:77]
	global_load_lds_dwordx4 v179, s[78:79] offset:1024
	global_load_lds_dwordx4 v178, s[80:81] offset:2048
	global_load_lds_dwordx4 v179, s[82:83] offset:3072
	v_add_u32_e32 v178, 0x80, v178
	v_add_u32_e32 v179, 0x80, v179
	v_and_b32_e32 v5, 31, v4
	v_lshrrev_b32_e32 v2, 1, v5
	v_and_b32_e32 v2, 7, v2
	v_lshrrev_b32_e32 v4, 5, v4
	v_xor_b32_e32 v2, v2, v4
	v_lshlrev_b32_e32 v5, 7, v5
	s_and_b32 s0, s3, 3
	s_lshr_b32 s1, s3, 2
	s_lshl_b32 s10, s0, 13
	s_lshl_b32 s11, s1, 13
	s_add_i32 s11, s11, 0x10000
	v_xor_b32_e32 v232, 0, v2
	v_lshl_add_u32 v232, v232, 4, v5
	v_add_u32_e32 v228, s10, v232
	v_add_u32_e32 v232, s11, v232
	v_xor_b32_e32 v233, 2, v2
	v_lshl_add_u32 v233, v233, 4, v5
	v_add_u32_e32 v229, s10, v233
	v_add_u32_e32 v233, s11, v233
	v_xor_b32_e32 v234, 4, v2
	v_lshl_add_u32 v234, v234, 4, v5
	v_add_u32_e32 v230, s10, v234
	v_add_u32_e32 v234, s11, v234
	v_xor_b32_e32 v235, 6, v2
	v_lshl_add_u32 v235, v235, 4, v5
	v_add_u32_e32 v231, s10, v235
	v_add_u32_e32 v235, s11, v235
	s_lshl_b32 s12, s26, 8
	s_lshl_b32 s0, s0, 6
	s_add_i32 s12, s12, s0
	v_lshrrev_b32_e32 v5, 7, v5
	v_add_u32_e32 v5, s12, v5
	v_lshlrev_b32_e32 v5, 12, v5
	s_lshl_b32 s12, s2, 10
	s_lshl_b32 s1, s1, 8
	s_add_i32 s12, s12, s1
	v_lshlrev_b32_e32 v4, 4, v4
	v_add3_u32 v242, v5, v4, s12
	v_add_u32_e32 v243, 0x20000, v242
	s_waitcnt vmcnt(0) lgkmcnt(0)
	s_barrier
	ds_read_b128 v[132:135], v228 offset:0
	ds_read_b128 v[136:139], v228 offset:4096
	ds_read_b128 v[140:143], v232 offset:0
	ds_read_b128 v[144:147], v232 offset:4096
	ds_read_b128 v[148:151], v232 offset:16384
	ds_read_b128 v[180:183], v232 offset:20480
	s_mov_b32 m0, s45
	s_nop 0
	global_load_lds_dwordx4 v178, s[68:69]
	global_load_lds_dwordx4 v179, s[70:71] offset:1024
	global_load_lds_dwordx4 v178, s[72:73] offset:2048
	global_load_lds_dwordx4 v179, s[74:75] offset:3072
	ds_read_b128 v[184:187], v229 offset:0
	ds_read_b128 v[208:211], v229 offset:4096
	ds_read_b128 v[212:215], v233 offset:0
	ds_read_b128 v[216:219], v233 offset:4096
	ds_read_b128 v[220:223], v233 offset:16384
	ds_read_b128 v[224:227], v233 offset:20480
	s_waitcnt lgkmcnt(6)
	v_mfma_f32_32x32x16_bf16 v[4:19], v[140:143], v[132:135], 0
	v_mfma_f32_32x32x16_bf16 v[68:83], v[140:143], v[136:139], 0
	v_mfma_f32_32x32x16_bf16 v[20:35], v[144:147], v[132:135], 0
	v_mfma_f32_32x32x16_bf16 v[84:99], v[144:147], v[136:139], 0
	v_mfma_f32_32x32x16_bf16 v[36:51], v[148:151], v[132:135], 0
	v_mfma_f32_32x32x16_bf16 v[100:115], v[148:151], v[136:139], 0
	v_mfma_f32_32x32x16_bf16 v[52:67], v[180:183], v[132:135], 0
	v_mfma_f32_32x32x16_bf16 v[116:131], v[180:183], v[136:139], 0
	s_mov_b32 m0, s47
	s_nop 0
	global_load_lds_dwordx4 v178, s[76:77]
	global_load_lds_dwordx4 v179, s[78:79] offset:1024
	global_load_lds_dwordx4 v178, s[80:81] offset:2048
	global_load_lds_dwordx4 v179, s[82:83] offset:3072
	v_add_u32_e32 v178, 0x80, v178
	v_add_u32_e32 v179, 0x80, v179
	ds_read_b128 v[132:135], v230 offset:0
	ds_read_b128 v[136:139], v230 offset:4096
	ds_read_b128 v[140:143], v234 offset:0
	ds_read_b128 v[144:147], v234 offset:4096
	ds_read_b128 v[148:151], v234 offset:16384
	ds_read_b128 v[180:183], v234 offset:20480
	s_waitcnt lgkmcnt(6)
; #define MFMA32(a, b, c) __builtin_amdgcn_mfma_f32_32x32x16_bf16((a), (b), (c), 0, 0, 0)
; template <bool SWAP, class Epi>
; DI void gemm_tile(const u16* __restrict__ A, int lda, const u16* __restrict__ Bw, int ldb, int K, char* lds, Epi epi) {
;     ...
;   auto compute = [&](int st) {
;     const char* as = lds + st * GEMM_STAGE;
;     const char* bs = as + 36864;
; #pragma unroll
;     for (int ks = 0; ks < 4; ++ks) {
;       bf16x8 af[2], bfr[2];
; #pragma unroll
;       for (int mi = 0; mi < 2; ++mi) af[mi] = *(const bf16x8*)(as + ((wm * 64 + mi * 32 + r) * 72 + ks * 16 + 8 * h) * 2);
; #pragma unroll
;       for (int ni = 0; ni < 2; ++ni) bfr[ni] = *(const bf16x8*)(bs + ((wn * 64 + ni * 32 + r) * 72 + ks * 16 + 8 * h) * 2);
; #pragma unroll
;       for (int mi = 0; mi < 2; ++mi)
; #pragma unroll
;         for (int ni = 0; ni < 2; ++ni) {
;           if (SWAP) acc[mi][ni] = MFMA32(bfr[ni], af[mi], acc[mi][ni]);
;           else acc[mi][ni] = MFMA32(af[mi], bfr[ni], acc[mi][ni]);
;         }
;     }
;   };
;   gload(0, ra0, rb0);
;   lstore(0, ra0, rb0);
;   gload(1, ra1, rb1);
;   __syncthreads();
;   for (int kt = 0; kt < nk; kt += 2) {
;     if (kt + 2 < nk) gload(kt + 2, ra0, rb0);
;     compute(0);
;     lstore(1, ra1, rb1);
;     __syncthreads();
;     if (kt + 3 < nk) gload(kt + 3, ra1, rb1);
;     compute(1);
;     if (kt + 2 < nk) lstore(0, ra0, rb0);
;     __syncthreads();
;   }
	v_mfma_f32_32x32x16_bf16 v[4:19], v[212:215], v[184:187], v[4:19]
	v_mfma_f32_32x32x16_bf16 v[68:83], v[212:215], v[208:211], v[68:83]
	v_mfma_f32_32x32x16_bf16 v[20:35], v[216:219], v[184:187], v[20:35]
	v_mfma_f32_32x32x16_bf16 v[84:99], v[216:219], v[208:211], v[84:99]
	v_mfma_f32_32x32x16_bf16 v[36:51], v[220:223], v[184:187], v[36:51]
	v_mfma_f32_32x32x16_bf16 v[100:115], v[220:223], v[208:211], v[100:115]
	v_mfma_f32_32x32x16_bf16 v[52:67], v[224:227], v[184:187], v[52:67]
	v_mfma_f32_32x32x16_bf16 v[116:131], v[224:227], v[208:211], v[116:131]
	ds_read_b128 v[184:187], v231 offset:0
	ds_read_b128 v[208:211], v231 offset:4096
	ds_read_b128 v[212:215], v235 offset:0
	ds_read_b128 v[216:219], v235 offset:4096
	ds_read_b128 v[220:223], v235 offset:16384
	ds_read_b128 v[224:227], v235 offset:20480
	s_waitcnt lgkmcnt(6)
	v_mfma_f32_32x32x16_bf16 v[4:19], v[140:143], v[132:135], v[4:19]
	v_mfma_f32_32x32x16_bf16 v[68:83], v[140:143], v[136:139], v[68:83]
	v_mfma_f32_32x32x16_bf16 v[20:35], v[144:147], v[132:135], v[20:35]
	v_mfma_f32_32x32x16_bf16 v[84:99], v[144:147], v[136:139], v[84:99]
	v_mfma_f32_32x32x16_bf16 v[36:51], v[148:151], v[132:135], v[36:51]
	v_mfma_f32_32x32x16_bf16 v[100:115], v[148:151], v[136:139], v[100:115]
	v_mfma_f32_32x32x16_bf16 v[52:67], v[180:183], v[132:135], v[52:67]
	v_mfma_f32_32x32x16_bf16 v[116:131], v[180:183], v[136:139], v[116:131]
	s_waitcnt lgkmcnt(0)
	v_mfma_f32_32x32x16_bf16 v[4:19], v[212:215], v[184:187], v[4:19]
	v_mfma_f32_32x32x16_bf16 v[68:83], v[212:215], v[208:211], v[68:83]
	v_mfma_f32_32x32x16_bf16 v[20:35], v[216:219], v[184:187], v[20:35]
	v_mfma_f32_32x32x16_bf16 v[84:99], v[216:219], v[208:211], v[84:99]
	v_mfma_f32_32x32x16_bf16 v[36:51], v[220:223], v[184:187], v[36:51]
	v_mfma_f32_32x32x16_bf16 v[100:115], v[220:223], v[208:211], v[100:115]
	v_mfma_f32_32x32x16_bf16 v[52:67], v[224:227], v[184:187], v[52:67]
	v_mfma_f32_32x32x16_bf16 v[116:131], v[224:227], v[208:211], v[116:131]
	s_waitcnt vmcnt(0) lgkmcnt(0)
	s_barrier
	ds_read_b128 v[132:135], v228 offset:32768
	ds_read_b128 v[136:139], v228 offset:36864
	ds_read_b128 v[140:143], v232 offset:32768
	ds_read_b128 v[144:147], v232 offset:36864
	ds_read_b128 v[148:151], v232 offset:49152
	ds_read_b128 v[180:183], v232 offset:53248
	s_mov_b32 m0, s44
	s_nop 0
	global_load_lds_dwordx4 v178, s[68:69]
	global_load_lds_dwordx4 v179, s[70:71] offset:1024
	global_load_lds_dwordx4 v178, s[72:73] offset:2048
	global_load_lds_dwordx4 v179, s[74:75] offset:3072
	ds_read_b128 v[184:187], v229 offset:32768
	ds_read_b128 v[208:211], v229 offset:36864
	ds_read_b128 v[212:215], v233 offset:32768
	ds_read_b128 v[216:219], v233 offset:36864
	ds_read_b128 v[220:223], v233 offset:49152
	ds_read_b128 v[224:227], v233 offset:53248
	s_waitcnt lgkmcnt(6)
	v_mfma_f32_32x32x16_bf16 v[4:19], v[140:143], v[132:135], v[4:19]
	v_mfma_f32_32x32x16_bf16 v[68:83], v[140:143], v[136:139], v[68:83]
	v_mfma_f32_32x32x16_bf16 v[20:35], v[144:147], v[132:135], v[20:35]
	v_mfma_f32_32x32x16_bf16 v[84:99], v[144:147], v[136:139], v[84:99]
	v_mfma_f32_32x32x16_bf16 v[36:51], v[148:151], v[132:135], v[36:51]
	v_mfma_f32_32x32x16_bf16 v[100:115], v[148:151], v[136:139], v[100:115]
	v_mfma_f32_32x32x16_bf16 v[52:67], v[180:183], v[132:135], v[52:67]
	v_mfma_f32_32x32x16_bf16 v[116:131], v[180:183], v[136:139], v[116:131]
	s_mov_b32 m0, s46
	s_nop 0
	global_load_lds_dwordx4 v178, s[76:77]
	global_load_lds_dwordx4 v179, s[78:79] offset:1024
	global_load_lds_dwordx4 v178, s[80:81] offset:2048
	global_load_lds_dwordx4 v179, s[82:83] offset:3072
	v_add_u32_e32 v178, 0x80, v178
	v_add_u32_e32 v179, 0x80, v179
	ds_read_b128 v[132:135], v230 offset:32768
	ds_read_b128 v[136:139], v230 offset:36864
	ds_read_b128 v[140:143], v234 offset:32768
	ds_read_b128 v[144:147], v234 offset:36864
	ds_read_b128 v[148:151], v234 offset:49152
	ds_read_b128 v[180:183], v234 offset:53248
	s_waitcnt lgkmcnt(6)
	v_mfma_f32_32x32x16_bf16 v[4:19], v[212:215], v[184:187], v[4:19]
	v_mfma_f32_32x32x16_bf16 v[68:83], v[212:215], v[208:211], v[68:83]
	v_mfma_f32_32x32x16_bf16 v[20:35], v[216:219], v[184:187], v[20:35]
	v_mfma_f32_32x32x16_bf16 v[84:99], v[216:219], v[208:211], v[84:99]
	v_mfma_f32_32x32x16_bf16 v[36:51], v[220:223], v[184:187], v[36:51]
	v_mfma_f32_32x32x16_bf16 v[100:115], v[220:223], v[208:211], v[100:115]
	v_mfma_f32_32x32x16_bf16 v[52:67], v[224:227], v[184:187], v[52:67]
	v_mfma_f32_32x32x16_bf16 v[116:131], v[224:227], v[208:211], v[116:131]
	ds_read_b128 v[184:187], v231 offset:32768
	ds_read_b128 v[208:211], v231 offset:36864
	ds_read_b128 v[212:215], v235 offset:32768
	ds_read_b128 v[216:219], v235 offset:36864
	ds_read_b128 v[220:223], v235 offset:49152
	ds_read_b128 v[224:227], v235 offset:53248
	s_waitcnt lgkmcnt(6)
	v_mfma_f32_32x32x16_bf16 v[4:19], v[140:143], v[132:135], v[4:19]
	v_mfma_f32_32x32x16_bf16 v[68:83], v[140:143], v[136:139], v[68:83]
	v_mfma_f32_32x32x16_bf16 v[20:35], v[144:147], v[132:135], v[20:35]
	v_mfma_f32_32x32x16_bf16 v[84:99], v[144:147], v[136:139], v[84:99]
	v_mfma_f32_32x32x16_bf16 v[36:51], v[148:151], v[132:135], v[36:51]
	v_mfma_f32_32x32x16_bf16 v[100:115], v[148:151], v[136:139], v[100:115]
	v_mfma_f32_32x32x16_bf16 v[52:67], v[180:183], v[132:135], v[52:67]
	v_mfma_f32_32x32x16_bf16 v[116:131], v[180:183], v[136:139], v[116:131]
	s_waitcnt lgkmcnt(0)
	v_mfma_f32_32x32x16_bf16 v[4:19], v[212:215], v[184:187], v[4:19]
	v_mfma_f32_32x32x16_bf16 v[68:83], v[212:215], v[208:211], v[68:83]
	v_mfma_f32_32x32x16_bf16 v[20:35], v[216:219], v[184:187], v[20:35]
	v_mfma_f32_32x32x16_bf16 v[84:99], v[216:219], v[208:211], v[84:99]
	v_mfma_f32_32x32x16_bf16 v[36:51], v[220:223], v[184:187], v[36:51]
	v_mfma_f32_32x32x16_bf16 v[100:115], v[220:223], v[208:211], v[100:115]
	v_mfma_f32_32x32x16_bf16 v[52:67], v[224:227], v[184:187], v[52:67]
	v_mfma_f32_32x32x16_bf16 v[116:131], v[224:227], v[208:211], v[116:131]
	s_waitcnt vmcnt(0) lgkmcnt(0)
	s_barrier
; #define MFMA32(a, b, c) __builtin_amdgcn_mfma_f32_32x32x16_bf16((a), (b), (c), 0, 0, 0)
; template <bool SWAP, class Epi>
; DI void gemm_tile(const u16* __restrict__ A, int lda, const u16* __restrict__ Bw, int ldb, int K, char* lds, Epi epi) {
;     ...
;   auto compute = [&](int st) {
;     const char* as = lds + st * GEMM_STAGE;
;     const char* bs = as + 36864;
; #pragma unroll
;     for (int ks = 0; ks < 4; ++ks) {
;       bf16x8 af[2], bfr[2];
; #pragma unroll
;       for (int mi = 0; mi < 2; ++mi) af[mi] = *(const bf16x8*)(as + ((wm * 64 + mi * 32 + r) * 72 + ks * 16 + 8 * h) * 2);
; #pragma unroll
;       for (int ni = 0; ni < 2; ++ni) bfr[ni] = *(const bf16x8*)(bs + ((wn * 64 + ni * 32 + r) * 72 + ks * 16 + 8 * h) * 2);
; #pragma unroll
;       for (int mi = 0; mi < 2; ++mi)
; #pragma unroll
;         for (int ni = 0; ni < 2; ++ni) {
;           if (SWAP) acc[mi][ni] = MFMA32(bfr[ni], af[mi], acc[mi][ni]);
;           else acc[mi][ni] = MFMA32(af[mi], bfr[ni], acc[mi][ni]);
;         }
;     }
;   };
;   gload(0, ra0, rb0);
;   lstore(0, ra0, rb0);
;   gload(1, ra1, rb1);
;   __syncthreads();
;   for (int kt = 0; kt < nk; kt += 2) {
;     if (kt + 2 < nk) gload(kt + 2, ra0, rb0);
;     compute(0);
;     lstore(1, ra1, rb1);
;     __syncthreads();
;     if (kt + 3 < nk) gload(kt + 3, ra1, rb1);
;     compute(1);
;     if (kt + 2 < nk) lstore(0, ra0, rb0);
;     __syncthreads();
;   }
	ds_read_b128 v[132:135], v228 offset:0
	ds_read_b128 v[136:139], v228 offset:4096
	ds_read_b128 v[140:143], v232 offset:0
	ds_read_b128 v[144:147], v232 offset:4096
	ds_read_b128 v[148:151], v232 offset:16384
	ds_read_b128 v[180:183], v232 offset:20480
	s_mov_b32 m0, s45
	s_nop 0
	global_load_lds_dwordx4 v178, s[68:69]
	global_load_lds_dwordx4 v179, s[70:71] offset:1024
	global_load_lds_dwordx4 v178, s[72:73] offset:2048
	global_load_lds_dwordx4 v179, s[74:75] offset:3072
	ds_read_b128 v[184:187], v229 offset:0
	ds_read_b128 v[208:211], v229 offset:4096
	ds_read_b128 v[212:215], v233 offset:0
	ds_read_b128 v[216:219], v233 offset:4096
	ds_read_b128 v[220:223], v233 offset:16384
	ds_read_b128 v[224:227], v233 offset:20480
	s_waitcnt lgkmcnt(6)
	v_mfma_f32_32x32x16_bf16 v[4:19], v[140:143], v[132:135], v[4:19]
	v_mfma_f32_32x32x16_bf16 v[68:83], v[140:143], v[136:139], v[68:83]
	v_mfma_f32_32x32x16_bf16 v[20:35], v[144:147], v[132:135], v[20:35]
	v_mfma_f32_32x32x16_bf16 v[84:99], v[144:147], v[136:139], v[84:99]
	v_mfma_f32_32x32x16_bf16 v[36:51], v[148:151], v[132:135], v[36:51]
	v_mfma_f32_32x32x16_bf16 v[100:115], v[148:151], v[136:139], v[100:115]
	v_mfma_f32_32x32x16_bf16 v[52:67], v[180:183], v[132:135], v[52:67]
	v_mfma_f32_32x32x16_bf16 v[116:131], v[180:183], v[136:139], v[116:131]
	s_mov_b32 m0, s47
	s_nop 0
	global_load_lds_dwordx4 v178, s[76:77]
	global_load_lds_dwordx4 v179, s[78:79] offset:1024
	global_load_lds_dwordx4 v178, s[80:81] offset:2048
	global_load_lds_dwordx4 v179, s[82:83] offset:3072
	v_add_u32_e32 v178, 0x80, v178
	v_add_u32_e32 v179, 0x80, v179
	ds_read_b128 v[132:135], v230 offset:0
	ds_read_b128 v[136:139], v230 offset:4096
	ds_read_b128 v[140:143], v234 offset:0
	ds_read_b128 v[144:147], v234 offset:4096
	ds_read_b128 v[148:151], v234 offset:16384
	ds_read_b128 v[180:183], v234 offset:20480
	s_waitcnt lgkmcnt(6)
	v_mfma_f32_32x32x16_bf16 v[4:19], v[212:215], v[184:187], v[4:19]
	v_mfma_f32_32x32x16_bf16 v[68:83], v[212:215], v[208:211], v[68:83]
	v_mfma_f32_32x32x16_bf16 v[20:35], v[216:219], v[184:187], v[20:35]
	v_mfma_f32_32x32x16_bf16 v[84:99], v[216:219], v[208:211], v[84:99]
	v_mfma_f32_32x32x16_bf16 v[36:51], v[220:223], v[184:187], v[36:51]
	v_mfma_f32_32x32x16_bf16 v[100:115], v[220:223], v[208:211], v[100:115]
	v_mfma_f32_32x32x16_bf16 v[52:67], v[224:227], v[184:187], v[52:67]
	v_mfma_f32_32x32x16_bf16 v[116:131], v[224:227], v[208:211], v[116:131]
	ds_read_b128 v[184:187], v231 offset:0
	ds_read_b128 v[208:211], v231 offset:4096
	ds_read_b128 v[212:215], v235 offset:0
	ds_read_b128 v[216:219], v235 offset:4096
	ds_read_b128 v[220:223], v235 offset:16384
	ds_read_b128 v[224:227], v235 offset:20480
	s_waitcnt lgkmcnt(6)
	v_mfma_f32_32x32x16_bf16 v[4:19], v[140:143], v[132:135], v[4:19]
	v_mfma_f32_32x32x16_bf16 v[68:83], v[140:143], v[136:139], v[68:83]
	v_mfma_f32_32x32x16_bf16 v[20:35], v[144:147], v[132:135], v[20:35]
	v_mfma_f32_32x32x16_bf16 v[84:99], v[144:147], v[136:139], v[84:99]
	v_mfma_f32_32x32x16_bf16 v[36:51], v[148:151], v[132:135], v[36:51]
	v_mfma_f32_32x32x16_bf16 v[100:115], v[148:151], v[136:139], v[100:115]
	v_mfma_f32_32x32x16_bf16 v[52:67], v[180:183], v[132:135], v[52:67]
	v_mfma_f32_32x32x16_bf16 v[116:131], v[180:183], v[136:139], v[116:131]
	s_waitcnt lgkmcnt(0)
	v_mfma_f32_32x32x16_bf16 v[4:19], v[212:215], v[184:187], v[4:19]
	v_mfma_f32_32x32x16_bf16 v[68:83], v[212:215], v[208:211], v[68:83]
	v_mfma_f32_32x32x16_bf16 v[20:35], v[216:219], v[184:187], v[20:35]
	v_mfma_f32_32x32x16_bf16 v[84:99], v[216:219], v[208:211], v[84:99]
	v_mfma_f32_32x32x16_bf16 v[36:51], v[220:223], v[184:187], v[36:51]
	v_mfma_f32_32x32x16_bf16 v[100:115], v[220:223], v[208:211], v[100:115]
	v_mfma_f32_32x32x16_bf16 v[52:67], v[224:227], v[184:187], v[52:67]
	v_mfma_f32_32x32x16_bf16 v[116:131], v[224:227], v[208:211], v[116:131]
	s_waitcnt vmcnt(0) lgkmcnt(0)
	s_barrier
	ds_read_b128 v[132:135], v228 offset:32768
	ds_read_b128 v[136:139], v228 offset:36864
	ds_read_b128 v[140:143], v232 offset:32768
	ds_read_b128 v[144:147], v232 offset:36864
	ds_read_b128 v[148:151], v232 offset:49152
	ds_read_b128 v[180:183], v232 offset:53248
	s_mov_b32 m0, s44
	s_nop 0
	global_load_lds_dwordx4 v178, s[68:69]
	global_load_lds_dwordx4 v179, s[70:71] offset:1024
	global_load_lds_dwordx4 v178, s[72:73] offset:2048
	global_load_lds_dwordx4 v179, s[74:75] offset:3072
	ds_read_b128 v[184:187], v229 offset:32768
	ds_read_b128 v[208:211], v229 offset:36864
	ds_read_b128 v[212:215], v233 offset:32768
	ds_read_b128 v[216:219], v233 offset:36864
	ds_read_b128 v[220:223], v233 offset:49152
	ds_read_b128 v[224:227], v233 offset:53248
	s_waitcnt lgkmcnt(6)
	v_mfma_f32_32x32x16_bf16 v[4:19], v[140:143], v[132:135], v[4:19]
	v_mfma_f32_32x32x16_bf16 v[68:83], v[140:143], v[136:139], v[68:83]
	v_mfma_f32_32x32x16_bf16 v[20:35], v[144:147], v[132:135], v[20:35]
	v_mfma_f32_32x32x16_bf16 v[84:99], v[144:147], v[136:139], v[84:99]
	v_mfma_f32_32x32x16_bf16 v[36:51], v[148:151], v[132:135], v[36:51]
	v_mfma_f32_32x32x16_bf16 v[100:115], v[148:151], v[136:139], v[100:115]
	v_mfma_f32_32x32x16_bf16 v[52:67], v[180:183], v[132:135], v[52:67]
	v_mfma_f32_32x32x16_bf16 v[116:131], v[180:183], v[136:139], v[116:131]
	s_mov_b32 m0, s46
	s_nop 0
	global_load_lds_dwordx4 v178, s[76:77]
	global_load_lds_dwordx4 v179, s[78:79] offset:1024
	global_load_lds_dwordx4 v178, s[80:81] offset:2048
	global_load_lds_dwordx4 v179, s[82:83] offset:3072
	v_add_u32_e32 v178, 0x80, v178
	v_add_u32_e32 v179, 0x80, v179
	ds_read_b128 v[132:135], v230 offset:32768
	ds_read_b128 v[136:139], v230 offset:36864
	ds_read_b128 v[140:143], v234 offset:32768
	ds_read_b128 v[144:147], v234 offset:36864
	ds_read_b128 v[148:151], v234 offset:49152
	ds_read_b128 v[180:183], v234 offset:53248
	s_waitcnt lgkmcnt(6)
; #define MFMA32(a, b, c) __builtin_amdgcn_mfma_f32_32x32x16_bf16((a), (b), (c), 0, 0, 0)
; template <bool SWAP, class Epi>
; DI void gemm_tile(const u16* __restrict__ A, int lda, const u16* __restrict__ Bw, int ldb, int K, char* lds, Epi epi) {
;     ...
;   auto compute = [&](int st) {
;     const char* as = lds + st * GEMM_STAGE;
;     const char* bs = as + 36864;
; #pragma unroll
;     for (int ks = 0; ks < 4; ++ks) {
;       bf16x8 af[2], bfr[2];
; #pragma unroll
;       for (int mi = 0; mi < 2; ++mi) af[mi] = *(const bf16x8*)(as + ((wm * 64 + mi * 32 + r) * 72 + ks * 16 + 8 * h) * 2);
; #pragma unroll
;       for (int ni = 0; ni < 2; ++ni) bfr[ni] = *(const bf16x8*)(bs + ((wn * 64 + ni * 32 + r) * 72 + ks * 16 + 8 * h) * 2);
; #pragma unroll
;       for (int mi = 0; mi < 2; ++mi)
; #pragma unroll
;         for (int ni = 0; ni < 2; ++ni) {
;           if (SWAP) acc[mi][ni] = MFMA32(bfr[ni], af[mi], acc[mi][ni]);
;           else acc[mi][ni] = MFMA32(af[mi], bfr[ni], acc[mi][ni]);
;         }
;     }
;   };
;   gload(0, ra0, rb0);
;   lstore(0, ra0, rb0);
;   gload(1, ra1, rb1);
;   __syncthreads();
;   for (int kt = 0; kt < nk; kt += 2) {
;     if (kt + 2 < nk) gload(kt + 2, ra0, rb0);
;     compute(0);
;     lstore(1, ra1, rb1);
;     __syncthreads();
;     if (kt + 3 < nk) gload(kt + 3, ra1, rb1);
;     compute(1);
;     if (kt + 2 < nk) lstore(0, ra0, rb0);
;     __syncthreads();
;   }
	v_mfma_f32_32x32x16_bf16 v[4:19], v[212:215], v[184:187], v[4:19]
	v_mfma_f32_32x32x16_bf16 v[68:83], v[212:215], v[208:211], v[68:83]
	v_mfma_f32_32x32x16_bf16 v[20:35], v[216:219], v[184:187], v[20:35]
	v_mfma_f32_32x32x16_bf16 v[84:99], v[216:219], v[208:211], v[84:99]
	v_mfma_f32_32x32x16_bf16 v[36:51], v[220:223], v[184:187], v[36:51]
	v_mfma_f32_32x32x16_bf16 v[100:115], v[220:223], v[208:211], v[100:115]
	v_mfma_f32_32x32x16_bf16 v[52:67], v[224:227], v[184:187], v[52:67]
	v_mfma_f32_32x32x16_bf16 v[116:131], v[224:227], v[208:211], v[116:131]
	ds_read_b128 v[184:187], v231 offset:32768
	ds_read_b128 v[208:211], v231 offset:36864
	ds_read_b128 v[212:215], v235 offset:32768
	ds_read_b128 v[216:219], v235 offset:36864
	ds_read_b128 v[220:223], v235 offset:49152
	ds_read_b128 v[224:227], v235 offset:53248
	s_waitcnt lgkmcnt(6)
	v_mfma_f32_32x32x16_bf16 v[4:19], v[140:143], v[132:135], v[4:19]
	v_mfma_f32_32x32x16_bf16 v[68:83], v[140:143], v[136:139], v[68:83]
	v_mfma_f32_32x32x16_bf16 v[20:35], v[144:147], v[132:135], v[20:35]
	v_mfma_f32_32x32x16_bf16 v[84:99], v[144:147], v[136:139], v[84:99]
	v_mfma_f32_32x32x16_bf16 v[36:51], v[148:151], v[132:135], v[36:51]
	v_mfma_f32_32x32x16_bf16 v[100:115], v[148:151], v[136:139], v[100:115]
	v_mfma_f32_32x32x16_bf16 v[52:67], v[180:183], v[132:135], v[52:67]
	v_mfma_f32_32x32x16_bf16 v[116:131], v[180:183], v[136:139], v[116:131]
	s_waitcnt lgkmcnt(0)
	v_mfma_f32_32x32x16_bf16 v[4:19], v[212:215], v[184:187], v[4:19]
	v_mfma_f32_32x32x16_bf16 v[68:83], v[212:215], v[208:211], v[68:83]
	v_mfma_f32_32x32x16_bf16 v[20:35], v[216:219], v[184:187], v[20:35]
	v_mfma_f32_32x32x16_bf16 v[84:99], v[216:219], v[208:211], v[84:99]
	v_mfma_f32_32x32x16_bf16 v[36:51], v[220:223], v[184:187], v[36:51]
	v_mfma_f32_32x32x16_bf16 v[100:115], v[220:223], v[208:211], v[100:115]
	v_mfma_f32_32x32x16_bf16 v[52:67], v[224:227], v[184:187], v[52:67]
	v_mfma_f32_32x32x16_bf16 v[116:131], v[224:227], v[208:211], v[116:131]
	s_waitcnt vmcnt(0) lgkmcnt(0)
	s_barrier
	ds_read_b128 v[132:135], v228 offset:0
	ds_read_b128 v[136:139], v228 offset:4096
	ds_read_b128 v[140:143], v232 offset:0
	ds_read_b128 v[144:147], v232 offset:4096
	ds_read_b128 v[148:151], v232 offset:16384
	ds_read_b128 v[180:183], v232 offset:20480
	s_mov_b32 m0, s45
	s_nop 0
	global_load_lds_dwordx4 v178, s[68:69]
	global_load_lds_dwordx4 v179, s[70:71] offset:1024
	global_load_lds_dwordx4 v178, s[72:73] offset:2048
	global_load_lds_dwordx4 v179, s[74:75] offset:3072
	ds_read_b128 v[184:187], v229 offset:0
	ds_read_b128 v[208:211], v229 offset:4096
	ds_read_b128 v[212:215], v233 offset:0
	ds_read_b128 v[216:219], v233 offset:4096
	ds_read_b128 v[220:223], v233 offset:16384
	ds_read_b128 v[224:227], v233 offset:20480
	s_waitcnt lgkmcnt(6)
	v_mfma_f32_32x32x16_bf16 v[4:19], v[140:143], v[132:135], v[4:19]
	v_mfma_f32_32x32x16_bf16 v[68:83], v[140:143], v[136:139], v[68:83]
	v_mfma_f32_32x32x16_bf16 v[20:35], v[144:147], v[132:135], v[20:35]
	v_mfma_f32_32x32x16_bf16 v[84:99], v[144:147], v[136:139], v[84:99]
	v_mfma_f32_32x32x16_bf16 v[36:51], v[148:151], v[132:135], v[36:51]
	v_mfma_f32_32x32x16_bf16 v[100:115], v[148:151], v[136:139], v[100:115]
	v_mfma_f32_32x32x16_bf16 v[52:67], v[180:183], v[132:135], v[52:67]
	v_mfma_f32_32x32x16_bf16 v[116:131], v[180:183], v[136:139], v[116:131]
	s_mov_b32 m0, s47
	s_nop 0
	global_load_lds_dwordx4 v178, s[76:77]
	global_load_lds_dwordx4 v179, s[78:79] offset:1024
	global_load_lds_dwordx4 v178, s[80:81] offset:2048
	global_load_lds_dwordx4 v179, s[82:83] offset:3072
	v_add_u32_e32 v178, 0x80, v178
	v_add_u32_e32 v179, 0x80, v179
	ds_read_b128 v[132:135], v230 offset:0
	ds_read_b128 v[136:139], v230 offset:4096
	ds_read_b128 v[140:143], v234 offset:0
	ds_read_b128 v[144:147], v234 offset:4096
	ds_read_b128 v[148:151], v234 offset:16384
	ds_read_b128 v[180:183], v234 offset:20480
	s_waitcnt lgkmcnt(6)
	v_mfma_f32_32x32x16_bf16 v[4:19], v[212:215], v[184:187], v[4:19]
	v_mfma_f32_32x32x16_bf16 v[68:83], v[212:215], v[208:211], v[68:83]
	v_mfma_f32_32x32x16_bf16 v[20:35], v[216:219], v[184:187], v[20:35]
	v_mfma_f32_32x32x16_bf16 v[84:99], v[216:219], v[208:211], v[84:99]
	v_mfma_f32_32x32x16_bf16 v[36:51], v[220:223], v[184:187], v[36:51]
	v_mfma_f32_32x32x16_bf16 v[100:115], v[220:223], v[208:211], v[100:115]
	v_mfma_f32_32x32x16_bf16 v[52:67], v[224:227], v[184:187], v[52:67]
	v_mfma_f32_32x32x16_bf16 v[116:131], v[224:227], v[208:211], v[116:131]
	ds_read_b128 v[184:187], v231 offset:0
	ds_read_b128 v[208:211], v231 offset:4096
	ds_read_b128 v[212:215], v235 offset:0
	ds_read_b128 v[216:219], v235 offset:4096
	ds_read_b128 v[220:223], v235 offset:16384
	ds_read_b128 v[224:227], v235 offset:20480
	s_waitcnt lgkmcnt(6)
	v_mfma_f32_32x32x16_bf16 v[4:19], v[140:143], v[132:135], v[4:19]
	v_mfma_f32_32x32x16_bf16 v[68:83], v[140:143], v[136:139], v[68:83]
	v_mfma_f32_32x32x16_bf16 v[20:35], v[144:147], v[132:135], v[20:35]
	v_mfma_f32_32x32x16_bf16 v[84:99], v[144:147], v[136:139], v[84:99]
	v_mfma_f32_32x32x16_bf16 v[36:51], v[148:151], v[132:135], v[36:51]
	v_mfma_f32_32x32x16_bf16 v[100:115], v[148:151], v[136:139], v[100:115]
	v_mfma_f32_32x32x16_bf16 v[52:67], v[180:183], v[132:135], v[52:67]
	v_mfma_f32_32x32x16_bf16 v[116:131], v[180:183], v[136:139], v[116:131]
	s_waitcnt lgkmcnt(0)
	v_mfma_f32_32x32x16_bf16 v[4:19], v[212:215], v[184:187], v[4:19]
	v_mfma_f32_32x32x16_bf16 v[68:83], v[212:215], v[208:211], v[68:83]
	v_mfma_f32_32x32x16_bf16 v[20:35], v[216:219], v[184:187], v[20:35]
	v_mfma_f32_32x32x16_bf16 v[84:99], v[216:219], v[208:211], v[84:99]
	v_mfma_f32_32x32x16_bf16 v[36:51], v[220:223], v[184:187], v[36:51]
	v_mfma_f32_32x32x16_bf16 v[100:115], v[220:223], v[208:211], v[100:115]
	v_mfma_f32_32x32x16_bf16 v[52:67], v[224:227], v[184:187], v[52:67]
	v_mfma_f32_32x32x16_bf16 v[116:131], v[224:227], v[208:211], v[116:131]
	s_waitcnt vmcnt(0) lgkmcnt(0)
	s_barrier
; #define MFMA32(a, b, c) __builtin_amdgcn_mfma_f32_32x32x16_bf16((a), (b), (c), 0, 0, 0)
; template <bool SWAP, class Epi>
; DI void gemm_tile(const u16* __restrict__ A, int lda, const u16* __restrict__ Bw, int ldb, int K, char* lds, Epi epi) {
;     ...
;   auto compute = [&](int st) {
;     const char* as = lds + st * GEMM_STAGE;
;     const char* bs = as + 36864;
; #pragma unroll
;     for (int ks = 0; ks < 4; ++ks) {
;       bf16x8 af[2], bfr[2];
; #pragma unroll
;       for (int mi = 0; mi < 2; ++mi) af[mi] = *(const bf16x8*)(as + ((wm * 64 + mi * 32 + r) * 72 + ks * 16 + 8 * h) * 2);
; #pragma unroll
;       for (int ni = 0; ni < 2; ++ni) bfr[ni] = *(const bf16x8*)(bs + ((wn * 64 + ni * 32 + r) * 72 + ks * 16 + 8 * h) * 2);
; #pragma unroll
;       for (int mi = 0; mi < 2; ++mi)
; #pragma unroll
;         for (int ni = 0; ni < 2; ++ni) {
;           if (SWAP) acc[mi][ni] = MFMA32(bfr[ni], af[mi], acc[mi][ni]);
;           else acc[mi][ni] = MFMA32(af[mi], bfr[ni], acc[mi][ni]);
;         }
;     }
;   };
;   gload(0, ra0, rb0);
;   lstore(0, ra0, rb0);
;   gload(1, ra1, rb1);
;   __syncthreads();
;   for (int kt = 0; kt < nk; kt += 2) {
;     if (kt + 2 < nk) gload(kt + 2, ra0, rb0);
;     compute(0);
;     lstore(1, ra1, rb1);
;     __syncthreads();
;     if (kt + 3 < nk) gload(kt + 3, ra1, rb1);
;     compute(1);
;     if (kt + 2 < nk) lstore(0, ra0, rb0);
;     __syncthreads();
;   }
	ds_read_b128 v[132:135], v228 offset:32768
	ds_read_b128 v[136:139], v228 offset:36864
	ds_read_b128 v[140:143], v232 offset:32768
	ds_read_b128 v[144:147], v232 offset:36864
	ds_read_b128 v[148:151], v232 offset:49152
	ds_read_b128 v[180:183], v232 offset:53248
	s_mov_b32 m0, s44
	s_nop 0
	global_load_lds_dwordx4 v178, s[68:69]
	global_load_lds_dwordx4 v179, s[70:71] offset:1024
	global_load_lds_dwordx4 v178, s[72:73] offset:2048
	global_load_lds_dwordx4 v179, s[74:75] offset:3072
	ds_read_b128 v[184:187], v229 offset:32768
	ds_read_b128 v[208:211], v229 offset:36864
	ds_read_b128 v[212:215], v233 offset:32768
	ds_read_b128 v[216:219], v233 offset:36864
	ds_read_b128 v[220:223], v233 offset:49152
	ds_read_b128 v[224:227], v233 offset:53248
	s_waitcnt lgkmcnt(6)
	v_mfma_f32_32x32x16_bf16 v[4:19], v[140:143], v[132:135], v[4:19]
	v_mfma_f32_32x32x16_bf16 v[68:83], v[140:143], v[136:139], v[68:83]
	v_mfma_f32_32x32x16_bf16 v[20:35], v[144:147], v[132:135], v[20:35]
	v_mfma_f32_32x32x16_bf16 v[84:99], v[144:147], v[136:139], v[84:99]
	v_mfma_f32_32x32x16_bf16 v[36:51], v[148:151], v[132:135], v[36:51]
	v_mfma_f32_32x32x16_bf16 v[100:115], v[148:151], v[136:139], v[100:115]
	v_mfma_f32_32x32x16_bf16 v[52:67], v[180:183], v[132:135], v[52:67]
	v_mfma_f32_32x32x16_bf16 v[116:131], v[180:183], v[136:139], v[116:131]
	s_mov_b32 m0, s46
	s_nop 0
	global_load_lds_dwordx4 v178, s[76:77]
	global_load_lds_dwordx4 v179, s[78:79] offset:1024
	global_load_lds_dwordx4 v178, s[80:81] offset:2048
	global_load_lds_dwordx4 v179, s[82:83] offset:3072
	v_add_u32_e32 v178, 0x80, v178
	v_add_u32_e32 v179, 0x80, v179
	ds_read_b128 v[132:135], v230 offset:32768
	ds_read_b128 v[136:139], v230 offset:36864
	ds_read_b128 v[140:143], v234 offset:32768
	ds_read_b128 v[144:147], v234 offset:36864
	ds_read_b128 v[148:151], v234 offset:49152
	ds_read_b128 v[180:183], v234 offset:53248
	s_waitcnt lgkmcnt(6)
	v_mfma_f32_32x32x16_bf16 v[4:19], v[212:215], v[184:187], v[4:19]
	v_mfma_f32_32x32x16_bf16 v[68:83], v[212:215], v[208:211], v[68:83]
	v_mfma_f32_32x32x16_bf16 v[20:35], v[216:219], v[184:187], v[20:35]
	v_mfma_f32_32x32x16_bf16 v[84:99], v[216:219], v[208:211], v[84:99]
	v_mfma_f32_32x32x16_bf16 v[36:51], v[220:223], v[184:187], v[36:51]
	v_mfma_f32_32x32x16_bf16 v[100:115], v[220:223], v[208:211], v[100:115]
	v_mfma_f32_32x32x16_bf16 v[52:67], v[224:227], v[184:187], v[52:67]
	v_mfma_f32_32x32x16_bf16 v[116:131], v[224:227], v[208:211], v[116:131]
	ds_read_b128 v[184:187], v231 offset:32768
	ds_read_b128 v[208:211], v231 offset:36864
	ds_read_b128 v[212:215], v235 offset:32768
	ds_read_b128 v[216:219], v235 offset:36864
	ds_read_b128 v[220:223], v235 offset:49152
	ds_read_b128 v[224:227], v235 offset:53248
	s_waitcnt lgkmcnt(6)
	v_mfma_f32_32x32x16_bf16 v[4:19], v[140:143], v[132:135], v[4:19]
	v_mfma_f32_32x32x16_bf16 v[68:83], v[140:143], v[136:139], v[68:83]
	v_mfma_f32_32x32x16_bf16 v[20:35], v[144:147], v[132:135], v[20:35]
	v_mfma_f32_32x32x16_bf16 v[84:99], v[144:147], v[136:139], v[84:99]
	v_mfma_f32_32x32x16_bf16 v[36:51], v[148:151], v[132:135], v[36:51]
	v_mfma_f32_32x32x16_bf16 v[100:115], v[148:151], v[136:139], v[100:115]
	v_mfma_f32_32x32x16_bf16 v[52:67], v[180:183], v[132:135], v[52:67]
	v_mfma_f32_32x32x16_bf16 v[116:131], v[180:183], v[136:139], v[116:131]
	s_waitcnt lgkmcnt(0)
	v_mfma_f32_32x32x16_bf16 v[4:19], v[212:215], v[184:187], v[4:19]
	v_mfma_f32_32x32x16_bf16 v[68:83], v[212:215], v[208:211], v[68:83]
	v_mfma_f32_32x32x16_bf16 v[20:35], v[216:219], v[184:187], v[20:35]
	v_mfma_f32_32x32x16_bf16 v[84:99], v[216:219], v[208:211], v[84:99]
	v_mfma_f32_32x32x16_bf16 v[36:51], v[220:223], v[184:187], v[36:51]
	v_mfma_f32_32x32x16_bf16 v[100:115], v[220:223], v[208:211], v[100:115]
	v_mfma_f32_32x32x16_bf16 v[52:67], v[224:227], v[184:187], v[52:67]
	v_mfma_f32_32x32x16_bf16 v[116:131], v[224:227], v[208:211], v[116:131]
	s_waitcnt vmcnt(0) lgkmcnt(0)
	s_barrier
	ds_read_b128 v[132:135], v228 offset:0
	ds_read_b128 v[136:139], v228 offset:4096
	ds_read_b128 v[140:143], v232 offset:0
	ds_read_b128 v[144:147], v232 offset:4096
	ds_read_b128 v[148:151], v232 offset:16384
	ds_read_b128 v[180:183], v232 offset:20480
	s_mov_b32 m0, s45
	s_nop 0
	global_load_lds_dwordx4 v178, s[68:69]
	global_load_lds_dwordx4 v179, s[70:71] offset:1024
	global_load_lds_dwordx4 v178, s[72:73] offset:2048
	global_load_lds_dwordx4 v179, s[74:75] offset:3072
	ds_read_b128 v[184:187], v229 offset:0
	ds_read_b128 v[208:211], v229 offset:4096
	ds_read_b128 v[212:215], v233 offset:0
	ds_read_b128 v[216:219], v233 offset:4096
	ds_read_b128 v[220:223], v233 offset:16384
	ds_read_b128 v[224:227], v233 offset:20480
	s_waitcnt lgkmcnt(6)
	v_mfma_f32_32x32x16_bf16 v[4:19], v[140:143], v[132:135], v[4:19]
	v_mfma_f32_32x32x16_bf16 v[68:83], v[140:143], v[136:139], v[68:83]
	v_mfma_f32_32x32x16_bf16 v[20:35], v[144:147], v[132:135], v[20:35]
	v_mfma_f32_32x32x16_bf16 v[84:99], v[144:147], v[136:139], v[84:99]
	v_mfma_f32_32x32x16_bf16 v[36:51], v[148:151], v[132:135], v[36:51]
	v_mfma_f32_32x32x16_bf16 v[100:115], v[148:151], v[136:139], v[100:115]
	v_mfma_f32_32x32x16_bf16 v[52:67], v[180:183], v[132:135], v[52:67]
	v_mfma_f32_32x32x16_bf16 v[116:131], v[180:183], v[136:139], v[116:131]
	s_mov_b32 m0, s47
	s_nop 0
	global_load_lds_dwordx4 v178, s[76:77]
	global_load_lds_dwordx4 v179, s[78:79] offset:1024
	global_load_lds_dwordx4 v178, s[80:81] offset:2048
	global_load_lds_dwordx4 v179, s[82:83] offset:3072
	v_add_u32_e32 v178, 0x80, v178
	v_add_u32_e32 v179, 0x80, v179
	ds_read_b128 v[132:135], v230 offset:0
	ds_read_b128 v[136:139], v230 offset:4096
	ds_read_b128 v[140:143], v234 offset:0
	ds_read_b128 v[144:147], v234 offset:4096
	ds_read_b128 v[148:151], v234 offset:16384
	ds_read_b128 v[180:183], v234 offset:20480
	s_waitcnt lgkmcnt(6)
; #define MFMA32(a, b, c) __builtin_amdgcn_mfma_f32_32x32x16_bf16((a), (b), (c), 0, 0, 0)
; template <bool SWAP, class Epi>
; DI void gemm_tile(const u16* __restrict__ A, int lda, const u16* __restrict__ Bw, int ldb, int K, char* lds, Epi epi) {
;     ...
;   auto compute = [&](int st) {
;     const char* as = lds + st * GEMM_STAGE;
;     const char* bs = as + 36864;
; #pragma unroll
;     for (int ks = 0; ks < 4; ++ks) {
;       bf16x8 af[2], bfr[2];
; #pragma unroll
;       for (int mi = 0; mi < 2; ++mi) af[mi] = *(const bf16x8*)(as + ((wm * 64 + mi * 32 + r) * 72 + ks * 16 + 8 * h) * 2);
; #pragma unroll
;       for (int ni = 0; ni < 2; ++ni) bfr[ni] = *(const bf16x8*)(bs + ((wn * 64 + ni * 32 + r) * 72 + ks * 16 + 8 * h) * 2);
; #pragma unroll
;       for (int mi = 0; mi < 2; ++mi)
; #pragma unroll
;         for (int ni = 0; ni < 2; ++ni) {
;           if (SWAP) acc[mi][ni] = MFMA32(bfr[ni], af[mi], acc[mi][ni]);
;           else acc[mi][ni] = MFMA32(af[mi], bfr[ni], acc[mi][ni]);
;         }
;     }
;   };
;   gload(0, ra0, rb0);
;   lstore(0, ra0, rb0);
;   gload(1, ra1, rb1);
;   __syncthreads();
;   for (int kt = 0; kt < nk; kt += 2) {
;     if (kt + 2 < nk) gload(kt + 2, ra0, rb0);
;     compute(0);
;     lstore(1, ra1, rb1);
;     __syncthreads();
;     if (kt + 3 < nk) gload(kt + 3, ra1, rb1);
;     compute(1);
;     if (kt + 2 < nk) lstore(0, ra0, rb0);
;     __syncthreads();
;   }
	v_mfma_f32_32x32x16_bf16 v[4:19], v[212:215], v[184:187], v[4:19]
	v_mfma_f32_32x32x16_bf16 v[68:83], v[212:215], v[208:211], v[68:83]
	v_mfma_f32_32x32x16_bf16 v[20:35], v[216:219], v[184:187], v[20:35]
	v_mfma_f32_32x32x16_bf16 v[84:99], v[216:219], v[208:211], v[84:99]
	v_mfma_f32_32x32x16_bf16 v[36:51], v[220:223], v[184:187], v[36:51]
	v_mfma_f32_32x32x16_bf16 v[100:115], v[220:223], v[208:211], v[100:115]
	v_mfma_f32_32x32x16_bf16 v[52:67], v[224:227], v[184:187], v[52:67]
	v_mfma_f32_32x32x16_bf16 v[116:131], v[224:227], v[208:211], v[116:131]
	ds_read_b128 v[184:187], v231 offset:0
	ds_read_b128 v[208:211], v231 offset:4096
	ds_read_b128 v[212:215], v235 offset:0
	ds_read_b128 v[216:219], v235 offset:4096
	ds_read_b128 v[220:223], v235 offset:16384
	ds_read_b128 v[224:227], v235 offset:20480
	s_waitcnt lgkmcnt(6)
	v_mfma_f32_32x32x16_bf16 v[4:19], v[140:143], v[132:135], v[4:19]
	v_mfma_f32_32x32x16_bf16 v[68:83], v[140:143], v[136:139], v[68:83]
	v_mfma_f32_32x32x16_bf16 v[20:35], v[144:147], v[132:135], v[20:35]
	v_mfma_f32_32x32x16_bf16 v[84:99], v[144:147], v[136:139], v[84:99]
	v_mfma_f32_32x32x16_bf16 v[36:51], v[148:151], v[132:135], v[36:51]
	v_mfma_f32_32x32x16_bf16 v[100:115], v[148:151], v[136:139], v[100:115]
	v_mfma_f32_32x32x16_bf16 v[52:67], v[180:183], v[132:135], v[52:67]
	v_mfma_f32_32x32x16_bf16 v[116:131], v[180:183], v[136:139], v[116:131]
	s_waitcnt lgkmcnt(0)
	v_mfma_f32_32x32x16_bf16 v[4:19], v[212:215], v[184:187], v[4:19]
	v_mfma_f32_32x32x16_bf16 v[68:83], v[212:215], v[208:211], v[68:83]
	v_mfma_f32_32x32x16_bf16 v[20:35], v[216:219], v[184:187], v[20:35]
	v_mfma_f32_32x32x16_bf16 v[84:99], v[216:219], v[208:211], v[84:99]
	v_mfma_f32_32x32x16_bf16 v[36:51], v[220:223], v[184:187], v[36:51]
	v_mfma_f32_32x32x16_bf16 v[100:115], v[220:223], v[208:211], v[100:115]
	v_mfma_f32_32x32x16_bf16 v[52:67], v[224:227], v[184:187], v[52:67]
	v_mfma_f32_32x32x16_bf16 v[116:131], v[224:227], v[208:211], v[116:131]
	s_waitcnt vmcnt(0) lgkmcnt(0)
	s_barrier
	ds_read_b128 v[132:135], v228 offset:32768
	ds_read_b128 v[136:139], v228 offset:36864
	ds_read_b128 v[140:143], v232 offset:32768
	ds_read_b128 v[144:147], v232 offset:36864
	ds_read_b128 v[148:151], v232 offset:49152
	ds_read_b128 v[180:183], v232 offset:53248
	s_mov_b32 m0, s44
	s_nop 0
	global_load_lds_dwordx4 v178, s[68:69]
	global_load_lds_dwordx4 v179, s[70:71] offset:1024
	global_load_lds_dwordx4 v178, s[72:73] offset:2048
	global_load_lds_dwordx4 v179, s[74:75] offset:3072
	ds_read_b128 v[184:187], v229 offset:32768
	ds_read_b128 v[208:211], v229 offset:36864
	ds_read_b128 v[212:215], v233 offset:32768
	ds_read_b128 v[216:219], v233 offset:36864
	ds_read_b128 v[220:223], v233 offset:49152
	ds_read_b128 v[224:227], v233 offset:53248
	s_waitcnt lgkmcnt(6)
	v_mfma_f32_32x32x16_bf16 v[4:19], v[140:143], v[132:135], v[4:19]
	v_mfma_f32_32x32x16_bf16 v[68:83], v[140:143], v[136:139], v[68:83]
	v_mfma_f32_32x32x16_bf16 v[20:35], v[144:147], v[132:135], v[20:35]
	v_mfma_f32_32x32x16_bf16 v[84:99], v[144:147], v[136:139], v[84:99]
	v_mfma_f32_32x32x16_bf16 v[36:51], v[148:151], v[132:135], v[36:51]
	v_mfma_f32_32x32x16_bf16 v[100:115], v[148:151], v[136:139], v[100:115]
	v_mfma_f32_32x32x16_bf16 v[52:67], v[180:183], v[132:135], v[52:67]
	v_mfma_f32_32x32x16_bf16 v[116:131], v[180:183], v[136:139], v[116:131]
	s_mov_b32 m0, s46
	s_nop 0
	global_load_lds_dwordx4 v178, s[76:77]
	global_load_lds_dwordx4 v179, s[78:79] offset:1024
	global_load_lds_dwordx4 v178, s[80:81] offset:2048
	global_load_lds_dwordx4 v179, s[82:83] offset:3072
	v_add_u32_e32 v178, 0x80, v178
	v_add_u32_e32 v179, 0x80, v179
	ds_read_b128 v[132:135], v230 offset:32768
	ds_read_b128 v[136:139], v230 offset:36864
	ds_read_b128 v[140:143], v234 offset:32768
	ds_read_b128 v[144:147], v234 offset:36864
	ds_read_b128 v[148:151], v234 offset:49152
	ds_read_b128 v[180:183], v234 offset:53248
	s_waitcnt lgkmcnt(6)
	v_mfma_f32_32x32x16_bf16 v[4:19], v[212:215], v[184:187], v[4:19]
	v_mfma_f32_32x32x16_bf16 v[68:83], v[212:215], v[208:211], v[68:83]
	v_mfma_f32_32x32x16_bf16 v[20:35], v[216:219], v[184:187], v[20:35]
	v_mfma_f32_32x32x16_bf16 v[84:99], v[216:219], v[208:211], v[84:99]
	v_mfma_f32_32x32x16_bf16 v[36:51], v[220:223], v[184:187], v[36:51]
	v_mfma_f32_32x32x16_bf16 v[100:115], v[220:223], v[208:211], v[100:115]
	v_mfma_f32_32x32x16_bf16 v[52:67], v[224:227], v[184:187], v[52:67]
	v_mfma_f32_32x32x16_bf16 v[116:131], v[224:227], v[208:211], v[116:131]
	ds_read_b128 v[184:187], v231 offset:32768
	ds_read_b128 v[208:211], v231 offset:36864
	ds_read_b128 v[212:215], v235 offset:32768
	ds_read_b128 v[216:219], v235 offset:36864
	ds_read_b128 v[220:223], v235 offset:49152
	ds_read_b128 v[224:227], v235 offset:53248
	s_waitcnt lgkmcnt(6)
	v_mfma_f32_32x32x16_bf16 v[4:19], v[140:143], v[132:135], v[4:19]
	v_mfma_f32_32x32x16_bf16 v[68:83], v[140:143], v[136:139], v[68:83]
	v_mfma_f32_32x32x16_bf16 v[20:35], v[144:147], v[132:135], v[20:35]
	v_mfma_f32_32x32x16_bf16 v[84:99], v[144:147], v[136:139], v[84:99]
	v_mfma_f32_32x32x16_bf16 v[36:51], v[148:151], v[132:135], v[36:51]
	v_mfma_f32_32x32x16_bf16 v[100:115], v[148:151], v[136:139], v[100:115]
	v_mfma_f32_32x32x16_bf16 v[52:67], v[180:183], v[132:135], v[52:67]
	v_mfma_f32_32x32x16_bf16 v[116:131], v[180:183], v[136:139], v[116:131]
	s_waitcnt lgkmcnt(0)
	v_mfma_f32_32x32x16_bf16 v[4:19], v[212:215], v[184:187], v[4:19]
	v_mfma_f32_32x32x16_bf16 v[68:83], v[212:215], v[208:211], v[68:83]
	v_mfma_f32_32x32x16_bf16 v[20:35], v[216:219], v[184:187], v[20:35]
	v_mfma_f32_32x32x16_bf16 v[84:99], v[216:219], v[208:211], v[84:99]
	v_mfma_f32_32x32x16_bf16 v[36:51], v[220:223], v[184:187], v[36:51]
	v_mfma_f32_32x32x16_bf16 v[100:115], v[220:223], v[208:211], v[100:115]
	v_mfma_f32_32x32x16_bf16 v[52:67], v[224:227], v[184:187], v[52:67]
	v_mfma_f32_32x32x16_bf16 v[116:131], v[224:227], v[208:211], v[116:131]
	s_waitcnt vmcnt(0) lgkmcnt(0)
	s_barrier
; #define MFMA32(a, b, c) __builtin_amdgcn_mfma_f32_32x32x16_bf16((a), (b), (c), 0, 0, 0)
; template <bool SWAP, class Epi>
; DI void gemm_tile(const u16* __restrict__ A, int lda, const u16* __restrict__ Bw, int ldb, int K, char* lds, Epi epi) {
;     ...
;   auto compute = [&](int st) {
;     const char* as = lds + st * GEMM_STAGE;
;     const char* bs = as + 36864;
; #pragma unroll
;     for (int ks = 0; ks < 4; ++ks) {
;       bf16x8 af[2], bfr[2];
; #pragma unroll
;       for (int mi = 0; mi < 2; ++mi) af[mi] = *(const bf16x8*)(as + ((wm * 64 + mi * 32 + r) * 72 + ks * 16 + 8 * h) * 2);
; #pragma unroll
;       for (int ni = 0; ni < 2; ++ni) bfr[ni] = *(const bf16x8*)(bs + ((wn * 64 + ni * 32 + r) * 72 + ks * 16 + 8 * h) * 2);
; #pragma unroll
;       for (int mi = 0; mi < 2; ++mi)
; #pragma unroll
;         for (int ni = 0; ni < 2; ++ni) {
;           if (SWAP) acc[mi][ni] = MFMA32(bfr[ni], af[mi], acc[mi][ni]);
;           else acc[mi][ni] = MFMA32(af[mi], bfr[ni], acc[mi][ni]);
;         }
;     }
;   };
;   gload(0, ra0, rb0);
;   lstore(0, ra0, rb0);
;   gload(1, ra1, rb1);
;   __syncthreads();
;   for (int kt = 0; kt < nk; kt += 2) {
;     if (kt + 2 < nk) gload(kt + 2, ra0, rb0);
;     compute(0);
;     lstore(1, ra1, rb1);
;     __syncthreads();
;     if (kt + 3 < nk) gload(kt + 3, ra1, rb1);
;     compute(1);
;     if (kt + 2 < nk) lstore(0, ra0, rb0);
;     __syncthreads();
;   }
	ds_read_b128 v[132:135], v228 offset:0
	ds_read_b128 v[136:139], v228 offset:4096
	ds_read_b128 v[140:143], v232 offset:0
	ds_read_b128 v[144:147], v232 offset:4096
	ds_read_b128 v[148:151], v232 offset:16384
	ds_read_b128 v[180:183], v232 offset:20480
	s_mov_b32 m0, s45
	s_nop 0
	global_load_lds_dwordx4 v178, s[68:69]
	global_load_lds_dwordx4 v179, s[70:71] offset:1024
	global_load_lds_dwordx4 v178, s[72:73] offset:2048
	global_load_lds_dwordx4 v179, s[74:75] offset:3072
	ds_read_b128 v[184:187], v229 offset:0
	ds_read_b128 v[208:211], v229 offset:4096
	ds_read_b128 v[212:215], v233 offset:0
	ds_read_b128 v[216:219], v233 offset:4096
	ds_read_b128 v[220:223], v233 offset:16384
	ds_read_b128 v[224:227], v233 offset:20480
	s_waitcnt lgkmcnt(6)
	v_mfma_f32_32x32x16_bf16 v[4:19], v[140:143], v[132:135], v[4:19]
	v_mfma_f32_32x32x16_bf16 v[68:83], v[140:143], v[136:139], v[68:83]
	v_mfma_f32_32x32x16_bf16 v[20:35], v[144:147], v[132:135], v[20:35]
	v_mfma_f32_32x32x16_bf16 v[84:99], v[144:147], v[136:139], v[84:99]
	v_mfma_f32_32x32x16_bf16 v[36:51], v[148:151], v[132:135], v[36:51]
	v_mfma_f32_32x32x16_bf16 v[100:115], v[148:151], v[136:139], v[100:115]
	v_mfma_f32_32x32x16_bf16 v[52:67], v[180:183], v[132:135], v[52:67]
	v_mfma_f32_32x32x16_bf16 v[116:131], v[180:183], v[136:139], v[116:131]
	s_mov_b32 m0, s47
	s_nop 0
	global_load_lds_dwordx4 v178, s[76:77]
	global_load_lds_dwordx4 v179, s[78:79] offset:1024
	global_load_lds_dwordx4 v178, s[80:81] offset:2048
	global_load_lds_dwordx4 v179, s[82:83] offset:3072
	v_add_u32_e32 v178, 0x80, v178
	v_add_u32_e32 v179, 0x80, v179
	ds_read_b128 v[132:135], v230 offset:0
	ds_read_b128 v[136:139], v230 offset:4096
	ds_read_b128 v[140:143], v234 offset:0
	ds_read_b128 v[144:147], v234 offset:4096
	ds_read_b128 v[148:151], v234 offset:16384
	ds_read_b128 v[180:183], v234 offset:20480
	s_waitcnt lgkmcnt(6)
	v_mfma_f32_32x32x16_bf16 v[4:19], v[212:215], v[184:187], v[4:19]
	v_mfma_f32_32x32x16_bf16 v[68:83], v[212:215], v[208:211], v[68:83]
	v_mfma_f32_32x32x16_bf16 v[20:35], v[216:219], v[184:187], v[20:35]
	v_mfma_f32_32x32x16_bf16 v[84:99], v[216:219], v[208:211], v[84:99]
	v_mfma_f32_32x32x16_bf16 v[36:51], v[220:223], v[184:187], v[36:51]
	v_mfma_f32_32x32x16_bf16 v[100:115], v[220:223], v[208:211], v[100:115]
	v_mfma_f32_32x32x16_bf16 v[52:67], v[224:227], v[184:187], v[52:67]
	v_mfma_f32_32x32x16_bf16 v[116:131], v[224:227], v[208:211], v[116:131]
	ds_read_b128 v[184:187], v231 offset:0
	ds_read_b128 v[208:211], v231 offset:4096
	ds_read_b128 v[212:215], v235 offset:0
	ds_read_b128 v[216:219], v235 offset:4096
	ds_read_b128 v[220:223], v235 offset:16384
	ds_read_b128 v[224:227], v235 offset:20480
	s_waitcnt lgkmcnt(6)
	v_mfma_f32_32x32x16_bf16 v[4:19], v[140:143], v[132:135], v[4:19]
	v_mfma_f32_32x32x16_bf16 v[68:83], v[140:143], v[136:139], v[68:83]
	v_mfma_f32_32x32x16_bf16 v[20:35], v[144:147], v[132:135], v[20:35]
	v_mfma_f32_32x32x16_bf16 v[84:99], v[144:147], v[136:139], v[84:99]
	v_mfma_f32_32x32x16_bf16 v[36:51], v[148:151], v[132:135], v[36:51]
	v_mfma_f32_32x32x16_bf16 v[100:115], v[148:151], v[136:139], v[100:115]
	v_mfma_f32_32x32x16_bf16 v[52:67], v[180:183], v[132:135], v[52:67]
	v_mfma_f32_32x32x16_bf16 v[116:131], v[180:183], v[136:139], v[116:131]
	s_waitcnt lgkmcnt(0)
	v_mfma_f32_32x32x16_bf16 v[4:19], v[212:215], v[184:187], v[4:19]
	v_mfma_f32_32x32x16_bf16 v[68:83], v[212:215], v[208:211], v[68:83]
	v_mfma_f32_32x32x16_bf16 v[20:35], v[216:219], v[184:187], v[20:35]
	v_mfma_f32_32x32x16_bf16 v[84:99], v[216:219], v[208:211], v[84:99]
	v_mfma_f32_32x32x16_bf16 v[36:51], v[220:223], v[184:187], v[36:51]
	v_mfma_f32_32x32x16_bf16 v[100:115], v[220:223], v[208:211], v[100:115]
	v_mfma_f32_32x32x16_bf16 v[52:67], v[224:227], v[184:187], v[52:67]
	v_mfma_f32_32x32x16_bf16 v[116:131], v[224:227], v[208:211], v[116:131]
	s_waitcnt vmcnt(0) lgkmcnt(0)
	s_barrier
	ds_read_b128 v[132:135], v228 offset:32768
	ds_read_b128 v[136:139], v228 offset:36864
	ds_read_b128 v[140:143], v232 offset:32768
	ds_read_b128 v[144:147], v232 offset:36864
	ds_read_b128 v[148:151], v232 offset:49152
	ds_read_b128 v[180:183], v232 offset:53248
	s_mov_b32 m0, s44
	s_nop 0
	global_load_lds_dwordx4 v178, s[68:69]
	global_load_lds_dwordx4 v179, s[70:71] offset:1024
	global_load_lds_dwordx4 v178, s[72:73] offset:2048
	global_load_lds_dwordx4 v179, s[74:75] offset:3072
	ds_read_b128 v[184:187], v229 offset:32768
	ds_read_b128 v[208:211], v229 offset:36864
	ds_read_b128 v[212:215], v233 offset:32768
	ds_read_b128 v[216:219], v233 offset:36864
	ds_read_b128 v[220:223], v233 offset:49152
	ds_read_b128 v[224:227], v233 offset:53248
	s_waitcnt lgkmcnt(6)
	v_mfma_f32_32x32x16_bf16 v[4:19], v[140:143], v[132:135], v[4:19]
	v_mfma_f32_32x32x16_bf16 v[68:83], v[140:143], v[136:139], v[68:83]
	v_mfma_f32_32x32x16_bf16 v[20:35], v[144:147], v[132:135], v[20:35]
	v_mfma_f32_32x32x16_bf16 v[84:99], v[144:147], v[136:139], v[84:99]
	v_mfma_f32_32x32x16_bf16 v[36:51], v[148:151], v[132:135], v[36:51]
	v_mfma_f32_32x32x16_bf16 v[100:115], v[148:151], v[136:139], v[100:115]
	v_mfma_f32_32x32x16_bf16 v[52:67], v[180:183], v[132:135], v[52:67]
	v_mfma_f32_32x32x16_bf16 v[116:131], v[180:183], v[136:139], v[116:131]
	s_mov_b32 m0, s46
	s_nop 0
	global_load_lds_dwordx4 v178, s[76:77]
	global_load_lds_dwordx4 v179, s[78:79] offset:1024
	global_load_lds_dwordx4 v178, s[80:81] offset:2048
	global_load_lds_dwordx4 v179, s[82:83] offset:3072
	v_add_u32_e32 v178, 0x80, v178
	v_add_u32_e32 v179, 0x80, v179
	ds_read_b128 v[132:135], v230 offset:32768
	ds_read_b128 v[136:139], v230 offset:36864
	ds_read_b128 v[140:143], v234 offset:32768
	ds_read_b128 v[144:147], v234 offset:36864
	ds_read_b128 v[148:151], v234 offset:49152
	ds_read_b128 v[180:183], v234 offset:53248
	s_waitcnt lgkmcnt(6)
; #define MFMA32(a, b, c) __builtin_amdgcn_mfma_f32_32x32x16_bf16((a), (b), (c), 0, 0, 0)
; template <bool SWAP, class Epi>
; DI void gemm_tile(const u16* __restrict__ A, int lda, const u16* __restrict__ Bw, int ldb, int K, char* lds, Epi epi) {
;     ...
;   auto compute = [&](int st) {
;     const char* as = lds + st * GEMM_STAGE;
;     const char* bs = as + 36864;
; #pragma unroll
;     for (int ks = 0; ks < 4; ++ks) {
;       bf16x8 af[2], bfr[2];
; #pragma unroll
;       for (int mi = 0; mi < 2; ++mi) af[mi] = *(const bf16x8*)(as + ((wm * 64 + mi * 32 + r) * 72 + ks * 16 + 8 * h) * 2);
; #pragma unroll
;       for (int ni = 0; ni < 2; ++ni) bfr[ni] = *(const bf16x8*)(bs + ((wn * 64 + ni * 32 + r) * 72 + ks * 16 + 8 * h) * 2);
; #pragma unroll
;       for (int mi = 0; mi < 2; ++mi)
; #pragma unroll
;         for (int ni = 0; ni < 2; ++ni) {
;           if (SWAP) acc[mi][ni] = MFMA32(bfr[ni], af[mi], acc[mi][ni]);
;           else acc[mi][ni] = MFMA32(af[mi], bfr[ni], acc[mi][ni]);
;         }
;     }
;   };
;   gload(0, ra0, rb0);
;   lstore(0, ra0, rb0);
;   gload(1, ra1, rb1);
;   __syncthreads();
;   for (int kt = 0; kt < nk; kt += 2) {
;     if (kt + 2 < nk) gload(kt + 2, ra0, rb0);
;     compute(0);
;     lstore(1, ra1, rb1);
;     __syncthreads();
;     if (kt + 3 < nk) gload(kt + 3, ra1, rb1);
;     compute(1);
;     if (kt + 2 < nk) lstore(0, ra0, rb0);
;     __syncthreads();
;   }
	v_mfma_f32_32x32x16_bf16 v[4:19], v[212:215], v[184:187], v[4:19]
	v_mfma_f32_32x32x16_bf16 v[68:83], v[212:215], v[208:211], v[68:83]
	v_mfma_f32_32x32x16_bf16 v[20:35], v[216:219], v[184:187], v[20:35]
	v_mfma_f32_32x32x16_bf16 v[84:99], v[216:219], v[208:211], v[84:99]
	v_mfma_f32_32x32x16_bf16 v[36:51], v[220:223], v[184:187], v[36:51]
	v_mfma_f32_32x32x16_bf16 v[100:115], v[220:223], v[208:211], v[100:115]
	v_mfma_f32_32x32x16_bf16 v[52:67], v[224:227], v[184:187], v[52:67]
	v_mfma_f32_32x32x16_bf16 v[116:131], v[224:227], v[208:211], v[116:131]
	ds_read_b128 v[184:187], v231 offset:32768
	ds_read_b128 v[208:211], v231 offset:36864
	ds_read_b128 v[212:215], v235 offset:32768
	ds_read_b128 v[216:219], v235 offset:36864
	ds_read_b128 v[220:223], v235 offset:49152
	ds_read_b128 v[224:227], v235 offset:53248
	s_waitcnt lgkmcnt(6)
	v_mfma_f32_32x32x16_bf16 v[4:19], v[140:143], v[132:135], v[4:19]
	v_mfma_f32_32x32x16_bf16 v[68:83], v[140:143], v[136:139], v[68:83]
	v_mfma_f32_32x32x16_bf16 v[20:35], v[144:147], v[132:135], v[20:35]
	v_mfma_f32_32x32x16_bf16 v[84:99], v[144:147], v[136:139], v[84:99]
	v_mfma_f32_32x32x16_bf16 v[36:51], v[148:151], v[132:135], v[36:51]
	v_mfma_f32_32x32x16_bf16 v[100:115], v[148:151], v[136:139], v[100:115]
	v_mfma_f32_32x32x16_bf16 v[52:67], v[180:183], v[132:135], v[52:67]
	v_mfma_f32_32x32x16_bf16 v[116:131], v[180:183], v[136:139], v[116:131]
	s_waitcnt lgkmcnt(0)
	v_mfma_f32_32x32x16_bf16 v[4:19], v[212:215], v[184:187], v[4:19]
	v_mfma_f32_32x32x16_bf16 v[68:83], v[212:215], v[208:211], v[68:83]
	v_mfma_f32_32x32x16_bf16 v[20:35], v[216:219], v[184:187], v[20:35]
	v_mfma_f32_32x32x16_bf16 v[84:99], v[216:219], v[208:211], v[84:99]
	v_mfma_f32_32x32x16_bf16 v[36:51], v[220:223], v[184:187], v[36:51]
	v_mfma_f32_32x32x16_bf16 v[100:115], v[220:223], v[208:211], v[100:115]
	v_mfma_f32_32x32x16_bf16 v[52:67], v[224:227], v[184:187], v[52:67]
	v_mfma_f32_32x32x16_bf16 v[116:131], v[224:227], v[208:211], v[116:131]
	s_waitcnt vmcnt(0) lgkmcnt(0)
	s_barrier
	ds_read_b128 v[132:135], v228 offset:0
	ds_read_b128 v[136:139], v228 offset:4096
	ds_read_b128 v[140:143], v232 offset:0
	ds_read_b128 v[144:147], v232 offset:4096
	ds_read_b128 v[148:151], v232 offset:16384
	ds_read_b128 v[180:183], v232 offset:20480
	s_mov_b32 m0, s45
	s_nop 0
	global_load_lds_dwordx4 v178, s[68:69]
	global_load_lds_dwordx4 v179, s[70:71] offset:1024
	global_load_lds_dwordx4 v178, s[72:73] offset:2048
	global_load_lds_dwordx4 v179, s[74:75] offset:3072
	ds_read_b128 v[184:187], v229 offset:0
	ds_read_b128 v[208:211], v229 offset:4096
	ds_read_b128 v[212:215], v233 offset:0
	ds_read_b128 v[216:219], v233 offset:4096
	ds_read_b128 v[220:223], v233 offset:16384
	ds_read_b128 v[224:227], v233 offset:20480
	s_waitcnt lgkmcnt(6)
	v_mfma_f32_32x32x16_bf16 v[4:19], v[140:143], v[132:135], v[4:19]
	v_mfma_f32_32x32x16_bf16 v[68:83], v[140:143], v[136:139], v[68:83]
	v_mfma_f32_32x32x16_bf16 v[20:35], v[144:147], v[132:135], v[20:35]
	v_mfma_f32_32x32x16_bf16 v[84:99], v[144:147], v[136:139], v[84:99]
	v_mfma_f32_32x32x16_bf16 v[36:51], v[148:151], v[132:135], v[36:51]
	v_mfma_f32_32x32x16_bf16 v[100:115], v[148:151], v[136:139], v[100:115]
	v_mfma_f32_32x32x16_bf16 v[52:67], v[180:183], v[132:135], v[52:67]
	v_mfma_f32_32x32x16_bf16 v[116:131], v[180:183], v[136:139], v[116:131]
	s_mov_b32 m0, s47
	s_nop 0
	global_load_lds_dwordx4 v178, s[76:77]
	global_load_lds_dwordx4 v179, s[78:79] offset:1024
	global_load_lds_dwordx4 v178, s[80:81] offset:2048
	global_load_lds_dwordx4 v179, s[82:83] offset:3072
	v_add_u32_e32 v178, 0x80, v178
	v_add_u32_e32 v179, 0x80, v179
	ds_read_b128 v[132:135], v230 offset:0
	ds_read_b128 v[136:139], v230 offset:4096
	ds_read_b128 v[140:143], v234 offset:0
	ds_read_b128 v[144:147], v234 offset:4096
	ds_read_b128 v[148:151], v234 offset:16384
	ds_read_b128 v[180:183], v234 offset:20480
	s_waitcnt lgkmcnt(6)
	v_mfma_f32_32x32x16_bf16 v[4:19], v[212:215], v[184:187], v[4:19]
	v_mfma_f32_32x32x16_bf16 v[68:83], v[212:215], v[208:211], v[68:83]
	v_mfma_f32_32x32x16_bf16 v[20:35], v[216:219], v[184:187], v[20:35]
	v_mfma_f32_32x32x16_bf16 v[84:99], v[216:219], v[208:211], v[84:99]
	v_mfma_f32_32x32x16_bf16 v[36:51], v[220:223], v[184:187], v[36:51]
	v_mfma_f32_32x32x16_bf16 v[100:115], v[220:223], v[208:211], v[100:115]
	v_mfma_f32_32x32x16_bf16 v[52:67], v[224:227], v[184:187], v[52:67]
	v_mfma_f32_32x32x16_bf16 v[116:131], v[224:227], v[208:211], v[116:131]
	ds_read_b128 v[184:187], v231 offset:0
	ds_read_b128 v[208:211], v231 offset:4096
	ds_read_b128 v[212:215], v235 offset:0
	ds_read_b128 v[216:219], v235 offset:4096
	ds_read_b128 v[220:223], v235 offset:16384
	ds_read_b128 v[224:227], v235 offset:20480
	s_waitcnt lgkmcnt(6)
	v_mfma_f32_32x32x16_bf16 v[4:19], v[140:143], v[132:135], v[4:19]
	v_mfma_f32_32x32x16_bf16 v[68:83], v[140:143], v[136:139], v[68:83]
	v_mfma_f32_32x32x16_bf16 v[20:35], v[144:147], v[132:135], v[20:35]
	v_mfma_f32_32x32x16_bf16 v[84:99], v[144:147], v[136:139], v[84:99]
	v_mfma_f32_32x32x16_bf16 v[36:51], v[148:151], v[132:135], v[36:51]
	v_mfma_f32_32x32x16_bf16 v[100:115], v[148:151], v[136:139], v[100:115]
	v_mfma_f32_32x32x16_bf16 v[52:67], v[180:183], v[132:135], v[52:67]
	v_mfma_f32_32x32x16_bf16 v[116:131], v[180:183], v[136:139], v[116:131]
	s_waitcnt lgkmcnt(0)
	v_mfma_f32_32x32x16_bf16 v[4:19], v[212:215], v[184:187], v[4:19]
	v_mfma_f32_32x32x16_bf16 v[68:83], v[212:215], v[208:211], v[68:83]
	v_mfma_f32_32x32x16_bf16 v[20:35], v[216:219], v[184:187], v[20:35]
	v_mfma_f32_32x32x16_bf16 v[84:99], v[216:219], v[208:211], v[84:99]
	v_mfma_f32_32x32x16_bf16 v[36:51], v[220:223], v[184:187], v[36:51]
	v_mfma_f32_32x32x16_bf16 v[100:115], v[220:223], v[208:211], v[100:115]
	v_mfma_f32_32x32x16_bf16 v[52:67], v[224:227], v[184:187], v[52:67]
	v_mfma_f32_32x32x16_bf16 v[116:131], v[224:227], v[208:211], v[116:131]
	s_waitcnt vmcnt(0) lgkmcnt(0)
	s_barrier
; #define MFMA32(a, b, c) __builtin_amdgcn_mfma_f32_32x32x16_bf16((a), (b), (c), 0, 0, 0)
; template <bool SWAP, class Epi>
; DI void gemm_tile(const u16* __restrict__ A, int lda, const u16* __restrict__ Bw, int ldb, int K, char* lds, Epi epi) {
;     ...
;   auto compute = [&](int st) {
;     const char* as = lds + st * GEMM_STAGE;
;     const char* bs = as + 36864;
; #pragma unroll
;     for (int ks = 0; ks < 4; ++ks) {
;       bf16x8 af[2], bfr[2];
; #pragma unroll
;       for (int mi = 0; mi < 2; ++mi) af[mi] = *(const bf16x8*)(as + ((wm * 64 + mi * 32 + r) * 72 + ks * 16 + 8 * h) * 2);
; #pragma unroll
;       for (int ni = 0; ni < 2; ++ni) bfr[ni] = *(const bf16x8*)(bs + ((wn * 64 + ni * 32 + r) * 72 + ks * 16 + 8 * h) * 2);
; #pragma unroll
;       for (int mi = 0; mi < 2; ++mi)
; #pragma unroll
;         for (int ni = 0; ni < 2; ++ni) {
;           if (SWAP) acc[mi][ni] = MFMA32(bfr[ni], af[mi], acc[mi][ni]);
;           else acc[mi][ni] = MFMA32(af[mi], bfr[ni], acc[mi][ni]);
;         }
;     }
;   };
;   gload(0, ra0, rb0);
;   lstore(0, ra0, rb0);
;   gload(1, ra1, rb1);
;   __syncthreads();
;   for (int kt = 0; kt < nk; kt += 2) {
;     if (kt + 2 < nk) gload(kt + 2, ra0, rb0);
;     compute(0);
;     lstore(1, ra1, rb1);
;     __syncthreads();
;     if (kt + 3 < nk) gload(kt + 3, ra1, rb1);
;     compute(1);
;     if (kt + 2 < nk) lstore(0, ra0, rb0);
;     __syncthreads();
;   }
	ds_read_b128 v[132:135], v228 offset:32768
	ds_read_b128 v[136:139], v228 offset:36864
	ds_read_b128 v[140:143], v232 offset:32768
	ds_read_b128 v[144:147], v232 offset:36864
	ds_read_b128 v[148:151], v232 offset:49152
	ds_read_b128 v[180:183], v232 offset:53248
	s_mov_b32 m0, s44
	s_nop 0
	global_load_lds_dwordx4 v178, s[68:69]
	global_load_lds_dwordx4 v179, s[70:71] offset:1024
	global_load_lds_dwordx4 v178, s[72:73] offset:2048
	global_load_lds_dwordx4 v179, s[74:75] offset:3072
	ds_read_b128 v[184:187], v229 offset:32768
	ds_read_b128 v[208:211], v229 offset:36864
	ds_read_b128 v[212:215], v233 offset:32768
	ds_read_b128 v[216:219], v233 offset:36864
	ds_read_b128 v[220:223], v233 offset:49152
	ds_read_b128 v[224:227], v233 offset:53248
	s_waitcnt lgkmcnt(6)
	v_mfma_f32_32x32x16_bf16 v[4:19], v[140:143], v[132:135], v[4:19]
	v_mfma_f32_32x32x16_bf16 v[68:83], v[140:143], v[136:139], v[68:83]
	v_mfma_f32_32x32x16_bf16 v[20:35], v[144:147], v[132:135], v[20:35]
	v_mfma_f32_32x32x16_bf16 v[84:99], v[144:147], v[136:139], v[84:99]
	v_mfma_f32_32x32x16_bf16 v[36:51], v[148:151], v[132:135], v[36:51]
	v_mfma_f32_32x32x16_bf16 v[100:115], v[148:151], v[136:139], v[100:115]
	v_mfma_f32_32x32x16_bf16 v[52:67], v[180:183], v[132:135], v[52:67]
	v_mfma_f32_32x32x16_bf16 v[116:131], v[180:183], v[136:139], v[116:131]
	s_mov_b32 m0, s46
	s_nop 0
	global_load_lds_dwordx4 v178, s[76:77]
	global_load_lds_dwordx4 v179, s[78:79] offset:1024
	global_load_lds_dwordx4 v178, s[80:81] offset:2048
	global_load_lds_dwordx4 v179, s[82:83] offset:3072
	v_add_u32_e32 v178, 0x80, v178
	v_add_u32_e32 v179, 0x80, v179
	ds_read_b128 v[132:135], v230 offset:32768
	ds_read_b128 v[136:139], v230 offset:36864
	ds_read_b128 v[140:143], v234 offset:32768
	ds_read_b128 v[144:147], v234 offset:36864
	ds_read_b128 v[148:151], v234 offset:49152
	ds_read_b128 v[180:183], v234 offset:53248
	s_waitcnt lgkmcnt(6)
	v_mfma_f32_32x32x16_bf16 v[4:19], v[212:215], v[184:187], v[4:19]
	v_mfma_f32_32x32x16_bf16 v[68:83], v[212:215], v[208:211], v[68:83]
	v_mfma_f32_32x32x16_bf16 v[20:35], v[216:219], v[184:187], v[20:35]
	v_mfma_f32_32x32x16_bf16 v[84:99], v[216:219], v[208:211], v[84:99]
	v_mfma_f32_32x32x16_bf16 v[36:51], v[220:223], v[184:187], v[36:51]
	v_mfma_f32_32x32x16_bf16 v[100:115], v[220:223], v[208:211], v[100:115]
	v_mfma_f32_32x32x16_bf16 v[52:67], v[224:227], v[184:187], v[52:67]
	v_mfma_f32_32x32x16_bf16 v[116:131], v[224:227], v[208:211], v[116:131]
	ds_read_b128 v[184:187], v231 offset:32768
	ds_read_b128 v[208:211], v231 offset:36864
	ds_read_b128 v[212:215], v235 offset:32768
	ds_read_b128 v[216:219], v235 offset:36864
	ds_read_b128 v[220:223], v235 offset:49152
	ds_read_b128 v[224:227], v235 offset:53248
	s_waitcnt lgkmcnt(6)
	v_mfma_f32_32x32x16_bf16 v[4:19], v[140:143], v[132:135], v[4:19]
	v_mfma_f32_32x32x16_bf16 v[68:83], v[140:143], v[136:139], v[68:83]
	v_mfma_f32_32x32x16_bf16 v[20:35], v[144:147], v[132:135], v[20:35]
	v_mfma_f32_32x32x16_bf16 v[84:99], v[144:147], v[136:139], v[84:99]
	v_mfma_f32_32x32x16_bf16 v[36:51], v[148:151], v[132:135], v[36:51]
	v_mfma_f32_32x32x16_bf16 v[100:115], v[148:151], v[136:139], v[100:115]
	v_mfma_f32_32x32x16_bf16 v[52:67], v[180:183], v[132:135], v[52:67]
	v_mfma_f32_32x32x16_bf16 v[116:131], v[180:183], v[136:139], v[116:131]
	s_waitcnt lgkmcnt(0)
	v_mfma_f32_32x32x16_bf16 v[4:19], v[212:215], v[184:187], v[4:19]
	v_mfma_f32_32x32x16_bf16 v[68:83], v[212:215], v[208:211], v[68:83]
	v_mfma_f32_32x32x16_bf16 v[20:35], v[216:219], v[184:187], v[20:35]
	v_mfma_f32_32x32x16_bf16 v[84:99], v[216:219], v[208:211], v[84:99]
	v_mfma_f32_32x32x16_bf16 v[36:51], v[220:223], v[184:187], v[36:51]
	v_mfma_f32_32x32x16_bf16 v[100:115], v[220:223], v[208:211], v[100:115]
	v_mfma_f32_32x32x16_bf16 v[52:67], v[224:227], v[184:187], v[52:67]
	v_mfma_f32_32x32x16_bf16 v[116:131], v[224:227], v[208:211], v[116:131]
	s_waitcnt vmcnt(0) lgkmcnt(0)
	s_barrier
	ds_read_b128 v[132:135], v228 offset:0
	ds_read_b128 v[136:139], v228 offset:4096
	ds_read_b128 v[140:143], v232 offset:0
	ds_read_b128 v[144:147], v232 offset:4096
	ds_read_b128 v[148:151], v232 offset:16384
	ds_read_b128 v[180:183], v232 offset:20480
	s_mov_b32 m0, s45
	s_nop 0
	global_load_lds_dwordx4 v178, s[68:69]
	global_load_lds_dwordx4 v179, s[70:71] offset:1024
	global_load_lds_dwordx4 v178, s[72:73] offset:2048
	global_load_lds_dwordx4 v179, s[74:75] offset:3072
	ds_read_b128 v[184:187], v229 offset:0
	ds_read_b128 v[208:211], v229 offset:4096
	ds_read_b128 v[212:215], v233 offset:0
	ds_read_b128 v[216:219], v233 offset:4096
	ds_read_b128 v[220:223], v233 offset:16384
	ds_read_b128 v[224:227], v233 offset:20480
	s_waitcnt lgkmcnt(6)
	v_mfma_f32_32x32x16_bf16 v[4:19], v[140:143], v[132:135], v[4:19]
	v_mfma_f32_32x32x16_bf16 v[68:83], v[140:143], v[136:139], v[68:83]
	v_mfma_f32_32x32x16_bf16 v[20:35], v[144:147], v[132:135], v[20:35]
	v_mfma_f32_32x32x16_bf16 v[84:99], v[144:147], v[136:139], v[84:99]
	v_mfma_f32_32x32x16_bf16 v[36:51], v[148:151], v[132:135], v[36:51]
	v_mfma_f32_32x32x16_bf16 v[100:115], v[148:151], v[136:139], v[100:115]
	v_mfma_f32_32x32x16_bf16 v[52:67], v[180:183], v[132:135], v[52:67]
	v_mfma_f32_32x32x16_bf16 v[116:131], v[180:183], v[136:139], v[116:131]
	s_mov_b32 m0, s47
	s_nop 0
	global_load_lds_dwordx4 v178, s[76:77]
	global_load_lds_dwordx4 v179, s[78:79] offset:1024
	global_load_lds_dwordx4 v178, s[80:81] offset:2048
	global_load_lds_dwordx4 v179, s[82:83] offset:3072
	v_add_u32_e32 v178, 0x80, v178
	v_add_u32_e32 v179, 0x80, v179
	ds_read_b128 v[132:135], v230 offset:0
	ds_read_b128 v[136:139], v230 offset:4096
	ds_read_b128 v[140:143], v234 offset:0
	ds_read_b128 v[144:147], v234 offset:4096
	ds_read_b128 v[148:151], v234 offset:16384
	ds_read_b128 v[180:183], v234 offset:20480
	s_waitcnt lgkmcnt(6)
; #define MFMA32(a, b, c) __builtin_amdgcn_mfma_f32_32x32x16_bf16((a), (b), (c), 0, 0, 0)
; template <bool SWAP, class Epi>
; DI void gemm_tile(const u16* __restrict__ A, int lda, const u16* __restrict__ Bw, int ldb, int K, char* lds, Epi epi) {
;     ...
;   auto compute = [&](int st) {
;     const char* as = lds + st * GEMM_STAGE;
;     const char* bs = as + 36864;
; #pragma unroll
;     for (int ks = 0; ks < 4; ++ks) {
;       bf16x8 af[2], bfr[2];
; #pragma unroll
;       for (int mi = 0; mi < 2; ++mi) af[mi] = *(const bf16x8*)(as + ((wm * 64 + mi * 32 + r) * 72 + ks * 16 + 8 * h) * 2);
; #pragma unroll
;       for (int ni = 0; ni < 2; ++ni) bfr[ni] = *(const bf16x8*)(bs + ((wn * 64 + ni * 32 + r) * 72 + ks * 16 + 8 * h) * 2);
; #pragma unroll
;       for (int mi = 0; mi < 2; ++mi)
; #pragma unroll
;         for (int ni = 0; ni < 2; ++ni) {
;           if (SWAP) acc[mi][ni] = MFMA32(bfr[ni], af[mi], acc[mi][ni]);
;           else acc[mi][ni] = MFMA32(af[mi], bfr[ni], acc[mi][ni]);
;         }
;     }
;   };
;   gload(0, ra0, rb0);
;   lstore(0, ra0, rb0);
;   gload(1, ra1, rb1);
;   __syncthreads();
;   for (int kt = 0; kt < nk; kt += 2) {
;     if (kt + 2 < nk) gload(kt + 2, ra0, rb0);
;     compute(0);
;     lstore(1, ra1, rb1);
;     __syncthreads();
;     if (kt + 3 < nk) gload(kt + 3, ra1, rb1);
;     compute(1);
;     if (kt + 2 < nk) lstore(0, ra0, rb0);
;     __syncthreads();
;   }
	v_mfma_f32_32x32x16_bf16 v[4:19], v[212:215], v[184:187], v[4:19]
	v_mfma_f32_32x32x16_bf16 v[68:83], v[212:215], v[208:211], v[68:83]
	v_mfma_f32_32x32x16_bf16 v[20:35], v[216:219], v[184:187], v[20:35]
	v_mfma_f32_32x32x16_bf16 v[84:99], v[216:219], v[208:211], v[84:99]
	v_mfma_f32_32x32x16_bf16 v[36:51], v[220:223], v[184:187], v[36:51]
	v_mfma_f32_32x32x16_bf16 v[100:115], v[220:223], v[208:211], v[100:115]
	v_mfma_f32_32x32x16_bf16 v[52:67], v[224:227], v[184:187], v[52:67]
	v_mfma_f32_32x32x16_bf16 v[116:131], v[224:227], v[208:211], v[116:131]
	ds_read_b128 v[184:187], v231 offset:0
	ds_read_b128 v[208:211], v231 offset:4096
	ds_read_b128 v[212:215], v235 offset:0
	ds_read_b128 v[216:219], v235 offset:4096
	ds_read_b128 v[220:223], v235 offset:16384
	ds_read_b128 v[224:227], v235 offset:20480
	s_waitcnt lgkmcnt(6)
	v_mfma_f32_32x32x16_bf16 v[4:19], v[140:143], v[132:135], v[4:19]
	v_mfma_f32_32x32x16_bf16 v[68:83], v[140:143], v[136:139], v[68:83]
	v_mfma_f32_32x32x16_bf16 v[20:35], v[144:147], v[132:135], v[20:35]
	v_mfma_f32_32x32x16_bf16 v[84:99], v[144:147], v[136:139], v[84:99]
	v_mfma_f32_32x32x16_bf16 v[36:51], v[148:151], v[132:135], v[36:51]
	v_mfma_f32_32x32x16_bf16 v[100:115], v[148:151], v[136:139], v[100:115]
	v_mfma_f32_32x32x16_bf16 v[52:67], v[180:183], v[132:135], v[52:67]
	v_mfma_f32_32x32x16_bf16 v[116:131], v[180:183], v[136:139], v[116:131]
	s_waitcnt lgkmcnt(0)
	v_mfma_f32_32x32x16_bf16 v[4:19], v[212:215], v[184:187], v[4:19]
	v_mfma_f32_32x32x16_bf16 v[68:83], v[212:215], v[208:211], v[68:83]
	v_mfma_f32_32x32x16_bf16 v[20:35], v[216:219], v[184:187], v[20:35]
	v_mfma_f32_32x32x16_bf16 v[84:99], v[216:219], v[208:211], v[84:99]
	v_mfma_f32_32x32x16_bf16 v[36:51], v[220:223], v[184:187], v[36:51]
	v_mfma_f32_32x32x16_bf16 v[100:115], v[220:223], v[208:211], v[100:115]
	v_mfma_f32_32x32x16_bf16 v[52:67], v[224:227], v[184:187], v[52:67]
	v_mfma_f32_32x32x16_bf16 v[116:131], v[224:227], v[208:211], v[116:131]
	s_waitcnt vmcnt(0) lgkmcnt(0)
	s_barrier
	ds_read_b128 v[132:135], v228 offset:32768
	ds_read_b128 v[136:139], v228 offset:36864
	ds_read_b128 v[140:143], v232 offset:32768
	ds_read_b128 v[144:147], v232 offset:36864
	ds_read_b128 v[148:151], v232 offset:49152
	ds_read_b128 v[180:183], v232 offset:53248
	s_mov_b32 m0, s44
	s_nop 0
	global_load_lds_dwordx4 v178, s[68:69]
	global_load_lds_dwordx4 v179, s[70:71] offset:1024
	global_load_lds_dwordx4 v178, s[72:73] offset:2048
	global_load_lds_dwordx4 v179, s[74:75] offset:3072
	ds_read_b128 v[184:187], v229 offset:32768
	ds_read_b128 v[208:211], v229 offset:36864
	ds_read_b128 v[212:215], v233 offset:32768
	ds_read_b128 v[216:219], v233 offset:36864
	ds_read_b128 v[220:223], v233 offset:49152
	ds_read_b128 v[224:227], v233 offset:53248
	s_waitcnt lgkmcnt(6)
	v_mfma_f32_32x32x16_bf16 v[4:19], v[140:143], v[132:135], v[4:19]
	v_mfma_f32_32x32x16_bf16 v[68:83], v[140:143], v[136:139], v[68:83]
	v_mfma_f32_32x32x16_bf16 v[20:35], v[144:147], v[132:135], v[20:35]
	v_mfma_f32_32x32x16_bf16 v[84:99], v[144:147], v[136:139], v[84:99]
	v_mfma_f32_32x32x16_bf16 v[36:51], v[148:151], v[132:135], v[36:51]
	v_mfma_f32_32x32x16_bf16 v[100:115], v[148:151], v[136:139], v[100:115]
	v_mfma_f32_32x32x16_bf16 v[52:67], v[180:183], v[132:135], v[52:67]
	v_mfma_f32_32x32x16_bf16 v[116:131], v[180:183], v[136:139], v[116:131]
	s_mov_b32 m0, s46
	s_nop 0
	global_load_lds_dwordx4 v178, s[76:77]
	global_load_lds_dwordx4 v179, s[78:79] offset:1024
	global_load_lds_dwordx4 v178, s[80:81] offset:2048
	global_load_lds_dwordx4 v179, s[82:83] offset:3072
	v_add_u32_e32 v178, 0x80, v178
	v_add_u32_e32 v179, 0x80, v179
	ds_read_b128 v[132:135], v230 offset:32768
	ds_read_b128 v[136:139], v230 offset:36864
	ds_read_b128 v[140:143], v234 offset:32768
	ds_read_b128 v[144:147], v234 offset:36864
	ds_read_b128 v[148:151], v234 offset:49152
	ds_read_b128 v[180:183], v234 offset:53248
	s_waitcnt lgkmcnt(6)
	v_mfma_f32_32x32x16_bf16 v[4:19], v[212:215], v[184:187], v[4:19]
	v_mfma_f32_32x32x16_bf16 v[68:83], v[212:215], v[208:211], v[68:83]
	v_mfma_f32_32x32x16_bf16 v[20:35], v[216:219], v[184:187], v[20:35]
	v_mfma_f32_32x32x16_bf16 v[84:99], v[216:219], v[208:211], v[84:99]
	v_mfma_f32_32x32x16_bf16 v[36:51], v[220:223], v[184:187], v[36:51]
	v_mfma_f32_32x32x16_bf16 v[100:115], v[220:223], v[208:211], v[100:115]
	v_mfma_f32_32x32x16_bf16 v[52:67], v[224:227], v[184:187], v[52:67]
	v_mfma_f32_32x32x16_bf16 v[116:131], v[224:227], v[208:211], v[116:131]
	ds_read_b128 v[184:187], v231 offset:32768
	ds_read_b128 v[208:211], v231 offset:36864
	ds_read_b128 v[212:215], v235 offset:32768
	ds_read_b128 v[216:219], v235 offset:36864
	ds_read_b128 v[220:223], v235 offset:49152
	ds_read_b128 v[224:227], v235 offset:53248
	s_waitcnt lgkmcnt(6)
	v_mfma_f32_32x32x16_bf16 v[4:19], v[140:143], v[132:135], v[4:19]
	v_mfma_f32_32x32x16_bf16 v[68:83], v[140:143], v[136:139], v[68:83]
	v_mfma_f32_32x32x16_bf16 v[20:35], v[144:147], v[132:135], v[20:35]
	v_mfma_f32_32x32x16_bf16 v[84:99], v[144:147], v[136:139], v[84:99]
	v_mfma_f32_32x32x16_bf16 v[36:51], v[148:151], v[132:135], v[36:51]
	v_mfma_f32_32x32x16_bf16 v[100:115], v[148:151], v[136:139], v[100:115]
	v_mfma_f32_32x32x16_bf16 v[52:67], v[180:183], v[132:135], v[52:67]
	v_mfma_f32_32x32x16_bf16 v[116:131], v[180:183], v[136:139], v[116:131]
	s_waitcnt lgkmcnt(0)
	v_mfma_f32_32x32x16_bf16 v[4:19], v[212:215], v[184:187], v[4:19]
	v_mfma_f32_32x32x16_bf16 v[68:83], v[212:215], v[208:211], v[68:83]
	v_mfma_f32_32x32x16_bf16 v[20:35], v[216:219], v[184:187], v[20:35]
	v_mfma_f32_32x32x16_bf16 v[84:99], v[216:219], v[208:211], v[84:99]
	v_mfma_f32_32x32x16_bf16 v[36:51], v[220:223], v[184:187], v[36:51]
	v_mfma_f32_32x32x16_bf16 v[100:115], v[220:223], v[208:211], v[100:115]
	v_mfma_f32_32x32x16_bf16 v[52:67], v[224:227], v[184:187], v[52:67]
	v_mfma_f32_32x32x16_bf16 v[116:131], v[224:227], v[208:211], v[116:131]
	s_waitcnt vmcnt(0) lgkmcnt(0)
	s_barrier
; #define MFMA32(a, b, c) __builtin_amdgcn_mfma_f32_32x32x16_bf16((a), (b), (c), 0, 0, 0)
; template <bool SWAP, class Epi>
; DI void gemm_tile(const u16* __restrict__ A, int lda, const u16* __restrict__ Bw, int ldb, int K, char* lds, Epi epi) {
;     ...
;     for (int ks = 0; ks < 4; ++ks) {
;       bf16x8 af[2], bfr[2];
; #pragma unroll
;       for (int mi = 0; mi < 2; ++mi) af[mi] = *(const bf16x8*)(as + ((wm * 64 + mi * 32 + r) * 72 + ks * 16 + 8 * h) * 2);
; #pragma unroll
;       for (int ni = 0; ni < 2; ++ni) bfr[ni] = *(const bf16x8*)(bs + ((wn * 64 + ni * 32 + r) * 72 + ks * 16 + 8 * h) * 2);
; #pragma unroll
;       for (int mi = 0; mi < 2; ++mi)
; #pragma unroll
;         for (int ni = 0; ni < 2; ++ni) {
;           if (SWAP) acc[mi][ni] = MFMA32(bfr[ni], af[mi], acc[mi][ni]);
;           else acc[mi][ni] = MFMA32(af[mi], bfr[ni], acc[mi][ni]);
;         }
;     }
;   };
;   gload(0, ra0, rb0);
;   lstore(0, ra0, rb0);
;   gload(1, ra1, rb1);
;   __syncthreads();
;   for (int kt = 0; kt < nk; kt += 2) {
;     if (kt + 2 < nk) gload(kt + 2, ra0, rb0);
;     compute(0);
;     lstore(1, ra1, rb1);
;     __syncthreads();
;     if (kt + 3 < nk) gload(kt + 3, ra1, rb1);
;     compute(1);
;     if (kt + 2 < nk) lstore(0, ra0, rb0);
;     __syncthreads();
	ds_read_b128 v[132:135], v228 offset:0
	ds_read_b128 v[136:139], v228 offset:4096
	ds_read_b128 v[140:143], v232 offset:0
	ds_read_b128 v[144:147], v232 offset:4096
	ds_read_b128 v[148:151], v232 offset:16384
	ds_read_b128 v[180:183], v232 offset:20480
	s_mov_b32 m0, s45
	s_nop 0
	global_load_lds_dwordx4 v178, s[68:69]
	global_load_lds_dwordx4 v179, s[70:71] offset:1024
	global_load_lds_dwordx4 v178, s[72:73] offset:2048
	global_load_lds_dwordx4 v179, s[74:75] offset:3072
	ds_read_b128 v[184:187], v229 offset:0
	ds_read_b128 v[208:211], v229 offset:4096
	ds_read_b128 v[212:215], v233 offset:0
	ds_read_b128 v[216:219], v233 offset:4096
	ds_read_b128 v[220:223], v233 offset:16384
	ds_read_b128 v[224:227], v233 offset:20480
	s_waitcnt lgkmcnt(6)
	v_mfma_f32_32x32x16_bf16 v[4:19], v[140:143], v[132:135], v[4:19]
	v_mfma_f32_32x32x16_bf16 v[68:83], v[140:143], v[136:139], v[68:83]
	v_mfma_f32_32x32x16_bf16 v[20:35], v[144:147], v[132:135], v[20:35]
	v_mfma_f32_32x32x16_bf16 v[84:99], v[144:147], v[136:139], v[84:99]
	v_mfma_f32_32x32x16_bf16 v[36:51], v[148:151], v[132:135], v[36:51]
	v_mfma_f32_32x32x16_bf16 v[100:115], v[148:151], v[136:139], v[100:115]
	v_mfma_f32_32x32x16_bf16 v[52:67], v[180:183], v[132:135], v[52:67]
	v_mfma_f32_32x32x16_bf16 v[116:131], v[180:183], v[136:139], v[116:131]
	s_mov_b32 m0, s47
	s_nop 0
	global_load_lds_dwordx4 v178, s[76:77]
	global_load_lds_dwordx4 v179, s[78:79] offset:1024
	global_load_lds_dwordx4 v178, s[80:81] offset:2048
	global_load_lds_dwordx4 v179, s[82:83] offset:3072
	v_add_u32_e32 v178, 0x80, v178
	v_add_u32_e32 v179, 0x80, v179
	ds_read_b128 v[132:135], v230 offset:0
	ds_read_b128 v[136:139], v230 offset:4096
	ds_read_b128 v[140:143], v234 offset:0
	ds_read_b128 v[144:147], v234 offset:4096
	ds_read_b128 v[148:151], v234 offset:16384
	ds_read_b128 v[180:183], v234 offset:20480
	s_waitcnt lgkmcnt(6)
	v_mfma_f32_32x32x16_bf16 v[4:19], v[212:215], v[184:187], v[4:19]
	v_mfma_f32_32x32x16_bf16 v[68:83], v[212:215], v[208:211], v[68:83]
	v_mfma_f32_32x32x16_bf16 v[20:35], v[216:219], v[184:187], v[20:35]
	v_mfma_f32_32x32x16_bf16 v[84:99], v[216:219], v[208:211], v[84:99]
	v_mfma_f32_32x32x16_bf16 v[36:51], v[220:223], v[184:187], v[36:51]
	v_mfma_f32_32x32x16_bf16 v[100:115], v[220:223], v[208:211], v[100:115]
	v_mfma_f32_32x32x16_bf16 v[52:67], v[224:227], v[184:187], v[52:67]
	v_mfma_f32_32x32x16_bf16 v[116:131], v[224:227], v[208:211], v[116:131]
	ds_read_b128 v[184:187], v231 offset:0
	ds_read_b128 v[208:211], v231 offset:4096
	ds_read_b128 v[212:215], v235 offset:0
	ds_read_b128 v[216:219], v235 offset:4096
	ds_read_b128 v[220:223], v235 offset:16384
	ds_read_b128 v[224:227], v235 offset:20480
	s_waitcnt lgkmcnt(6)
	v_mfma_f32_32x32x16_bf16 v[4:19], v[140:143], v[132:135], v[4:19]
	v_mfma_f32_32x32x16_bf16 v[68:83], v[140:143], v[136:139], v[68:83]
	v_mfma_f32_32x32x16_bf16 v[20:35], v[144:147], v[132:135], v[20:35]
	v_mfma_f32_32x32x16_bf16 v[84:99], v[144:147], v[136:139], v[84:99]
	v_mfma_f32_32x32x16_bf16 v[36:51], v[148:151], v[132:135], v[36:51]
	v_mfma_f32_32x32x16_bf16 v[100:115], v[148:151], v[136:139], v[100:115]
	v_mfma_f32_32x32x16_bf16 v[52:67], v[180:183], v[132:135], v[52:67]
	v_mfma_f32_32x32x16_bf16 v[116:131], v[180:183], v[136:139], v[116:131]
	s_waitcnt lgkmcnt(0)
	v_mfma_f32_32x32x16_bf16 v[4:19], v[212:215], v[184:187], v[4:19]
	v_mfma_f32_32x32x16_bf16 v[68:83], v[212:215], v[208:211], v[68:83]
	v_mfma_f32_32x32x16_bf16 v[20:35], v[216:219], v[184:187], v[20:35]
	v_mfma_f32_32x32x16_bf16 v[84:99], v[216:219], v[208:211], v[84:99]
	v_mfma_f32_32x32x16_bf16 v[36:51], v[220:223], v[184:187], v[36:51]
	v_mfma_f32_32x32x16_bf16 v[100:115], v[220:223], v[208:211], v[100:115]
	v_mfma_f32_32x32x16_bf16 v[52:67], v[224:227], v[184:187], v[52:67]
	v_mfma_f32_32x32x16_bf16 v[116:131], v[224:227], v[208:211], v[116:131]
	s_waitcnt vmcnt(0) lgkmcnt(0)
	s_barrier
	ds_read_b128 v[132:135], v228 offset:32768
	ds_read_b128 v[136:139], v228 offset:36864
	ds_read_b128 v[140:143], v232 offset:32768
	ds_read_b128 v[144:147], v232 offset:36864
	ds_read_b128 v[148:151], v232 offset:49152
	ds_read_b128 v[180:183], v232 offset:53248
	s_mov_b32 m0, s44
	s_nop 0
	global_load_lds_dwordx4 v178, s[68:69]
	global_load_lds_dwordx4 v179, s[70:71] offset:1024
	global_load_lds_dwordx4 v178, s[72:73] offset:2048
	global_load_lds_dwordx4 v179, s[74:75] offset:3072
	ds_read_b128 v[184:187], v229 offset:32768
	ds_read_b128 v[208:211], v229 offset:36864
	ds_read_b128 v[212:215], v233 offset:32768
	ds_read_b128 v[216:219], v233 offset:36864
	ds_read_b128 v[220:223], v233 offset:49152
	ds_read_b128 v[224:227], v233 offset:53248
	s_waitcnt lgkmcnt(6)
	v_mfma_f32_32x32x16_bf16 v[4:19], v[140:143], v[132:135], v[4:19]
	v_mfma_f32_32x32x16_bf16 v[68:83], v[140:143], v[136:139], v[68:83]
	v_mfma_f32_32x32x16_bf16 v[20:35], v[144:147], v[132:135], v[20:35]
	v_mfma_f32_32x32x16_bf16 v[84:99], v[144:147], v[136:139], v[84:99]
	v_mfma_f32_32x32x16_bf16 v[36:51], v[148:151], v[132:135], v[36:51]
	v_mfma_f32_32x32x16_bf16 v[100:115], v[148:151], v[136:139], v[100:115]
	v_mfma_f32_32x32x16_bf16 v[52:67], v[180:183], v[132:135], v[52:67]
	v_mfma_f32_32x32x16_bf16 v[116:131], v[180:183], v[136:139], v[116:131]
	s_mov_b32 m0, s46
	s_nop 0
	global_load_lds_dwordx4 v178, s[76:77]
	global_load_lds_dwordx4 v179, s[78:79] offset:1024
	global_load_lds_dwordx4 v178, s[80:81] offset:2048
	global_load_lds_dwordx4 v179, s[82:83] offset:3072
	v_add_u32_e32 v178, 0x80, v178
	v_add_u32_e32 v179, 0x80, v179
	ds_read_b128 v[132:135], v230 offset:32768
	ds_read_b128 v[136:139], v230 offset:36864
	ds_read_b128 v[140:143], v234 offset:32768
	ds_read_b128 v[144:147], v234 offset:36864
	ds_read_b128 v[148:151], v234 offset:49152
	ds_read_b128 v[180:183], v234 offset:53248
	s_waitcnt lgkmcnt(6)
; #define MFMA32(a, b, c) __builtin_amdgcn_mfma_f32_32x32x16_bf16((a), (b), (c), 0, 0, 0)
; template <bool SWAP, class Epi>
; DI void gemm_tile(const u16* __restrict__ A, int lda, const u16* __restrict__ Bw, int ldb, int K, char* lds, Epi epi) {
;     ...
;     for (int ks = 0; ks < 4; ++ks) {
;       bf16x8 af[2], bfr[2];
; #pragma unroll
;       for (int mi = 0; mi < 2; ++mi) af[mi] = *(const bf16x8*)(as + ((wm * 64 + mi * 32 + r) * 72 + ks * 16 + 8 * h) * 2);
; #pragma unroll
;       for (int ni = 0; ni < 2; ++ni) bfr[ni] = *(const bf16x8*)(bs + ((wn * 64 + ni * 32 + r) * 72 + ks * 16 + 8 * h) * 2);
; #pragma unroll
;       for (int mi = 0; mi < 2; ++mi)
; #pragma unroll
;         for (int ni = 0; ni < 2; ++ni) {
;           if (SWAP) acc[mi][ni] = MFMA32(bfr[ni], af[mi], acc[mi][ni]);
;           else acc[mi][ni] = MFMA32(af[mi], bfr[ni], acc[mi][ni]);
;         }
;     }
;   };
;   gload(0, ra0, rb0);
;   lstore(0, ra0, rb0);
;   gload(1, ra1, rb1);
;   __syncthreads();
;   for (int kt = 0; kt < nk; kt += 2) {
;     if (kt + 2 < nk) gload(kt + 2, ra0, rb0);
;     compute(0);
;     lstore(1, ra1, rb1);
;     __syncthreads();
;     if (kt + 3 < nk) gload(kt + 3, ra1, rb1);
;     compute(1);
;     if (kt + 2 < nk) lstore(0, ra0, rb0);
;     __syncthreads();
	v_mfma_f32_32x32x16_bf16 v[4:19], v[212:215], v[184:187], v[4:19]
	v_mfma_f32_32x32x16_bf16 v[68:83], v[212:215], v[208:211], v[68:83]
	v_mfma_f32_32x32x16_bf16 v[20:35], v[216:219], v[184:187], v[20:35]
	v_mfma_f32_32x32x16_bf16 v[84:99], v[216:219], v[208:211], v[84:99]
	v_mfma_f32_32x32x16_bf16 v[36:51], v[220:223], v[184:187], v[36:51]
	v_mfma_f32_32x32x16_bf16 v[100:115], v[220:223], v[208:211], v[100:115]
	v_mfma_f32_32x32x16_bf16 v[52:67], v[224:227], v[184:187], v[52:67]
	v_mfma_f32_32x32x16_bf16 v[116:131], v[224:227], v[208:211], v[116:131]
	ds_read_b128 v[184:187], v231 offset:32768
	ds_read_b128 v[208:211], v231 offset:36864
	ds_read_b128 v[212:215], v235 offset:32768
	ds_read_b128 v[216:219], v235 offset:36864
	ds_read_b128 v[220:223], v235 offset:49152
	ds_read_b128 v[224:227], v235 offset:53248
	s_waitcnt lgkmcnt(6)
	v_mfma_f32_32x32x16_bf16 v[4:19], v[140:143], v[132:135], v[4:19]
	v_mfma_f32_32x32x16_bf16 v[68:83], v[140:143], v[136:139], v[68:83]
	v_mfma_f32_32x32x16_bf16 v[20:35], v[144:147], v[132:135], v[20:35]
	v_mfma_f32_32x32x16_bf16 v[84:99], v[144:147], v[136:139], v[84:99]
	v_mfma_f32_32x32x16_bf16 v[36:51], v[148:151], v[132:135], v[36:51]
	v_mfma_f32_32x32x16_bf16 v[100:115], v[148:151], v[136:139], v[100:115]
	v_mfma_f32_32x32x16_bf16 v[52:67], v[180:183], v[132:135], v[52:67]
	v_mfma_f32_32x32x16_bf16 v[116:131], v[180:183], v[136:139], v[116:131]
	s_waitcnt lgkmcnt(0)
	v_mfma_f32_32x32x16_bf16 v[4:19], v[212:215], v[184:187], v[4:19]
	v_mfma_f32_32x32x16_bf16 v[68:83], v[212:215], v[208:211], v[68:83]
	v_mfma_f32_32x32x16_bf16 v[20:35], v[216:219], v[184:187], v[20:35]
	v_mfma_f32_32x32x16_bf16 v[84:99], v[216:219], v[208:211], v[84:99]
	v_mfma_f32_32x32x16_bf16 v[36:51], v[220:223], v[184:187], v[36:51]
	v_mfma_f32_32x32x16_bf16 v[100:115], v[220:223], v[208:211], v[100:115]
	v_mfma_f32_32x32x16_bf16 v[52:67], v[224:227], v[184:187], v[52:67]
	v_mfma_f32_32x32x16_bf16 v[116:131], v[224:227], v[208:211], v[116:131]
	s_waitcnt vmcnt(0) lgkmcnt(0)
	s_barrier
	ds_read_b128 v[132:135], v228 offset:0
	ds_read_b128 v[136:139], v228 offset:4096
	ds_read_b128 v[140:143], v232 offset:0
	ds_read_b128 v[144:147], v232 offset:4096
	ds_read_b128 v[148:151], v232 offset:16384
	ds_read_b128 v[180:183], v232 offset:20480
	s_mov_b32 m0, s45
	s_nop 0
	global_load_lds_dwordx4 v178, s[68:69]
	global_load_lds_dwordx4 v179, s[70:71] offset:1024
	global_load_lds_dwordx4 v178, s[72:73] offset:2048
	global_load_lds_dwordx4 v179, s[74:75] offset:3072
	ds_read_b128 v[184:187], v229 offset:0
	ds_read_b128 v[208:211], v229 offset:4096
	ds_read_b128 v[212:215], v233 offset:0
	ds_read_b128 v[216:219], v233 offset:4096
	ds_read_b128 v[220:223], v233 offset:16384
	ds_read_b128 v[224:227], v233 offset:20480
	s_waitcnt lgkmcnt(6)
	v_mfma_f32_32x32x16_bf16 v[4:19], v[140:143], v[132:135], v[4:19]
	v_mfma_f32_32x32x16_bf16 v[68:83], v[140:143], v[136:139], v[68:83]
	v_mfma_f32_32x32x16_bf16 v[20:35], v[144:147], v[132:135], v[20:35]
	v_mfma_f32_32x32x16_bf16 v[84:99], v[144:147], v[136:139], v[84:99]
	v_mfma_f32_32x32x16_bf16 v[36:51], v[148:151], v[132:135], v[36:51]
	v_mfma_f32_32x32x16_bf16 v[100:115], v[148:151], v[136:139], v[100:115]
	v_mfma_f32_32x32x16_bf16 v[52:67], v[180:183], v[132:135], v[52:67]
	v_mfma_f32_32x32x16_bf16 v[116:131], v[180:183], v[136:139], v[116:131]
	s_mov_b32 m0, s47
	s_nop 0
	global_load_lds_dwordx4 v178, s[76:77]
	global_load_lds_dwordx4 v179, s[78:79] offset:1024
	global_load_lds_dwordx4 v178, s[80:81] offset:2048
	global_load_lds_dwordx4 v179, s[82:83] offset:3072
	v_add_u32_e32 v178, 0x80, v178
	v_add_u32_e32 v179, 0x80, v179
	ds_read_b128 v[132:135], v230 offset:0
	ds_read_b128 v[136:139], v230 offset:4096
	ds_read_b128 v[140:143], v234 offset:0
	ds_read_b128 v[144:147], v234 offset:4096
	ds_read_b128 v[148:151], v234 offset:16384
	ds_read_b128 v[180:183], v234 offset:20480
	s_waitcnt lgkmcnt(6)
	v_mfma_f32_32x32x16_bf16 v[4:19], v[212:215], v[184:187], v[4:19]
	v_mfma_f32_32x32x16_bf16 v[68:83], v[212:215], v[208:211], v[68:83]
	v_mfma_f32_32x32x16_bf16 v[20:35], v[216:219], v[184:187], v[20:35]
	v_mfma_f32_32x32x16_bf16 v[84:99], v[216:219], v[208:211], v[84:99]
	v_mfma_f32_32x32x16_bf16 v[36:51], v[220:223], v[184:187], v[36:51]
	v_mfma_f32_32x32x16_bf16 v[100:115], v[220:223], v[208:211], v[100:115]
	v_mfma_f32_32x32x16_bf16 v[52:67], v[224:227], v[184:187], v[52:67]
	v_mfma_f32_32x32x16_bf16 v[116:131], v[224:227], v[208:211], v[116:131]
	ds_read_b128 v[184:187], v231 offset:0
	ds_read_b128 v[208:211], v231 offset:4096
	ds_read_b128 v[212:215], v235 offset:0
	ds_read_b128 v[216:219], v235 offset:4096
	ds_read_b128 v[220:223], v235 offset:16384
	ds_read_b128 v[224:227], v235 offset:20480
	s_waitcnt lgkmcnt(6)
	v_mfma_f32_32x32x16_bf16 v[4:19], v[140:143], v[132:135], v[4:19]
	v_mfma_f32_32x32x16_bf16 v[68:83], v[140:143], v[136:139], v[68:83]
	v_mfma_f32_32x32x16_bf16 v[20:35], v[144:147], v[132:135], v[20:35]
	v_mfma_f32_32x32x16_bf16 v[84:99], v[144:147], v[136:139], v[84:99]
	v_mfma_f32_32x32x16_bf16 v[36:51], v[148:151], v[132:135], v[36:51]
	v_mfma_f32_32x32x16_bf16 v[100:115], v[148:151], v[136:139], v[100:115]
	v_mfma_f32_32x32x16_bf16 v[52:67], v[180:183], v[132:135], v[52:67]
	v_mfma_f32_32x32x16_bf16 v[116:131], v[180:183], v[136:139], v[116:131]
	s_waitcnt lgkmcnt(0)
	v_mfma_f32_32x32x16_bf16 v[4:19], v[212:215], v[184:187], v[4:19]
	v_mfma_f32_32x32x16_bf16 v[68:83], v[212:215], v[208:211], v[68:83]
	v_mfma_f32_32x32x16_bf16 v[20:35], v[216:219], v[184:187], v[20:35]
	v_mfma_f32_32x32x16_bf16 v[84:99], v[216:219], v[208:211], v[84:99]
	v_mfma_f32_32x32x16_bf16 v[36:51], v[220:223], v[184:187], v[36:51]
	v_mfma_f32_32x32x16_bf16 v[100:115], v[220:223], v[208:211], v[100:115]
	v_mfma_f32_32x32x16_bf16 v[52:67], v[224:227], v[184:187], v[52:67]
	v_mfma_f32_32x32x16_bf16 v[116:131], v[224:227], v[208:211], v[116:131]
	s_waitcnt vmcnt(0) lgkmcnt(0)
	s_barrier
; #define MFMA32(a, b, c) __builtin_amdgcn_mfma_f32_32x32x16_bf16((a), (b), (c), 0, 0, 0)
; template <bool SWAP, class Epi>
; DI void gemm_tile(const u16* __restrict__ A, int lda, const u16* __restrict__ Bw, int ldb, int K, char* lds, Epi epi) {
;     ...
;     for (int ks = 0; ks < 4; ++ks) {
;       bf16x8 af[2], bfr[2];
; #pragma unroll
;       for (int mi = 0; mi < 2; ++mi) af[mi] = *(const bf16x8*)(as + ((wm * 64 + mi * 32 + r) * 72 + ks * 16 + 8 * h) * 2);
; #pragma unroll
;       for (int ni = 0; ni < 2; ++ni) bfr[ni] = *(const bf16x8*)(bs + ((wn * 64 + ni * 32 + r) * 72 + ks * 16 + 8 * h) * 2);
; #pragma unroll
;       for (int mi = 0; mi < 2; ++mi)
; #pragma unroll
;         for (int ni = 0; ni < 2; ++ni) {
;           if (SWAP) acc[mi][ni] = MFMA32(bfr[ni], af[mi], acc[mi][ni]);
;           else acc[mi][ni] = MFMA32(af[mi], bfr[ni], acc[mi][ni]);
;         }
;     }
;   };
;   gload(0, ra0, rb0);
;   lstore(0, ra0, rb0);
;   gload(1, ra1, rb1);
;   __syncthreads();
;   for (int kt = 0; kt < nk; kt += 2) {
;     if (kt + 2 < nk) gload(kt + 2, ra0, rb0);
;     compute(0);
;     lstore(1, ra1, rb1);
;     __syncthreads();
;     if (kt + 3 < nk) gload(kt + 3, ra1, rb1);
;     compute(1);
;     if (kt + 2 < nk) lstore(0, ra0, rb0);
;     __syncthreads();
	ds_read_b128 v[132:135], v228 offset:32768
	ds_read_b128 v[136:139], v228 offset:36864
	ds_read_b128 v[140:143], v232 offset:32768
	ds_read_b128 v[144:147], v232 offset:36864
	ds_read_b128 v[148:151], v232 offset:49152
	ds_read_b128 v[180:183], v232 offset:53248
	s_mov_b32 m0, s44
	s_nop 0
	global_load_lds_dwordx4 v178, s[68:69]
	global_load_lds_dwordx4 v179, s[70:71] offset:1024
	global_load_lds_dwordx4 v178, s[72:73] offset:2048
	global_load_lds_dwordx4 v179, s[74:75] offset:3072
	ds_read_b128 v[184:187], v229 offset:32768
	ds_read_b128 v[208:211], v229 offset:36864
	ds_read_b128 v[212:215], v233 offset:32768
	ds_read_b128 v[216:219], v233 offset:36864
	ds_read_b128 v[220:223], v233 offset:49152
	ds_read_b128 v[224:227], v233 offset:53248
	s_waitcnt lgkmcnt(6)
	v_mfma_f32_32x32x16_bf16 v[4:19], v[140:143], v[132:135], v[4:19]
	v_mfma_f32_32x32x16_bf16 v[68:83], v[140:143], v[136:139], v[68:83]
	v_mfma_f32_32x32x16_bf16 v[20:35], v[144:147], v[132:135], v[20:35]
	v_mfma_f32_32x32x16_bf16 v[84:99], v[144:147], v[136:139], v[84:99]
	v_mfma_f32_32x32x16_bf16 v[36:51], v[148:151], v[132:135], v[36:51]
	v_mfma_f32_32x32x16_bf16 v[100:115], v[148:151], v[136:139], v[100:115]
	v_mfma_f32_32x32x16_bf16 v[52:67], v[180:183], v[132:135], v[52:67]
	v_mfma_f32_32x32x16_bf16 v[116:131], v[180:183], v[136:139], v[116:131]
	s_mov_b32 m0, s46
	s_nop 0
	global_load_lds_dwordx4 v178, s[76:77]
	global_load_lds_dwordx4 v179, s[78:79] offset:1024
	global_load_lds_dwordx4 v178, s[80:81] offset:2048
	global_load_lds_dwordx4 v179, s[82:83] offset:3072
	v_add_u32_e32 v178, 0x80, v178
	v_add_u32_e32 v179, 0x80, v179
	ds_read_b128 v[132:135], v230 offset:32768
	ds_read_b128 v[136:139], v230 offset:36864
	ds_read_b128 v[140:143], v234 offset:32768
	ds_read_b128 v[144:147], v234 offset:36864
	ds_read_b128 v[148:151], v234 offset:49152
	ds_read_b128 v[180:183], v234 offset:53248
	s_waitcnt lgkmcnt(6)
	v_mfma_f32_32x32x16_bf16 v[4:19], v[212:215], v[184:187], v[4:19]
	v_mfma_f32_32x32x16_bf16 v[68:83], v[212:215], v[208:211], v[68:83]
	v_mfma_f32_32x32x16_bf16 v[20:35], v[216:219], v[184:187], v[20:35]
	v_mfma_f32_32x32x16_bf16 v[84:99], v[216:219], v[208:211], v[84:99]
	v_mfma_f32_32x32x16_bf16 v[36:51], v[220:223], v[184:187], v[36:51]
	v_mfma_f32_32x32x16_bf16 v[100:115], v[220:223], v[208:211], v[100:115]
	v_mfma_f32_32x32x16_bf16 v[52:67], v[224:227], v[184:187], v[52:67]
	v_mfma_f32_32x32x16_bf16 v[116:131], v[224:227], v[208:211], v[116:131]
	ds_read_b128 v[184:187], v231 offset:32768
	ds_read_b128 v[208:211], v231 offset:36864
	ds_read_b128 v[212:215], v235 offset:32768
	ds_read_b128 v[216:219], v235 offset:36864
	ds_read_b128 v[220:223], v235 offset:49152
	ds_read_b128 v[224:227], v235 offset:53248
	s_waitcnt lgkmcnt(6)
	v_mfma_f32_32x32x16_bf16 v[4:19], v[140:143], v[132:135], v[4:19]
	v_mfma_f32_32x32x16_bf16 v[68:83], v[140:143], v[136:139], v[68:83]
	v_mfma_f32_32x32x16_bf16 v[20:35], v[144:147], v[132:135], v[20:35]
	v_mfma_f32_32x32x16_bf16 v[84:99], v[144:147], v[136:139], v[84:99]
	v_mfma_f32_32x32x16_bf16 v[36:51], v[148:151], v[132:135], v[36:51]
	v_mfma_f32_32x32x16_bf16 v[100:115], v[148:151], v[136:139], v[100:115]
	v_mfma_f32_32x32x16_bf16 v[52:67], v[180:183], v[132:135], v[52:67]
	v_mfma_f32_32x32x16_bf16 v[116:131], v[180:183], v[136:139], v[116:131]
	s_waitcnt lgkmcnt(0)
	v_mfma_f32_32x32x16_bf16 v[4:19], v[212:215], v[184:187], v[4:19]
	v_mfma_f32_32x32x16_bf16 v[68:83], v[212:215], v[208:211], v[68:83]
	v_mfma_f32_32x32x16_bf16 v[20:35], v[216:219], v[184:187], v[20:35]
	v_mfma_f32_32x32x16_bf16 v[84:99], v[216:219], v[208:211], v[84:99]
	v_mfma_f32_32x32x16_bf16 v[36:51], v[220:223], v[184:187], v[36:51]
	v_mfma_f32_32x32x16_bf16 v[100:115], v[220:223], v[208:211], v[100:115]
	v_mfma_f32_32x32x16_bf16 v[52:67], v[224:227], v[184:187], v[52:67]
	v_mfma_f32_32x32x16_bf16 v[116:131], v[224:227], v[208:211], v[116:131]
	s_waitcnt vmcnt(0) lgkmcnt(0)
	s_barrier
	ds_read_b128 v[132:135], v228 offset:0
	ds_read_b128 v[136:139], v228 offset:4096
	ds_read_b128 v[140:143], v232 offset:0
	ds_read_b128 v[144:147], v232 offset:4096
	ds_read_b128 v[148:151], v232 offset:16384
	ds_read_b128 v[180:183], v232 offset:20480
	s_mov_b32 m0, s45
	s_nop 0
	global_load_lds_dwordx4 v178, s[68:69]
	global_load_lds_dwordx4 v179, s[70:71] offset:1024
	global_load_lds_dwordx4 v178, s[72:73] offset:2048
	global_load_lds_dwordx4 v179, s[74:75] offset:3072
	ds_read_b128 v[184:187], v229 offset:0
	ds_read_b128 v[208:211], v229 offset:4096
	ds_read_b128 v[212:215], v233 offset:0
	ds_read_b128 v[216:219], v233 offset:4096
	ds_read_b128 v[220:223], v233 offset:16384
	ds_read_b128 v[224:227], v233 offset:20480
	s_waitcnt lgkmcnt(6)
	v_mfma_f32_32x32x16_bf16 v[4:19], v[140:143], v[132:135], v[4:19]
	v_mfma_f32_32x32x16_bf16 v[68:83], v[140:143], v[136:139], v[68:83]
	v_mfma_f32_32x32x16_bf16 v[20:35], v[144:147], v[132:135], v[20:35]
	v_mfma_f32_32x32x16_bf16 v[84:99], v[144:147], v[136:139], v[84:99]
	v_mfma_f32_32x32x16_bf16 v[36:51], v[148:151], v[132:135], v[36:51]
	v_mfma_f32_32x32x16_bf16 v[100:115], v[148:151], v[136:139], v[100:115]
	v_mfma_f32_32x32x16_bf16 v[52:67], v[180:183], v[132:135], v[52:67]
	v_mfma_f32_32x32x16_bf16 v[116:131], v[180:183], v[136:139], v[116:131]
	s_mov_b32 m0, s47
	s_nop 0
	global_load_lds_dwordx4 v178, s[76:77]
	global_load_lds_dwordx4 v179, s[78:79] offset:1024
	global_load_lds_dwordx4 v178, s[80:81] offset:2048
	global_load_lds_dwordx4 v179, s[82:83] offset:3072
	v_add_u32_e32 v178, 0x80, v178
	v_add_u32_e32 v179, 0x80, v179
	ds_read_b128 v[132:135], v230 offset:0
	ds_read_b128 v[136:139], v230 offset:4096
	ds_read_b128 v[140:143], v234 offset:0
	ds_read_b128 v[144:147], v234 offset:4096
	ds_read_b128 v[148:151], v234 offset:16384
	ds_read_b128 v[180:183], v234 offset:20480
	s_waitcnt lgkmcnt(6)
; #define MFMA32(a, b, c) __builtin_amdgcn_mfma_f32_32x32x16_bf16((a), (b), (c), 0, 0, 0)
; template <bool SWAP, class Epi>
; DI void gemm_tile(const u16* __restrict__ A, int lda, const u16* __restrict__ Bw, int ldb, int K, char* lds, Epi epi) {
;     ...
;     for (int ks = 0; ks < 4; ++ks) {
;       bf16x8 af[2], bfr[2];
; #pragma unroll
;       for (int mi = 0; mi < 2; ++mi) af[mi] = *(const bf16x8*)(as + ((wm * 64 + mi * 32 + r) * 72 + ks * 16 + 8 * h) * 2);
; #pragma unroll
;       for (int ni = 0; ni < 2; ++ni) bfr[ni] = *(const bf16x8*)(bs + ((wn * 64 + ni * 32 + r) * 72 + ks * 16 + 8 * h) * 2);
; #pragma unroll
;       for (int mi = 0; mi < 2; ++mi)
; #pragma unroll
;         for (int ni = 0; ni < 2; ++ni) {
;           if (SWAP) acc[mi][ni] = MFMA32(bfr[ni], af[mi], acc[mi][ni]);
;           else acc[mi][ni] = MFMA32(af[mi], bfr[ni], acc[mi][ni]);
;         }
;     }
;   };
;   gload(0, ra0, rb0);
;   lstore(0, ra0, rb0);
;   gload(1, ra1, rb1);
;   __syncthreads();
;   for (int kt = 0; kt < nk; kt += 2) {
;     if (kt + 2 < nk) gload(kt + 2, ra0, rb0);
;     compute(0);
;     lstore(1, ra1, rb1);
;     __syncthreads();
;     if (kt + 3 < nk) gload(kt + 3, ra1, rb1);
;     compute(1);
;     if (kt + 2 < nk) lstore(0, ra0, rb0);
;     __syncthreads();
	v_mfma_f32_32x32x16_bf16 v[4:19], v[212:215], v[184:187], v[4:19]
	v_mfma_f32_32x32x16_bf16 v[68:83], v[212:215], v[208:211], v[68:83]
	v_mfma_f32_32x32x16_bf16 v[20:35], v[216:219], v[184:187], v[20:35]
	v_mfma_f32_32x32x16_bf16 v[84:99], v[216:219], v[208:211], v[84:99]
	v_mfma_f32_32x32x16_bf16 v[36:51], v[220:223], v[184:187], v[36:51]
	v_mfma_f32_32x32x16_bf16 v[100:115], v[220:223], v[208:211], v[100:115]
	v_mfma_f32_32x32x16_bf16 v[52:67], v[224:227], v[184:187], v[52:67]
	v_mfma_f32_32x32x16_bf16 v[116:131], v[224:227], v[208:211], v[116:131]
	ds_read_b128 v[184:187], v231 offset:0
	ds_read_b128 v[208:211], v231 offset:4096
	ds_read_b128 v[212:215], v235 offset:0
	ds_read_b128 v[216:219], v235 offset:4096
	ds_read_b128 v[220:223], v235 offset:16384
	ds_read_b128 v[224:227], v235 offset:20480
	s_waitcnt lgkmcnt(6)
	v_mfma_f32_32x32x16_bf16 v[4:19], v[140:143], v[132:135], v[4:19]
	v_mfma_f32_32x32x16_bf16 v[68:83], v[140:143], v[136:139], v[68:83]
	v_mfma_f32_32x32x16_bf16 v[20:35], v[144:147], v[132:135], v[20:35]
	v_mfma_f32_32x32x16_bf16 v[84:99], v[144:147], v[136:139], v[84:99]
	v_mfma_f32_32x32x16_bf16 v[36:51], v[148:151], v[132:135], v[36:51]
	v_mfma_f32_32x32x16_bf16 v[100:115], v[148:151], v[136:139], v[100:115]
	v_mfma_f32_32x32x16_bf16 v[52:67], v[180:183], v[132:135], v[52:67]
	v_mfma_f32_32x32x16_bf16 v[116:131], v[180:183], v[136:139], v[116:131]
	s_waitcnt lgkmcnt(0)
	v_mfma_f32_32x32x16_bf16 v[4:19], v[212:215], v[184:187], v[4:19]
	v_mfma_f32_32x32x16_bf16 v[68:83], v[212:215], v[208:211], v[68:83]
	v_mfma_f32_32x32x16_bf16 v[20:35], v[216:219], v[184:187], v[20:35]
	v_mfma_f32_32x32x16_bf16 v[84:99], v[216:219], v[208:211], v[84:99]
	v_mfma_f32_32x32x16_bf16 v[36:51], v[220:223], v[184:187], v[36:51]
	v_mfma_f32_32x32x16_bf16 v[100:115], v[220:223], v[208:211], v[100:115]
	v_mfma_f32_32x32x16_bf16 v[52:67], v[224:227], v[184:187], v[52:67]
	v_mfma_f32_32x32x16_bf16 v[116:131], v[224:227], v[208:211], v[116:131]
	s_waitcnt vmcnt(0) lgkmcnt(0)
	s_barrier
	ds_read_b128 v[132:135], v228 offset:32768
	ds_read_b128 v[136:139], v228 offset:36864
	ds_read_b128 v[140:143], v232 offset:32768
	ds_read_b128 v[144:147], v232 offset:36864
	ds_read_b128 v[148:151], v232 offset:49152
	ds_read_b128 v[180:183], v232 offset:53248
	s_mov_b32 m0, s44
	s_nop 0
	global_load_lds_dwordx4 v178, s[68:69]
	global_load_lds_dwordx4 v179, s[70:71] offset:1024
	global_load_lds_dwordx4 v178, s[72:73] offset:2048
	global_load_lds_dwordx4 v179, s[74:75] offset:3072
	ds_read_b128 v[184:187], v229 offset:32768
	ds_read_b128 v[208:211], v229 offset:36864
	ds_read_b128 v[212:215], v233 offset:32768
	ds_read_b128 v[216:219], v233 offset:36864
	ds_read_b128 v[220:223], v233 offset:49152
	ds_read_b128 v[224:227], v233 offset:53248
	s_waitcnt lgkmcnt(6)
	v_mfma_f32_32x32x16_bf16 v[4:19], v[140:143], v[132:135], v[4:19]
	v_mfma_f32_32x32x16_bf16 v[68:83], v[140:143], v[136:139], v[68:83]
	v_mfma_f32_32x32x16_bf16 v[20:35], v[144:147], v[132:135], v[20:35]
	v_mfma_f32_32x32x16_bf16 v[84:99], v[144:147], v[136:139], v[84:99]
	v_mfma_f32_32x32x16_bf16 v[36:51], v[148:151], v[132:135], v[36:51]
	v_mfma_f32_32x32x16_bf16 v[100:115], v[148:151], v[136:139], v[100:115]
	v_mfma_f32_32x32x16_bf16 v[52:67], v[180:183], v[132:135], v[52:67]
	v_mfma_f32_32x32x16_bf16 v[116:131], v[180:183], v[136:139], v[116:131]
	s_mov_b32 m0, s46
	s_nop 0
	global_load_lds_dwordx4 v178, s[76:77]
	global_load_lds_dwordx4 v179, s[78:79] offset:1024
	global_load_lds_dwordx4 v178, s[80:81] offset:2048
	global_load_lds_dwordx4 v179, s[82:83] offset:3072
	v_add_u32_e32 v178, 0x80, v178
	v_add_u32_e32 v179, 0x80, v179
	ds_read_b128 v[132:135], v230 offset:32768
	ds_read_b128 v[136:139], v230 offset:36864
	ds_read_b128 v[140:143], v234 offset:32768
	ds_read_b128 v[144:147], v234 offset:36864
	ds_read_b128 v[148:151], v234 offset:49152
	ds_read_b128 v[180:183], v234 offset:53248
	s_waitcnt lgkmcnt(6)
	v_mfma_f32_32x32x16_bf16 v[4:19], v[212:215], v[184:187], v[4:19]
	v_mfma_f32_32x32x16_bf16 v[68:83], v[212:215], v[208:211], v[68:83]
	v_mfma_f32_32x32x16_bf16 v[20:35], v[216:219], v[184:187], v[20:35]
	v_mfma_f32_32x32x16_bf16 v[84:99], v[216:219], v[208:211], v[84:99]
	v_mfma_f32_32x32x16_bf16 v[36:51], v[220:223], v[184:187], v[36:51]
	v_mfma_f32_32x32x16_bf16 v[100:115], v[220:223], v[208:211], v[100:115]
	v_mfma_f32_32x32x16_bf16 v[52:67], v[224:227], v[184:187], v[52:67]
	v_mfma_f32_32x32x16_bf16 v[116:131], v[224:227], v[208:211], v[116:131]
	ds_read_b128 v[184:187], v231 offset:32768
	ds_read_b128 v[208:211], v231 offset:36864
	ds_read_b128 v[212:215], v235 offset:32768
	ds_read_b128 v[216:219], v235 offset:36864
	ds_read_b128 v[220:223], v235 offset:49152
	ds_read_b128 v[224:227], v235 offset:53248
	s_waitcnt lgkmcnt(6)
	v_mfma_f32_32x32x16_bf16 v[4:19], v[140:143], v[132:135], v[4:19]
	v_mfma_f32_32x32x16_bf16 v[68:83], v[140:143], v[136:139], v[68:83]
	v_mfma_f32_32x32x16_bf16 v[20:35], v[144:147], v[132:135], v[20:35]
	v_mfma_f32_32x32x16_bf16 v[84:99], v[144:147], v[136:139], v[84:99]
	v_mfma_f32_32x32x16_bf16 v[36:51], v[148:151], v[132:135], v[36:51]
	v_mfma_f32_32x32x16_bf16 v[100:115], v[148:151], v[136:139], v[100:115]
	v_mfma_f32_32x32x16_bf16 v[52:67], v[180:183], v[132:135], v[52:67]
	v_mfma_f32_32x32x16_bf16 v[116:131], v[180:183], v[136:139], v[116:131]
	s_waitcnt lgkmcnt(0)
	v_mfma_f32_32x32x16_bf16 v[4:19], v[212:215], v[184:187], v[4:19]
	v_mfma_f32_32x32x16_bf16 v[68:83], v[212:215], v[208:211], v[68:83]
	v_mfma_f32_32x32x16_bf16 v[20:35], v[216:219], v[184:187], v[20:35]
	v_mfma_f32_32x32x16_bf16 v[84:99], v[216:219], v[208:211], v[84:99]
	v_mfma_f32_32x32x16_bf16 v[36:51], v[220:223], v[184:187], v[36:51]
	v_mfma_f32_32x32x16_bf16 v[100:115], v[220:223], v[208:211], v[100:115]
	v_mfma_f32_32x32x16_bf16 v[52:67], v[224:227], v[184:187], v[52:67]
	v_mfma_f32_32x32x16_bf16 v[116:131], v[224:227], v[208:211], v[116:131]
	s_waitcnt vmcnt(0) lgkmcnt(0)
	s_barrier
; #define MFMA32(a, b, c) __builtin_amdgcn_mfma_f32_32x32x16_bf16((a), (b), (c), 0, 0, 0)
; template <bool SWAP, class Epi>
; DI void gemm_tile(const u16* __restrict__ A, int lda, const u16* __restrict__ Bw, int ldb, int K, char* lds, Epi epi) {
;     ...
;     for (int ks = 0; ks < 4; ++ks) {
;       bf16x8 af[2], bfr[2];
; #pragma unroll
;       for (int mi = 0; mi < 2; ++mi) af[mi] = *(const bf16x8*)(as + ((wm * 64 + mi * 32 + r) * 72 + ks * 16 + 8 * h) * 2);
; #pragma unroll
;       for (int ni = 0; ni < 2; ++ni) bfr[ni] = *(const bf16x8*)(bs + ((wn * 64 + ni * 32 + r) * 72 + ks * 16 + 8 * h) * 2);
; #pragma unroll
;       for (int mi = 0; mi < 2; ++mi)
; #pragma unroll
;         for (int ni = 0; ni < 2; ++ni) {
;           if (SWAP) acc[mi][ni] = MFMA32(bfr[ni], af[mi], acc[mi][ni]);
;           else acc[mi][ni] = MFMA32(af[mi], bfr[ni], acc[mi][ni]);
;         }
;     }
;   };
;   gload(0, ra0, rb0);
;   lstore(0, ra0, rb0);
;   gload(1, ra1, rb1);
;   __syncthreads();
;   for (int kt = 0; kt < nk; kt += 2) {
;     if (kt + 2 < nk) gload(kt + 2, ra0, rb0);
;     compute(0);
;     lstore(1, ra1, rb1);
;     __syncthreads();
;     if (kt + 3 < nk) gload(kt + 3, ra1, rb1);
;     compute(1);
;     if (kt + 2 < nk) lstore(0, ra0, rb0);
;     __syncthreads();
	ds_read_b128 v[132:135], v228 offset:0
	ds_read_b128 v[136:139], v228 offset:4096
	ds_read_b128 v[140:143], v232 offset:0
	ds_read_b128 v[144:147], v232 offset:4096
	ds_read_b128 v[148:151], v232 offset:16384
	ds_read_b128 v[180:183], v232 offset:20480
	s_mov_b32 m0, s45
	s_nop 0
	global_load_lds_dwordx4 v178, s[68:69]
	global_load_lds_dwordx4 v179, s[70:71] offset:1024
	global_load_lds_dwordx4 v178, s[72:73] offset:2048
	global_load_lds_dwordx4 v179, s[74:75] offset:3072
	ds_read_b128 v[184:187], v229 offset:0
	ds_read_b128 v[208:211], v229 offset:4096
	ds_read_b128 v[212:215], v233 offset:0
	ds_read_b128 v[216:219], v233 offset:4096
	ds_read_b128 v[220:223], v233 offset:16384
	ds_read_b128 v[224:227], v233 offset:20480
	s_waitcnt lgkmcnt(6)
	v_mfma_f32_32x32x16_bf16 v[4:19], v[140:143], v[132:135], v[4:19]
	v_mfma_f32_32x32x16_bf16 v[68:83], v[140:143], v[136:139], v[68:83]
	v_mfma_f32_32x32x16_bf16 v[20:35], v[144:147], v[132:135], v[20:35]
	v_mfma_f32_32x32x16_bf16 v[84:99], v[144:147], v[136:139], v[84:99]
	v_mfma_f32_32x32x16_bf16 v[36:51], v[148:151], v[132:135], v[36:51]
	v_mfma_f32_32x32x16_bf16 v[100:115], v[148:151], v[136:139], v[100:115]
	v_mfma_f32_32x32x16_bf16 v[52:67], v[180:183], v[132:135], v[52:67]
	v_mfma_f32_32x32x16_bf16 v[116:131], v[180:183], v[136:139], v[116:131]
	s_mov_b32 m0, s47
	s_nop 0
	global_load_lds_dwordx4 v178, s[76:77]
	global_load_lds_dwordx4 v179, s[78:79] offset:1024
	global_load_lds_dwordx4 v178, s[80:81] offset:2048
	global_load_lds_dwordx4 v179, s[82:83] offset:3072
	v_add_u32_e32 v178, 0x80, v178
	v_add_u32_e32 v179, 0x80, v179
	ds_read_b128 v[132:135], v230 offset:0
	ds_read_b128 v[136:139], v230 offset:4096
	ds_read_b128 v[140:143], v234 offset:0
	ds_read_b128 v[144:147], v234 offset:4096
	ds_read_b128 v[148:151], v234 offset:16384
	ds_read_b128 v[180:183], v234 offset:20480
	s_waitcnt lgkmcnt(6)
	v_mfma_f32_32x32x16_bf16 v[4:19], v[212:215], v[184:187], v[4:19]
	v_mfma_f32_32x32x16_bf16 v[68:83], v[212:215], v[208:211], v[68:83]
	v_mfma_f32_32x32x16_bf16 v[20:35], v[216:219], v[184:187], v[20:35]
	v_mfma_f32_32x32x16_bf16 v[84:99], v[216:219], v[208:211], v[84:99]
	v_mfma_f32_32x32x16_bf16 v[36:51], v[220:223], v[184:187], v[36:51]
	v_mfma_f32_32x32x16_bf16 v[100:115], v[220:223], v[208:211], v[100:115]
	v_mfma_f32_32x32x16_bf16 v[52:67], v[224:227], v[184:187], v[52:67]
	v_mfma_f32_32x32x16_bf16 v[116:131], v[224:227], v[208:211], v[116:131]
	ds_read_b128 v[184:187], v231 offset:0
	ds_read_b128 v[208:211], v231 offset:4096
	ds_read_b128 v[212:215], v235 offset:0
	ds_read_b128 v[216:219], v235 offset:4096
	ds_read_b128 v[220:223], v235 offset:16384
	ds_read_b128 v[224:227], v235 offset:20480
	s_waitcnt lgkmcnt(6)
	v_mfma_f32_32x32x16_bf16 v[4:19], v[140:143], v[132:135], v[4:19]
	v_mfma_f32_32x32x16_bf16 v[68:83], v[140:143], v[136:139], v[68:83]
	v_mfma_f32_32x32x16_bf16 v[20:35], v[144:147], v[132:135], v[20:35]
	v_mfma_f32_32x32x16_bf16 v[84:99], v[144:147], v[136:139], v[84:99]
	v_mfma_f32_32x32x16_bf16 v[36:51], v[148:151], v[132:135], v[36:51]
	v_mfma_f32_32x32x16_bf16 v[100:115], v[148:151], v[136:139], v[100:115]
	v_mfma_f32_32x32x16_bf16 v[52:67], v[180:183], v[132:135], v[52:67]
	v_mfma_f32_32x32x16_bf16 v[116:131], v[180:183], v[136:139], v[116:131]
	s_waitcnt lgkmcnt(0)
	v_mfma_f32_32x32x16_bf16 v[4:19], v[212:215], v[184:187], v[4:19]
	v_mfma_f32_32x32x16_bf16 v[68:83], v[212:215], v[208:211], v[68:83]
	v_mfma_f32_32x32x16_bf16 v[20:35], v[216:219], v[184:187], v[20:35]
	v_mfma_f32_32x32x16_bf16 v[84:99], v[216:219], v[208:211], v[84:99]
	v_mfma_f32_32x32x16_bf16 v[36:51], v[220:223], v[184:187], v[36:51]
	v_mfma_f32_32x32x16_bf16 v[100:115], v[220:223], v[208:211], v[100:115]
	v_mfma_f32_32x32x16_bf16 v[52:67], v[224:227], v[184:187], v[52:67]
	v_mfma_f32_32x32x16_bf16 v[116:131], v[224:227], v[208:211], v[116:131]
	s_waitcnt vmcnt(0) lgkmcnt(0)
	s_barrier
	ds_read_b128 v[132:135], v228 offset:32768
	ds_read_b128 v[136:139], v228 offset:36864
	ds_read_b128 v[140:143], v232 offset:32768
	ds_read_b128 v[144:147], v232 offset:36864
	ds_read_b128 v[148:151], v232 offset:49152
	ds_read_b128 v[180:183], v232 offset:53248
	s_mov_b32 m0, s44
	s_nop 0
	global_load_lds_dwordx4 v178, s[68:69]
	global_load_lds_dwordx4 v179, s[70:71] offset:1024
	global_load_lds_dwordx4 v178, s[72:73] offset:2048
	global_load_lds_dwordx4 v179, s[74:75] offset:3072
	ds_read_b128 v[184:187], v229 offset:32768
	ds_read_b128 v[208:211], v229 offset:36864
	ds_read_b128 v[212:215], v233 offset:32768
	ds_read_b128 v[216:219], v233 offset:36864
	ds_read_b128 v[220:223], v233 offset:49152
	ds_read_b128 v[224:227], v233 offset:53248
	s_waitcnt lgkmcnt(6)
	v_mfma_f32_32x32x16_bf16 v[4:19], v[140:143], v[132:135], v[4:19]
	v_mfma_f32_32x32x16_bf16 v[68:83], v[140:143], v[136:139], v[68:83]
	v_mfma_f32_32x32x16_bf16 v[20:35], v[144:147], v[132:135], v[20:35]
	v_mfma_f32_32x32x16_bf16 v[84:99], v[144:147], v[136:139], v[84:99]
	v_mfma_f32_32x32x16_bf16 v[36:51], v[148:151], v[132:135], v[36:51]
	v_mfma_f32_32x32x16_bf16 v[100:115], v[148:151], v[136:139], v[100:115]
	v_mfma_f32_32x32x16_bf16 v[52:67], v[180:183], v[132:135], v[52:67]
	v_mfma_f32_32x32x16_bf16 v[116:131], v[180:183], v[136:139], v[116:131]
	s_mov_b32 m0, s46
	s_nop 0
	global_load_lds_dwordx4 v178, s[76:77]
	global_load_lds_dwordx4 v179, s[78:79] offset:1024
	global_load_lds_dwordx4 v178, s[80:81] offset:2048
	global_load_lds_dwordx4 v179, s[82:83] offset:3072
	v_add_u32_e32 v178, 0x80, v178
	v_add_u32_e32 v179, 0x80, v179
	ds_read_b128 v[132:135], v230 offset:32768
	ds_read_b128 v[136:139], v230 offset:36864
	ds_read_b128 v[140:143], v234 offset:32768
	ds_read_b128 v[144:147], v234 offset:36864
	ds_read_b128 v[148:151], v234 offset:49152
	ds_read_b128 v[180:183], v234 offset:53248
	s_waitcnt lgkmcnt(6)
; #define MFMA32(a, b, c) __builtin_amdgcn_mfma_f32_32x32x16_bf16((a), (b), (c), 0, 0, 0)
; template <bool SWAP, class Epi>
; DI void gemm_tile(const u16* __restrict__ A, int lda, const u16* __restrict__ Bw, int ldb, int K, char* lds, Epi epi) {
;     ...
;     for (int ks = 0; ks < 4; ++ks) {
;       bf16x8 af[2], bfr[2];
; #pragma unroll
;       for (int mi = 0; mi < 2; ++mi) af[mi] = *(const bf16x8*)(as + ((wm * 64 + mi * 32 + r) * 72 + ks * 16 + 8 * h) * 2);
; #pragma unroll
;       for (int ni = 0; ni < 2; ++ni) bfr[ni] = *(const bf16x8*)(bs + ((wn * 64 + ni * 32 + r) * 72 + ks * 16 + 8 * h) * 2);
; #pragma unroll
;       for (int mi = 0; mi < 2; ++mi)
; #pragma unroll
;         for (int ni = 0; ni < 2; ++ni) {
;           if (SWAP) acc[mi][ni] = MFMA32(bfr[ni], af[mi], acc[mi][ni]);
;           else acc[mi][ni] = MFMA32(af[mi], bfr[ni], acc[mi][ni]);
;         }
;     }
;   };
;   gload(0, ra0, rb0);
;   lstore(0, ra0, rb0);
;   gload(1, ra1, rb1);
;   __syncthreads();
;   for (int kt = 0; kt < nk; kt += 2) {
;     if (kt + 2 < nk) gload(kt + 2, ra0, rb0);
;     compute(0);
;     lstore(1, ra1, rb1);
;     __syncthreads();
;     if (kt + 3 < nk) gload(kt + 3, ra1, rb1);
;     compute(1);
;     if (kt + 2 < nk) lstore(0, ra0, rb0);
;     __syncthreads();
	v_mfma_f32_32x32x16_bf16 v[4:19], v[212:215], v[184:187], v[4:19]
	v_mfma_f32_32x32x16_bf16 v[68:83], v[212:215], v[208:211], v[68:83]
	v_mfma_f32_32x32x16_bf16 v[20:35], v[216:219], v[184:187], v[20:35]
	v_mfma_f32_32x32x16_bf16 v[84:99], v[216:219], v[208:211], v[84:99]
	v_mfma_f32_32x32x16_bf16 v[36:51], v[220:223], v[184:187], v[36:51]
	v_mfma_f32_32x32x16_bf16 v[100:115], v[220:223], v[208:211], v[100:115]
	v_mfma_f32_32x32x16_bf16 v[52:67], v[224:227], v[184:187], v[52:67]
	v_mfma_f32_32x32x16_bf16 v[116:131], v[224:227], v[208:211], v[116:131]
	ds_read_b128 v[184:187], v231 offset:32768
	ds_read_b128 v[208:211], v231 offset:36864
	ds_read_b128 v[212:215], v235 offset:32768
	ds_read_b128 v[216:219], v235 offset:36864
	ds_read_b128 v[220:223], v235 offset:49152
	ds_read_b128 v[224:227], v235 offset:53248
	s_waitcnt lgkmcnt(6)
	v_mfma_f32_32x32x16_bf16 v[4:19], v[140:143], v[132:135], v[4:19]
	v_mfma_f32_32x32x16_bf16 v[68:83], v[140:143], v[136:139], v[68:83]
	v_mfma_f32_32x32x16_bf16 v[20:35], v[144:147], v[132:135], v[20:35]
	v_mfma_f32_32x32x16_bf16 v[84:99], v[144:147], v[136:139], v[84:99]
	v_mfma_f32_32x32x16_bf16 v[36:51], v[148:151], v[132:135], v[36:51]
	v_mfma_f32_32x32x16_bf16 v[100:115], v[148:151], v[136:139], v[100:115]
	v_mfma_f32_32x32x16_bf16 v[52:67], v[180:183], v[132:135], v[52:67]
	v_mfma_f32_32x32x16_bf16 v[116:131], v[180:183], v[136:139], v[116:131]
	s_waitcnt lgkmcnt(0)
	v_mfma_f32_32x32x16_bf16 v[4:19], v[212:215], v[184:187], v[4:19]
	v_mfma_f32_32x32x16_bf16 v[68:83], v[212:215], v[208:211], v[68:83]
	v_mfma_f32_32x32x16_bf16 v[20:35], v[216:219], v[184:187], v[20:35]
	v_mfma_f32_32x32x16_bf16 v[84:99], v[216:219], v[208:211], v[84:99]
	v_mfma_f32_32x32x16_bf16 v[36:51], v[220:223], v[184:187], v[36:51]
	v_mfma_f32_32x32x16_bf16 v[100:115], v[220:223], v[208:211], v[100:115]
	v_mfma_f32_32x32x16_bf16 v[52:67], v[224:227], v[184:187], v[52:67]
	v_mfma_f32_32x32x16_bf16 v[116:131], v[224:227], v[208:211], v[116:131]
	s_waitcnt vmcnt(0) lgkmcnt(0)
	s_barrier
	ds_read_b128 v[132:135], v228 offset:0
	ds_read_b128 v[136:139], v228 offset:4096
	ds_read_b128 v[140:143], v232 offset:0
	ds_read_b128 v[144:147], v232 offset:4096
	ds_read_b128 v[148:151], v232 offset:16384
	ds_read_b128 v[180:183], v232 offset:20480
	s_mov_b32 m0, s45
	s_nop 0
	global_load_lds_dwordx4 v178, s[68:69]
	global_load_lds_dwordx4 v179, s[70:71] offset:1024
	global_load_lds_dwordx4 v178, s[72:73] offset:2048
	global_load_lds_dwordx4 v179, s[74:75] offset:3072
	ds_read_b128 v[184:187], v229 offset:0
	ds_read_b128 v[208:211], v229 offset:4096
	ds_read_b128 v[212:215], v233 offset:0
	ds_read_b128 v[216:219], v233 offset:4096
	ds_read_b128 v[220:223], v233 offset:16384
	ds_read_b128 v[224:227], v233 offset:20480
	s_waitcnt lgkmcnt(6)
	v_mfma_f32_32x32x16_bf16 v[4:19], v[140:143], v[132:135], v[4:19]
	v_mfma_f32_32x32x16_bf16 v[68:83], v[140:143], v[136:139], v[68:83]
	v_mfma_f32_32x32x16_bf16 v[20:35], v[144:147], v[132:135], v[20:35]
	v_mfma_f32_32x32x16_bf16 v[84:99], v[144:147], v[136:139], v[84:99]
	v_mfma_f32_32x32x16_bf16 v[36:51], v[148:151], v[132:135], v[36:51]
	v_mfma_f32_32x32x16_bf16 v[100:115], v[148:151], v[136:139], v[100:115]
	v_mfma_f32_32x32x16_bf16 v[52:67], v[180:183], v[132:135], v[52:67]
	v_mfma_f32_32x32x16_bf16 v[116:131], v[180:183], v[136:139], v[116:131]
	s_mov_b32 m0, s47
	s_nop 0
	global_load_lds_dwordx4 v178, s[76:77]
	global_load_lds_dwordx4 v179, s[78:79] offset:1024
	global_load_lds_dwordx4 v178, s[80:81] offset:2048
	global_load_lds_dwordx4 v179, s[82:83] offset:3072
	v_add_u32_e32 v178, 0x80, v178
	v_add_u32_e32 v179, 0x80, v179
	ds_read_b128 v[132:135], v230 offset:0
	ds_read_b128 v[136:139], v230 offset:4096
	ds_read_b128 v[140:143], v234 offset:0
	ds_read_b128 v[144:147], v234 offset:4096
	ds_read_b128 v[148:151], v234 offset:16384
	ds_read_b128 v[180:183], v234 offset:20480
	s_waitcnt lgkmcnt(6)
	v_mfma_f32_32x32x16_bf16 v[4:19], v[212:215], v[184:187], v[4:19]
	v_mfma_f32_32x32x16_bf16 v[68:83], v[212:215], v[208:211], v[68:83]
	v_mfma_f32_32x32x16_bf16 v[20:35], v[216:219], v[184:187], v[20:35]
	v_mfma_f32_32x32x16_bf16 v[84:99], v[216:219], v[208:211], v[84:99]
	v_mfma_f32_32x32x16_bf16 v[36:51], v[220:223], v[184:187], v[36:51]
	v_mfma_f32_32x32x16_bf16 v[100:115], v[220:223], v[208:211], v[100:115]
	v_mfma_f32_32x32x16_bf16 v[52:67], v[224:227], v[184:187], v[52:67]
	v_mfma_f32_32x32x16_bf16 v[116:131], v[224:227], v[208:211], v[116:131]
	ds_read_b128 v[184:187], v231 offset:0
	ds_read_b128 v[208:211], v231 offset:4096
	ds_read_b128 v[212:215], v235 offset:0
	ds_read_b128 v[216:219], v235 offset:4096
	ds_read_b128 v[220:223], v235 offset:16384
	ds_read_b128 v[224:227], v235 offset:20480
	s_waitcnt lgkmcnt(6)
	v_mfma_f32_32x32x16_bf16 v[4:19], v[140:143], v[132:135], v[4:19]
	v_mfma_f32_32x32x16_bf16 v[68:83], v[140:143], v[136:139], v[68:83]
	v_mfma_f32_32x32x16_bf16 v[20:35], v[144:147], v[132:135], v[20:35]
	v_mfma_f32_32x32x16_bf16 v[84:99], v[144:147], v[136:139], v[84:99]
	v_mfma_f32_32x32x16_bf16 v[36:51], v[148:151], v[132:135], v[36:51]
	v_mfma_f32_32x32x16_bf16 v[100:115], v[148:151], v[136:139], v[100:115]
	v_mfma_f32_32x32x16_bf16 v[52:67], v[180:183], v[132:135], v[52:67]
	v_mfma_f32_32x32x16_bf16 v[116:131], v[180:183], v[136:139], v[116:131]
	s_waitcnt lgkmcnt(0)
	v_mfma_f32_32x32x16_bf16 v[4:19], v[212:215], v[184:187], v[4:19]
	v_mfma_f32_32x32x16_bf16 v[68:83], v[212:215], v[208:211], v[68:83]
	v_mfma_f32_32x32x16_bf16 v[20:35], v[216:219], v[184:187], v[20:35]
	v_mfma_f32_32x32x16_bf16 v[84:99], v[216:219], v[208:211], v[84:99]
	v_mfma_f32_32x32x16_bf16 v[36:51], v[220:223], v[184:187], v[36:51]
	v_mfma_f32_32x32x16_bf16 v[100:115], v[220:223], v[208:211], v[100:115]
	v_mfma_f32_32x32x16_bf16 v[52:67], v[224:227], v[184:187], v[52:67]
	v_mfma_f32_32x32x16_bf16 v[116:131], v[224:227], v[208:211], v[116:131]
	s_waitcnt vmcnt(0) lgkmcnt(0)
	s_barrier
; #define MFMA32(a, b, c) __builtin_amdgcn_mfma_f32_32x32x16_bf16((a), (b), (c), 0, 0, 0)
; template <bool SWAP, class Epi>
; DI void gemm_tile(const u16* __restrict__ A, int lda, const u16* __restrict__ Bw, int ldb, int K, char* lds, Epi epi) {
;     ...
;     for (int ks = 0; ks < 4; ++ks) {
;       bf16x8 af[2], bfr[2];
; #pragma unroll
;       for (int mi = 0; mi < 2; ++mi) af[mi] = *(const bf16x8*)(as + ((wm * 64 + mi * 32 + r) * 72 + ks * 16 + 8 * h) * 2);
; #pragma unroll
;       for (int ni = 0; ni < 2; ++ni) bfr[ni] = *(const bf16x8*)(bs + ((wn * 64 + ni * 32 + r) * 72 + ks * 16 + 8 * h) * 2);
; #pragma unroll
;       for (int mi = 0; mi < 2; ++mi)
; #pragma unroll
;         for (int ni = 0; ni < 2; ++ni) {
;           if (SWAP) acc[mi][ni] = MFMA32(bfr[ni], af[mi], acc[mi][ni]);
;           else acc[mi][ni] = MFMA32(af[mi], bfr[ni], acc[mi][ni]);
;         }
;     }
;   };
;   gload(0, ra0, rb0);
;   lstore(0, ra0, rb0);
;   gload(1, ra1, rb1);
;   __syncthreads();
;   for (int kt = 0; kt < nk; kt += 2) {
;     if (kt + 2 < nk) gload(kt + 2, ra0, rb0);
;     compute(0);
;     lstore(1, ra1, rb1);
;     __syncthreads();
;     if (kt + 3 < nk) gload(kt + 3, ra1, rb1);
;     compute(1);
;     if (kt + 2 < nk) lstore(0, ra0, rb0);
;     __syncthreads();
	ds_read_b128 v[132:135], v228 offset:32768
	ds_read_b128 v[136:139], v228 offset:36864
	ds_read_b128 v[140:143], v232 offset:32768
	ds_read_b128 v[144:147], v232 offset:36864
	ds_read_b128 v[148:151], v232 offset:49152
	ds_read_b128 v[180:183], v232 offset:53248
	s_mov_b32 m0, s44
	s_nop 0
	global_load_lds_dwordx4 v178, s[68:69]
	global_load_lds_dwordx4 v179, s[70:71] offset:1024
	global_load_lds_dwordx4 v178, s[72:73] offset:2048
	global_load_lds_dwordx4 v179, s[74:75] offset:3072
	ds_read_b128 v[184:187], v229 offset:32768
	ds_read_b128 v[208:211], v229 offset:36864
	ds_read_b128 v[212:215], v233 offset:32768
	ds_read_b128 v[216:219], v233 offset:36864
	ds_read_b128 v[220:223], v233 offset:49152
	ds_read_b128 v[224:227], v233 offset:53248
	s_waitcnt lgkmcnt(6)
	v_mfma_f32_32x32x16_bf16 v[4:19], v[140:143], v[132:135], v[4:19]
	v_mfma_f32_32x32x16_bf16 v[68:83], v[140:143], v[136:139], v[68:83]
	v_mfma_f32_32x32x16_bf16 v[20:35], v[144:147], v[132:135], v[20:35]
	v_mfma_f32_32x32x16_bf16 v[84:99], v[144:147], v[136:139], v[84:99]
	v_mfma_f32_32x32x16_bf16 v[36:51], v[148:151], v[132:135], v[36:51]
	v_mfma_f32_32x32x16_bf16 v[100:115], v[148:151], v[136:139], v[100:115]
	v_mfma_f32_32x32x16_bf16 v[52:67], v[180:183], v[132:135], v[52:67]
	v_mfma_f32_32x32x16_bf16 v[116:131], v[180:183], v[136:139], v[116:131]
	s_mov_b32 m0, s46
	s_nop 0
	global_load_lds_dwordx4 v178, s[76:77]
	global_load_lds_dwordx4 v179, s[78:79] offset:1024
	global_load_lds_dwordx4 v178, s[80:81] offset:2048
	global_load_lds_dwordx4 v179, s[82:83] offset:3072
	v_add_u32_e32 v178, 0x80, v178
	v_add_u32_e32 v179, 0x80, v179
	ds_read_b128 v[132:135], v230 offset:32768
	ds_read_b128 v[136:139], v230 offset:36864
	ds_read_b128 v[140:143], v234 offset:32768
	ds_read_b128 v[144:147], v234 offset:36864
	ds_read_b128 v[148:151], v234 offset:49152
	ds_read_b128 v[180:183], v234 offset:53248
	s_waitcnt lgkmcnt(6)
	v_mfma_f32_32x32x16_bf16 v[4:19], v[212:215], v[184:187], v[4:19]
	v_mfma_f32_32x32x16_bf16 v[68:83], v[212:215], v[208:211], v[68:83]
	v_mfma_f32_32x32x16_bf16 v[20:35], v[216:219], v[184:187], v[20:35]
	v_mfma_f32_32x32x16_bf16 v[84:99], v[216:219], v[208:211], v[84:99]
	v_mfma_f32_32x32x16_bf16 v[36:51], v[220:223], v[184:187], v[36:51]
	v_mfma_f32_32x32x16_bf16 v[100:115], v[220:223], v[208:211], v[100:115]
	v_mfma_f32_32x32x16_bf16 v[52:67], v[224:227], v[184:187], v[52:67]
	v_mfma_f32_32x32x16_bf16 v[116:131], v[224:227], v[208:211], v[116:131]
	ds_read_b128 v[184:187], v231 offset:32768
	ds_read_b128 v[208:211], v231 offset:36864
	ds_read_b128 v[212:215], v235 offset:32768
	ds_read_b128 v[216:219], v235 offset:36864
	ds_read_b128 v[220:223], v235 offset:49152
	ds_read_b128 v[224:227], v235 offset:53248
	s_waitcnt lgkmcnt(6)
	v_mfma_f32_32x32x16_bf16 v[4:19], v[140:143], v[132:135], v[4:19]
	v_mfma_f32_32x32x16_bf16 v[68:83], v[140:143], v[136:139], v[68:83]
	v_mfma_f32_32x32x16_bf16 v[20:35], v[144:147], v[132:135], v[20:35]
	v_mfma_f32_32x32x16_bf16 v[84:99], v[144:147], v[136:139], v[84:99]
	v_mfma_f32_32x32x16_bf16 v[36:51], v[148:151], v[132:135], v[36:51]
	v_mfma_f32_32x32x16_bf16 v[100:115], v[148:151], v[136:139], v[100:115]
	v_mfma_f32_32x32x16_bf16 v[52:67], v[180:183], v[132:135], v[52:67]
	v_mfma_f32_32x32x16_bf16 v[116:131], v[180:183], v[136:139], v[116:131]
	s_waitcnt lgkmcnt(0)
	v_mfma_f32_32x32x16_bf16 v[4:19], v[212:215], v[184:187], v[4:19]
	v_mfma_f32_32x32x16_bf16 v[68:83], v[212:215], v[208:211], v[68:83]
	v_mfma_f32_32x32x16_bf16 v[20:35], v[216:219], v[184:187], v[20:35]
	v_mfma_f32_32x32x16_bf16 v[84:99], v[216:219], v[208:211], v[84:99]
	v_mfma_f32_32x32x16_bf16 v[36:51], v[220:223], v[184:187], v[36:51]
	v_mfma_f32_32x32x16_bf16 v[100:115], v[220:223], v[208:211], v[100:115]
	v_mfma_f32_32x32x16_bf16 v[52:67], v[224:227], v[184:187], v[52:67]
	v_mfma_f32_32x32x16_bf16 v[116:131], v[224:227], v[208:211], v[116:131]
	s_waitcnt vmcnt(0) lgkmcnt(0)
	s_barrier
	ds_read_b128 v[132:135], v228 offset:0
	ds_read_b128 v[136:139], v228 offset:4096
	ds_read_b128 v[140:143], v232 offset:0
	ds_read_b128 v[144:147], v232 offset:4096
	ds_read_b128 v[148:151], v232 offset:16384
	ds_read_b128 v[180:183], v232 offset:20480
	s_mov_b32 m0, s45
	s_nop 0
	global_load_lds_dwordx4 v178, s[68:69]
	global_load_lds_dwordx4 v179, s[70:71] offset:1024
	global_load_lds_dwordx4 v178, s[72:73] offset:2048
	global_load_lds_dwordx4 v179, s[74:75] offset:3072
	ds_read_b128 v[184:187], v229 offset:0
	ds_read_b128 v[208:211], v229 offset:4096
	ds_read_b128 v[212:215], v233 offset:0
	ds_read_b128 v[216:219], v233 offset:4096
	ds_read_b128 v[220:223], v233 offset:16384
	ds_read_b128 v[224:227], v233 offset:20480
	s_waitcnt lgkmcnt(6)
	v_mfma_f32_32x32x16_bf16 v[4:19], v[140:143], v[132:135], v[4:19]
	v_mfma_f32_32x32x16_bf16 v[68:83], v[140:143], v[136:139], v[68:83]
	v_mfma_f32_32x32x16_bf16 v[20:35], v[144:147], v[132:135], v[20:35]
	v_mfma_f32_32x32x16_bf16 v[84:99], v[144:147], v[136:139], v[84:99]
	v_mfma_f32_32x32x16_bf16 v[36:51], v[148:151], v[132:135], v[36:51]
	v_mfma_f32_32x32x16_bf16 v[100:115], v[148:151], v[136:139], v[100:115]
	v_mfma_f32_32x32x16_bf16 v[52:67], v[180:183], v[132:135], v[52:67]
	v_mfma_f32_32x32x16_bf16 v[116:131], v[180:183], v[136:139], v[116:131]
	s_mov_b32 m0, s47
	s_nop 0
	global_load_lds_dwordx4 v178, s[76:77]
	global_load_lds_dwordx4 v179, s[78:79] offset:1024
	global_load_lds_dwordx4 v178, s[80:81] offset:2048
	global_load_lds_dwordx4 v179, s[82:83] offset:3072
	v_add_u32_e32 v178, 0x80, v178
	v_add_u32_e32 v179, 0x80, v179
	ds_read_b128 v[132:135], v230 offset:0
	ds_read_b128 v[136:139], v230 offset:4096
	ds_read_b128 v[140:143], v234 offset:0
	ds_read_b128 v[144:147], v234 offset:4096
	ds_read_b128 v[148:151], v234 offset:16384
	ds_read_b128 v[180:183], v234 offset:20480
	s_waitcnt lgkmcnt(6)
; #define MFMA32(a, b, c) __builtin_amdgcn_mfma_f32_32x32x16_bf16((a), (b), (c), 0, 0, 0)
; template <bool SWAP, class Epi>
; DI void gemm_tile(const u16* __restrict__ A, int lda, const u16* __restrict__ Bw, int ldb, int K, char* lds, Epi epi) {
;     ...
;     for (int ks = 0; ks < 4; ++ks) {
;       bf16x8 af[2], bfr[2];
; #pragma unroll
;       for (int mi = 0; mi < 2; ++mi) af[mi] = *(const bf16x8*)(as + ((wm * 64 + mi * 32 + r) * 72 + ks * 16 + 8 * h) * 2);
; #pragma unroll
;       for (int ni = 0; ni < 2; ++ni) bfr[ni] = *(const bf16x8*)(bs + ((wn * 64 + ni * 32 + r) * 72 + ks * 16 + 8 * h) * 2);
; #pragma unroll
;       for (int mi = 0; mi < 2; ++mi)
; #pragma unroll
;         for (int ni = 0; ni < 2; ++ni) {
;           if (SWAP) acc[mi][ni] = MFMA32(bfr[ni], af[mi], acc[mi][ni]);
;           else acc[mi][ni] = MFMA32(af[mi], bfr[ni], acc[mi][ni]);
;         }
;     }
;   };
;   gload(0, ra0, rb0);
;   lstore(0, ra0, rb0);
;   gload(1, ra1, rb1);
;   __syncthreads();
;   for (int kt = 0; kt < nk; kt += 2) {
;     if (kt + 2 < nk) gload(kt + 2, ra0, rb0);
;     compute(0);
;     lstore(1, ra1, rb1);
;     __syncthreads();
;     if (kt + 3 < nk) gload(kt + 3, ra1, rb1);
;     compute(1);
;     if (kt + 2 < nk) lstore(0, ra0, rb0);
;     __syncthreads();
	v_mfma_f32_32x32x16_bf16 v[4:19], v[212:215], v[184:187], v[4:19]
	v_mfma_f32_32x32x16_bf16 v[68:83], v[212:215], v[208:211], v[68:83]
	v_mfma_f32_32x32x16_bf16 v[20:35], v[216:219], v[184:187], v[20:35]
	v_mfma_f32_32x32x16_bf16 v[84:99], v[216:219], v[208:211], v[84:99]
	v_mfma_f32_32x32x16_bf16 v[36:51], v[220:223], v[184:187], v[36:51]
	v_mfma_f32_32x32x16_bf16 v[100:115], v[220:223], v[208:211], v[100:115]
	v_mfma_f32_32x32x16_bf16 v[52:67], v[224:227], v[184:187], v[52:67]
	v_mfma_f32_32x32x16_bf16 v[116:131], v[224:227], v[208:211], v[116:131]
	ds_read_b128 v[184:187], v231 offset:0
	ds_read_b128 v[208:211], v231 offset:4096
	ds_read_b128 v[212:215], v235 offset:0
	ds_read_b128 v[216:219], v235 offset:4096
	ds_read_b128 v[220:223], v235 offset:16384
	ds_read_b128 v[224:227], v235 offset:20480
	s_waitcnt lgkmcnt(6)
	v_mfma_f32_32x32x16_bf16 v[4:19], v[140:143], v[132:135], v[4:19]
	v_mfma_f32_32x32x16_bf16 v[68:83], v[140:143], v[136:139], v[68:83]
	v_mfma_f32_32x32x16_bf16 v[20:35], v[144:147], v[132:135], v[20:35]
	v_mfma_f32_32x32x16_bf16 v[84:99], v[144:147], v[136:139], v[84:99]
	v_mfma_f32_32x32x16_bf16 v[36:51], v[148:151], v[132:135], v[36:51]
	v_mfma_f32_32x32x16_bf16 v[100:115], v[148:151], v[136:139], v[100:115]
	v_mfma_f32_32x32x16_bf16 v[52:67], v[180:183], v[132:135], v[52:67]
	v_mfma_f32_32x32x16_bf16 v[116:131], v[180:183], v[136:139], v[116:131]
	s_waitcnt lgkmcnt(0)
	v_mfma_f32_32x32x16_bf16 v[4:19], v[212:215], v[184:187], v[4:19]
	v_mfma_f32_32x32x16_bf16 v[68:83], v[212:215], v[208:211], v[68:83]
	v_mfma_f32_32x32x16_bf16 v[20:35], v[216:219], v[184:187], v[20:35]
	v_mfma_f32_32x32x16_bf16 v[84:99], v[216:219], v[208:211], v[84:99]
	v_mfma_f32_32x32x16_bf16 v[36:51], v[220:223], v[184:187], v[36:51]
	v_mfma_f32_32x32x16_bf16 v[100:115], v[220:223], v[208:211], v[100:115]
	v_mfma_f32_32x32x16_bf16 v[52:67], v[224:227], v[184:187], v[52:67]
	v_mfma_f32_32x32x16_bf16 v[116:131], v[224:227], v[208:211], v[116:131]
	s_waitcnt vmcnt(0) lgkmcnt(0)
	s_barrier
	ds_read_b128 v[132:135], v228 offset:32768
	ds_read_b128 v[136:139], v228 offset:36864
	ds_read_b128 v[140:143], v232 offset:32768
	ds_read_b128 v[144:147], v232 offset:36864
	ds_read_b128 v[148:151], v232 offset:49152
	ds_read_b128 v[180:183], v232 offset:53248
	s_mov_b32 m0, s44
	s_nop 0
	global_load_lds_dwordx4 v178, s[68:69]
	global_load_lds_dwordx4 v179, s[70:71] offset:1024
	global_load_lds_dwordx4 v178, s[72:73] offset:2048
	global_load_lds_dwordx4 v179, s[74:75] offset:3072
	ds_read_b128 v[184:187], v229 offset:32768
	ds_read_b128 v[208:211], v229 offset:36864
	ds_read_b128 v[212:215], v233 offset:32768
	ds_read_b128 v[216:219], v233 offset:36864
	ds_read_b128 v[220:223], v233 offset:49152
	ds_read_b128 v[224:227], v233 offset:53248
	s_waitcnt lgkmcnt(6)
	v_mfma_f32_32x32x16_bf16 v[4:19], v[140:143], v[132:135], v[4:19]
	v_mfma_f32_32x32x16_bf16 v[68:83], v[140:143], v[136:139], v[68:83]
	v_mfma_f32_32x32x16_bf16 v[20:35], v[144:147], v[132:135], v[20:35]
	v_mfma_f32_32x32x16_bf16 v[84:99], v[144:147], v[136:139], v[84:99]
	v_mfma_f32_32x32x16_bf16 v[36:51], v[148:151], v[132:135], v[36:51]
	v_mfma_f32_32x32x16_bf16 v[100:115], v[148:151], v[136:139], v[100:115]
	v_mfma_f32_32x32x16_bf16 v[52:67], v[180:183], v[132:135], v[52:67]
	v_mfma_f32_32x32x16_bf16 v[116:131], v[180:183], v[136:139], v[116:131]
	s_mov_b32 m0, s46
	s_nop 0
	global_load_lds_dwordx4 v178, s[76:77]
	global_load_lds_dwordx4 v179, s[78:79] offset:1024
	global_load_lds_dwordx4 v178, s[80:81] offset:2048
	global_load_lds_dwordx4 v179, s[82:83] offset:3072
	v_add_u32_e32 v178, 0x80, v178
	v_add_u32_e32 v179, 0x80, v179
	ds_read_b128 v[132:135], v230 offset:32768
	ds_read_b128 v[136:139], v230 offset:36864
	ds_read_b128 v[140:143], v234 offset:32768
	ds_read_b128 v[144:147], v234 offset:36864
	ds_read_b128 v[148:151], v234 offset:49152
	ds_read_b128 v[180:183], v234 offset:53248
	s_waitcnt lgkmcnt(6)
	v_mfma_f32_32x32x16_bf16 v[4:19], v[212:215], v[184:187], v[4:19]
	v_mfma_f32_32x32x16_bf16 v[68:83], v[212:215], v[208:211], v[68:83]
	v_mfma_f32_32x32x16_bf16 v[20:35], v[216:219], v[184:187], v[20:35]
	v_mfma_f32_32x32x16_bf16 v[84:99], v[216:219], v[208:211], v[84:99]
	v_mfma_f32_32x32x16_bf16 v[36:51], v[220:223], v[184:187], v[36:51]
	v_mfma_f32_32x32x16_bf16 v[100:115], v[220:223], v[208:211], v[100:115]
	v_mfma_f32_32x32x16_bf16 v[52:67], v[224:227], v[184:187], v[52:67]
	v_mfma_f32_32x32x16_bf16 v[116:131], v[224:227], v[208:211], v[116:131]
	ds_read_b128 v[184:187], v231 offset:32768
	ds_read_b128 v[208:211], v231 offset:36864
	ds_read_b128 v[212:215], v235 offset:32768
	ds_read_b128 v[216:219], v235 offset:36864
	ds_read_b128 v[220:223], v235 offset:49152
	ds_read_b128 v[224:227], v235 offset:53248
	s_waitcnt lgkmcnt(6)
	v_mfma_f32_32x32x16_bf16 v[4:19], v[140:143], v[132:135], v[4:19]
	v_mfma_f32_32x32x16_bf16 v[68:83], v[140:143], v[136:139], v[68:83]
	v_mfma_f32_32x32x16_bf16 v[20:35], v[144:147], v[132:135], v[20:35]
	v_mfma_f32_32x32x16_bf16 v[84:99], v[144:147], v[136:139], v[84:99]
	v_mfma_f32_32x32x16_bf16 v[36:51], v[148:151], v[132:135], v[36:51]
	v_mfma_f32_32x32x16_bf16 v[100:115], v[148:151], v[136:139], v[100:115]
	v_mfma_f32_32x32x16_bf16 v[52:67], v[180:183], v[132:135], v[52:67]
	v_mfma_f32_32x32x16_bf16 v[116:131], v[180:183], v[136:139], v[116:131]
	s_waitcnt lgkmcnt(0)
	v_mfma_f32_32x32x16_bf16 v[4:19], v[212:215], v[184:187], v[4:19]
	v_mfma_f32_32x32x16_bf16 v[68:83], v[212:215], v[208:211], v[68:83]
	v_mfma_f32_32x32x16_bf16 v[20:35], v[216:219], v[184:187], v[20:35]
	v_mfma_f32_32x32x16_bf16 v[84:99], v[216:219], v[208:211], v[84:99]
	v_mfma_f32_32x32x16_bf16 v[36:51], v[220:223], v[184:187], v[36:51]
	v_mfma_f32_32x32x16_bf16 v[100:115], v[220:223], v[208:211], v[100:115]
	v_mfma_f32_32x32x16_bf16 v[52:67], v[224:227], v[184:187], v[52:67]
	v_mfma_f32_32x32x16_bf16 v[116:131], v[224:227], v[208:211], v[116:131]
	s_waitcnt vmcnt(0) lgkmcnt(0)
	s_barrier
; #define MFMA32(a, b, c) __builtin_amdgcn_mfma_f32_32x32x16_bf16((a), (b), (c), 0, 0, 0)
; template <bool SWAP, class Epi>
; DI void gemm_tile(const u16* __restrict__ A, int lda, const u16* __restrict__ Bw, int ldb, int K, char* lds, Epi epi) {
;     ...
;     for (int ks = 0; ks < 4; ++ks) {
;       bf16x8 af[2], bfr[2];
; #pragma unroll
;       for (int mi = 0; mi < 2; ++mi) af[mi] = *(const bf16x8*)(as + ((wm * 64 + mi * 32 + r) * 72 + ks * 16 + 8 * h) * 2);
; #pragma unroll
;       for (int ni = 0; ni < 2; ++ni) bfr[ni] = *(const bf16x8*)(bs + ((wn * 64 + ni * 32 + r) * 72 + ks * 16 + 8 * h) * 2);
; #pragma unroll
;       for (int mi = 0; mi < 2; ++mi)
; #pragma unroll
;         for (int ni = 0; ni < 2; ++ni) {
;           if (SWAP) acc[mi][ni] = MFMA32(bfr[ni], af[mi], acc[mi][ni]);
;           else acc[mi][ni] = MFMA32(af[mi], bfr[ni], acc[mi][ni]);
;         }
;     }
;   };
;   gload(0, ra0, rb0);
;   lstore(0, ra0, rb0);
;   gload(1, ra1, rb1);
;   __syncthreads();
;   for (int kt = 0; kt < nk; kt += 2) {
;     if (kt + 2 < nk) gload(kt + 2, ra0, rb0);
;     compute(0);
;     lstore(1, ra1, rb1);
;     __syncthreads();
;     if (kt + 3 < nk) gload(kt + 3, ra1, rb1);
;     compute(1);
;     if (kt + 2 < nk) lstore(0, ra0, rb0);
;     __syncthreads();
	ds_read_b128 v[132:135], v228 offset:0
	ds_read_b128 v[136:139], v228 offset:4096
	ds_read_b128 v[140:143], v232 offset:0
	ds_read_b128 v[144:147], v232 offset:4096
	ds_read_b128 v[148:151], v232 offset:16384
	ds_read_b128 v[180:183], v232 offset:20480
	s_mov_b32 m0, s45
	s_nop 0
	global_load_lds_dwordx4 v178, s[68:69]
	global_load_lds_dwordx4 v179, s[70:71] offset:1024
	global_load_lds_dwordx4 v178, s[72:73] offset:2048
	global_load_lds_dwordx4 v179, s[74:75] offset:3072
	ds_read_b128 v[184:187], v229 offset:0
	ds_read_b128 v[208:211], v229 offset:4096
	ds_read_b128 v[212:215], v233 offset:0
	ds_read_b128 v[216:219], v233 offset:4096
	ds_read_b128 v[220:223], v233 offset:16384
	ds_read_b128 v[224:227], v233 offset:20480
	s_waitcnt lgkmcnt(6)
	v_mfma_f32_32x32x16_bf16 v[4:19], v[140:143], v[132:135], v[4:19]
	v_mfma_f32_32x32x16_bf16 v[68:83], v[140:143], v[136:139], v[68:83]
	v_mfma_f32_32x32x16_bf16 v[20:35], v[144:147], v[132:135], v[20:35]
	v_mfma_f32_32x32x16_bf16 v[84:99], v[144:147], v[136:139], v[84:99]
	v_mfma_f32_32x32x16_bf16 v[36:51], v[148:151], v[132:135], v[36:51]
	v_mfma_f32_32x32x16_bf16 v[100:115], v[148:151], v[136:139], v[100:115]
	v_mfma_f32_32x32x16_bf16 v[52:67], v[180:183], v[132:135], v[52:67]
	v_mfma_f32_32x32x16_bf16 v[116:131], v[180:183], v[136:139], v[116:131]
	s_mov_b32 m0, s47
	s_nop 0
	global_load_lds_dwordx4 v178, s[76:77]
	global_load_lds_dwordx4 v179, s[78:79] offset:1024
	global_load_lds_dwordx4 v178, s[80:81] offset:2048
	global_load_lds_dwordx4 v179, s[82:83] offset:3072
	v_add_u32_e32 v178, 0x80, v178
	v_add_u32_e32 v179, 0x80, v179
	ds_read_b128 v[132:135], v230 offset:0
	ds_read_b128 v[136:139], v230 offset:4096
	ds_read_b128 v[140:143], v234 offset:0
	ds_read_b128 v[144:147], v234 offset:4096
	ds_read_b128 v[148:151], v234 offset:16384
	ds_read_b128 v[180:183], v234 offset:20480
	s_waitcnt lgkmcnt(6)
	v_mfma_f32_32x32x16_bf16 v[4:19], v[212:215], v[184:187], v[4:19]
	v_mfma_f32_32x32x16_bf16 v[68:83], v[212:215], v[208:211], v[68:83]
	v_mfma_f32_32x32x16_bf16 v[20:35], v[216:219], v[184:187], v[20:35]
	v_mfma_f32_32x32x16_bf16 v[84:99], v[216:219], v[208:211], v[84:99]
	v_mfma_f32_32x32x16_bf16 v[36:51], v[220:223], v[184:187], v[36:51]
	v_mfma_f32_32x32x16_bf16 v[100:115], v[220:223], v[208:211], v[100:115]
	v_mfma_f32_32x32x16_bf16 v[52:67], v[224:227], v[184:187], v[52:67]
	v_mfma_f32_32x32x16_bf16 v[116:131], v[224:227], v[208:211], v[116:131]
	ds_read_b128 v[184:187], v231 offset:0
	ds_read_b128 v[208:211], v231 offset:4096
	ds_read_b128 v[212:215], v235 offset:0
	ds_read_b128 v[216:219], v235 offset:4096
	ds_read_b128 v[220:223], v235 offset:16384
	ds_read_b128 v[224:227], v235 offset:20480
	s_waitcnt lgkmcnt(6)
	v_mfma_f32_32x32x16_bf16 v[4:19], v[140:143], v[132:135], v[4:19]
	v_mfma_f32_32x32x16_bf16 v[68:83], v[140:143], v[136:139], v[68:83]
	v_mfma_f32_32x32x16_bf16 v[20:35], v[144:147], v[132:135], v[20:35]
	v_mfma_f32_32x32x16_bf16 v[84:99], v[144:147], v[136:139], v[84:99]
	v_mfma_f32_32x32x16_bf16 v[36:51], v[148:151], v[132:135], v[36:51]
	v_mfma_f32_32x32x16_bf16 v[100:115], v[148:151], v[136:139], v[100:115]
	v_mfma_f32_32x32x16_bf16 v[52:67], v[180:183], v[132:135], v[52:67]
	v_mfma_f32_32x32x16_bf16 v[116:131], v[180:183], v[136:139], v[116:131]
	s_waitcnt lgkmcnt(0)
	v_mfma_f32_32x32x16_bf16 v[4:19], v[212:215], v[184:187], v[4:19]
	v_mfma_f32_32x32x16_bf16 v[68:83], v[212:215], v[208:211], v[68:83]
	v_mfma_f32_32x32x16_bf16 v[20:35], v[216:219], v[184:187], v[20:35]
	v_mfma_f32_32x32x16_bf16 v[84:99], v[216:219], v[208:211], v[84:99]
	v_mfma_f32_32x32x16_bf16 v[36:51], v[220:223], v[184:187], v[36:51]
	v_mfma_f32_32x32x16_bf16 v[100:115], v[220:223], v[208:211], v[100:115]
	v_mfma_f32_32x32x16_bf16 v[52:67], v[224:227], v[184:187], v[52:67]
	v_mfma_f32_32x32x16_bf16 v[116:131], v[224:227], v[208:211], v[116:131]
	s_waitcnt vmcnt(0) lgkmcnt(0)
	s_barrier
	ds_read_b128 v[132:135], v228 offset:32768
	ds_read_b128 v[136:139], v228 offset:36864
	ds_read_b128 v[140:143], v232 offset:32768
	ds_read_b128 v[144:147], v232 offset:36864
	ds_read_b128 v[148:151], v232 offset:49152
	ds_read_b128 v[180:183], v232 offset:53248
	s_mov_b32 m0, s44
	s_nop 0
	global_load_lds_dwordx4 v178, s[68:69]
	global_load_lds_dwordx4 v179, s[70:71] offset:1024
	global_load_lds_dwordx4 v178, s[72:73] offset:2048
	global_load_lds_dwordx4 v179, s[74:75] offset:3072
	ds_read_b128 v[184:187], v229 offset:32768
	ds_read_b128 v[208:211], v229 offset:36864
	ds_read_b128 v[212:215], v233 offset:32768
	ds_read_b128 v[216:219], v233 offset:36864
	ds_read_b128 v[220:223], v233 offset:49152
	ds_read_b128 v[224:227], v233 offset:53248
	s_waitcnt lgkmcnt(6)
	v_mfma_f32_32x32x16_bf16 v[4:19], v[140:143], v[132:135], v[4:19]
	v_mfma_f32_32x32x16_bf16 v[68:83], v[140:143], v[136:139], v[68:83]
	v_mfma_f32_32x32x16_bf16 v[20:35], v[144:147], v[132:135], v[20:35]
	v_mfma_f32_32x32x16_bf16 v[84:99], v[144:147], v[136:139], v[84:99]
	v_mfma_f32_32x32x16_bf16 v[36:51], v[148:151], v[132:135], v[36:51]
	v_mfma_f32_32x32x16_bf16 v[100:115], v[148:151], v[136:139], v[100:115]
	v_mfma_f32_32x32x16_bf16 v[52:67], v[180:183], v[132:135], v[52:67]
	v_mfma_f32_32x32x16_bf16 v[116:131], v[180:183], v[136:139], v[116:131]
	s_mov_b32 m0, s46
	s_nop 0
	global_load_lds_dwordx4 v178, s[76:77]
	global_load_lds_dwordx4 v179, s[78:79] offset:1024
	global_load_lds_dwordx4 v178, s[80:81] offset:2048
	global_load_lds_dwordx4 v179, s[82:83] offset:3072
	v_add_u32_e32 v178, 0x80, v178
	v_add_u32_e32 v179, 0x80, v179
	ds_read_b128 v[132:135], v230 offset:32768
	ds_read_b128 v[136:139], v230 offset:36864
	ds_read_b128 v[140:143], v234 offset:32768
	ds_read_b128 v[144:147], v234 offset:36864
	ds_read_b128 v[148:151], v234 offset:49152
	ds_read_b128 v[180:183], v234 offset:53248
	s_waitcnt lgkmcnt(6)
; #define MFMA32(a, b, c) __builtin_amdgcn_mfma_f32_32x32x16_bf16((a), (b), (c), 0, 0, 0)
; template <bool SWAP, class Epi>
; DI void gemm_tile(const u16* __restrict__ A, int lda, const u16* __restrict__ Bw, int ldb, int K, char* lds, Epi epi) {
;     ...
;     for (int ks = 0; ks < 4; ++ks) {
;       bf16x8 af[2], bfr[2];
; #pragma unroll
;       for (int mi = 0; mi < 2; ++mi) af[mi] = *(const bf16x8*)(as + ((wm * 64 + mi * 32 + r) * 72 + ks * 16 + 8 * h) * 2);
; #pragma unroll
;       for (int ni = 0; ni < 2; ++ni) bfr[ni] = *(const bf16x8*)(bs + ((wn * 64 + ni * 32 + r) * 72 + ks * 16 + 8 * h) * 2);
; #pragma unroll
;       for (int mi = 0; mi < 2; ++mi)
; #pragma unroll
;         for (int ni = 0; ni < 2; ++ni) {
;           if (SWAP) acc[mi][ni] = MFMA32(bfr[ni], af[mi], acc[mi][ni]);
;           else acc[mi][ni] = MFMA32(af[mi], bfr[ni], acc[mi][ni]);
;         }
;     }
;   };
;   gload(0, ra0, rb0);
;   lstore(0, ra0, rb0);
;   gload(1, ra1, rb1);
;   __syncthreads();
;   for (int kt = 0; kt < nk; kt += 2) {
;     if (kt + 2 < nk) gload(kt + 2, ra0, rb0);
;     compute(0);
;     lstore(1, ra1, rb1);
;     __syncthreads();
;     if (kt + 3 < nk) gload(kt + 3, ra1, rb1);
;     compute(1);
;     if (kt + 2 < nk) lstore(0, ra0, rb0);
;     __syncthreads();
	v_mfma_f32_32x32x16_bf16 v[4:19], v[212:215], v[184:187], v[4:19]
	v_mfma_f32_32x32x16_bf16 v[68:83], v[212:215], v[208:211], v[68:83]
	v_mfma_f32_32x32x16_bf16 v[20:35], v[216:219], v[184:187], v[20:35]
	v_mfma_f32_32x32x16_bf16 v[84:99], v[216:219], v[208:211], v[84:99]
	v_mfma_f32_32x32x16_bf16 v[36:51], v[220:223], v[184:187], v[36:51]
	v_mfma_f32_32x32x16_bf16 v[100:115], v[220:223], v[208:211], v[100:115]
	v_mfma_f32_32x32x16_bf16 v[52:67], v[224:227], v[184:187], v[52:67]
	v_mfma_f32_32x32x16_bf16 v[116:131], v[224:227], v[208:211], v[116:131]
	ds_read_b128 v[184:187], v231 offset:32768
	ds_read_b128 v[208:211], v231 offset:36864
	ds_read_b128 v[212:215], v235 offset:32768
	ds_read_b128 v[216:219], v235 offset:36864
	ds_read_b128 v[220:223], v235 offset:49152
	ds_read_b128 v[224:227], v235 offset:53248
	s_waitcnt lgkmcnt(6)
	v_mfma_f32_32x32x16_bf16 v[4:19], v[140:143], v[132:135], v[4:19]
	v_mfma_f32_32x32x16_bf16 v[68:83], v[140:143], v[136:139], v[68:83]
	v_mfma_f32_32x32x16_bf16 v[20:35], v[144:147], v[132:135], v[20:35]
	v_mfma_f32_32x32x16_bf16 v[84:99], v[144:147], v[136:139], v[84:99]
	v_mfma_f32_32x32x16_bf16 v[36:51], v[148:151], v[132:135], v[36:51]
	v_mfma_f32_32x32x16_bf16 v[100:115], v[148:151], v[136:139], v[100:115]
	v_mfma_f32_32x32x16_bf16 v[52:67], v[180:183], v[132:135], v[52:67]
	v_mfma_f32_32x32x16_bf16 v[116:131], v[180:183], v[136:139], v[116:131]
	s_waitcnt lgkmcnt(0)
	v_mfma_f32_32x32x16_bf16 v[4:19], v[212:215], v[184:187], v[4:19]
	v_mfma_f32_32x32x16_bf16 v[68:83], v[212:215], v[208:211], v[68:83]
	v_mfma_f32_32x32x16_bf16 v[20:35], v[216:219], v[184:187], v[20:35]
	v_mfma_f32_32x32x16_bf16 v[84:99], v[216:219], v[208:211], v[84:99]
	v_mfma_f32_32x32x16_bf16 v[36:51], v[220:223], v[184:187], v[36:51]
	v_mfma_f32_32x32x16_bf16 v[100:115], v[220:223], v[208:211], v[100:115]
	v_mfma_f32_32x32x16_bf16 v[52:67], v[224:227], v[184:187], v[52:67]
	v_mfma_f32_32x32x16_bf16 v[116:131], v[224:227], v[208:211], v[116:131]
	s_waitcnt vmcnt(0) lgkmcnt(0)
	s_barrier
	ds_read_b128 v[132:135], v228 offset:0
	ds_read_b128 v[136:139], v228 offset:4096
	ds_read_b128 v[140:143], v232 offset:0
	ds_read_b128 v[144:147], v232 offset:4096
	ds_read_b128 v[148:151], v232 offset:16384
	ds_read_b128 v[180:183], v232 offset:20480
	s_mov_b32 m0, s45
	s_nop 0
	global_load_lds_dwordx4 v178, s[68:69]
	global_load_lds_dwordx4 v179, s[70:71] offset:1024
	global_load_lds_dwordx4 v178, s[72:73] offset:2048
	global_load_lds_dwordx4 v179, s[74:75] offset:3072
	ds_read_b128 v[184:187], v229 offset:0
	ds_read_b128 v[208:211], v229 offset:4096
	ds_read_b128 v[212:215], v233 offset:0
	ds_read_b128 v[216:219], v233 offset:4096
	ds_read_b128 v[220:223], v233 offset:16384
	ds_read_b128 v[224:227], v233 offset:20480
	s_waitcnt lgkmcnt(6)
	v_mfma_f32_32x32x16_bf16 v[4:19], v[140:143], v[132:135], v[4:19]
	v_mfma_f32_32x32x16_bf16 v[68:83], v[140:143], v[136:139], v[68:83]
	v_mfma_f32_32x32x16_bf16 v[20:35], v[144:147], v[132:135], v[20:35]
	v_mfma_f32_32x32x16_bf16 v[84:99], v[144:147], v[136:139], v[84:99]
	v_mfma_f32_32x32x16_bf16 v[36:51], v[148:151], v[132:135], v[36:51]
	v_mfma_f32_32x32x16_bf16 v[100:115], v[148:151], v[136:139], v[100:115]
	v_mfma_f32_32x32x16_bf16 v[52:67], v[180:183], v[132:135], v[52:67]
	v_mfma_f32_32x32x16_bf16 v[116:131], v[180:183], v[136:139], v[116:131]
	s_mov_b32 m0, s47
	s_nop 0
	global_load_lds_dwordx4 v178, s[76:77]
	global_load_lds_dwordx4 v179, s[78:79] offset:1024
	global_load_lds_dwordx4 v178, s[80:81] offset:2048
	global_load_lds_dwordx4 v179, s[82:83] offset:3072
	v_add_u32_e32 v178, 0x80, v178
	v_add_u32_e32 v179, 0x80, v179
	ds_read_b128 v[132:135], v230 offset:0
	ds_read_b128 v[136:139], v230 offset:4096
	ds_read_b128 v[140:143], v234 offset:0
	ds_read_b128 v[144:147], v234 offset:4096
	ds_read_b128 v[148:151], v234 offset:16384
	ds_read_b128 v[180:183], v234 offset:20480
	s_waitcnt lgkmcnt(6)
	v_mfma_f32_32x32x16_bf16 v[4:19], v[212:215], v[184:187], v[4:19]
	v_mfma_f32_32x32x16_bf16 v[68:83], v[212:215], v[208:211], v[68:83]
	v_mfma_f32_32x32x16_bf16 v[20:35], v[216:219], v[184:187], v[20:35]
	v_mfma_f32_32x32x16_bf16 v[84:99], v[216:219], v[208:211], v[84:99]
	v_mfma_f32_32x32x16_bf16 v[36:51], v[220:223], v[184:187], v[36:51]
	v_mfma_f32_32x32x16_bf16 v[100:115], v[220:223], v[208:211], v[100:115]
	v_mfma_f32_32x32x16_bf16 v[52:67], v[224:227], v[184:187], v[52:67]
	v_mfma_f32_32x32x16_bf16 v[116:131], v[224:227], v[208:211], v[116:131]
	ds_read_b128 v[184:187], v231 offset:0
	ds_read_b128 v[208:211], v231 offset:4096
	ds_read_b128 v[212:215], v235 offset:0
	ds_read_b128 v[216:219], v235 offset:4096
	ds_read_b128 v[220:223], v235 offset:16384
	ds_read_b128 v[224:227], v235 offset:20480
	s_waitcnt lgkmcnt(6)
	v_mfma_f32_32x32x16_bf16 v[4:19], v[140:143], v[132:135], v[4:19]
	v_mfma_f32_32x32x16_bf16 v[68:83], v[140:143], v[136:139], v[68:83]
	v_mfma_f32_32x32x16_bf16 v[20:35], v[144:147], v[132:135], v[20:35]
	v_mfma_f32_32x32x16_bf16 v[84:99], v[144:147], v[136:139], v[84:99]
	v_mfma_f32_32x32x16_bf16 v[36:51], v[148:151], v[132:135], v[36:51]
	v_mfma_f32_32x32x16_bf16 v[100:115], v[148:151], v[136:139], v[100:115]
	v_mfma_f32_32x32x16_bf16 v[52:67], v[180:183], v[132:135], v[52:67]
	v_mfma_f32_32x32x16_bf16 v[116:131], v[180:183], v[136:139], v[116:131]
	s_waitcnt lgkmcnt(0)
	v_mfma_f32_32x32x16_bf16 v[4:19], v[212:215], v[184:187], v[4:19]
	v_mfma_f32_32x32x16_bf16 v[68:83], v[212:215], v[208:211], v[68:83]
	v_mfma_f32_32x32x16_bf16 v[20:35], v[216:219], v[184:187], v[20:35]
	v_mfma_f32_32x32x16_bf16 v[84:99], v[216:219], v[208:211], v[84:99]
	v_mfma_f32_32x32x16_bf16 v[36:51], v[220:223], v[184:187], v[36:51]
	v_mfma_f32_32x32x16_bf16 v[100:115], v[220:223], v[208:211], v[100:115]
	v_mfma_f32_32x32x16_bf16 v[52:67], v[224:227], v[184:187], v[52:67]
	v_mfma_f32_32x32x16_bf16 v[116:131], v[224:227], v[208:211], v[116:131]
	s_waitcnt vmcnt(0) lgkmcnt(0)
	s_barrier
; #define MFMA32(a, b, c) __builtin_amdgcn_mfma_f32_32x32x16_bf16((a), (b), (c), 0, 0, 0)
; template <bool SWAP, class Epi>
; DI void gemm_tile(const u16* __restrict__ A, int lda, const u16* __restrict__ Bw, int ldb, int K, char* lds, Epi epi) {
;     ...
;     for (int ks = 0; ks < 4; ++ks) {
;       bf16x8 af[2], bfr[2];
; #pragma unroll
;       for (int mi = 0; mi < 2; ++mi) af[mi] = *(const bf16x8*)(as + ((wm * 64 + mi * 32 + r) * 72 + ks * 16 + 8 * h) * 2);
; #pragma unroll
;       for (int ni = 0; ni < 2; ++ni) bfr[ni] = *(const bf16x8*)(bs + ((wn * 64 + ni * 32 + r) * 72 + ks * 16 + 8 * h) * 2);
; #pragma unroll
;       for (int mi = 0; mi < 2; ++mi)
; #pragma unroll
;         for (int ni = 0; ni < 2; ++ni) {
;           if (SWAP) acc[mi][ni] = MFMA32(bfr[ni], af[mi], acc[mi][ni]);
;           else acc[mi][ni] = MFMA32(af[mi], bfr[ni], acc[mi][ni]);
;         }
;     }
;   };
;   gload(0, ra0, rb0);
;   lstore(0, ra0, rb0);
;   gload(1, ra1, rb1);
;   __syncthreads();
;   for (int kt = 0; kt < nk; kt += 2) {
;     if (kt + 2 < nk) gload(kt + 2, ra0, rb0);
;     compute(0);
;     lstore(1, ra1, rb1);
;     __syncthreads();
;     if (kt + 3 < nk) gload(kt + 3, ra1, rb1);
;     compute(1);
;     if (kt + 2 < nk) lstore(0, ra0, rb0);
;     __syncthreads();
	ds_read_b128 v[132:135], v228 offset:32768
	ds_read_b128 v[136:139], v228 offset:36864
	ds_read_b128 v[140:143], v232 offset:32768
	ds_read_b128 v[144:147], v232 offset:36864
	ds_read_b128 v[148:151], v232 offset:49152
	ds_read_b128 v[180:183], v232 offset:53248
	s_mov_b32 m0, s44
	s_nop 0
	global_load_lds_dwordx4 v178, s[68:69]
	global_load_lds_dwordx4 v179, s[70:71] offset:1024
	global_load_lds_dwordx4 v178, s[72:73] offset:2048
	global_load_lds_dwordx4 v179, s[74:75] offset:3072
	ds_read_b128 v[184:187], v229 offset:32768
	ds_read_b128 v[208:211], v229 offset:36864
	ds_read_b128 v[212:215], v233 offset:32768
	ds_read_b128 v[216:219], v233 offset:36864
	ds_read_b128 v[220:223], v233 offset:49152
	ds_read_b128 v[224:227], v233 offset:53248
	s_waitcnt lgkmcnt(6)
	v_mfma_f32_32x32x16_bf16 v[4:19], v[140:143], v[132:135], v[4:19]
	v_mfma_f32_32x32x16_bf16 v[68:83], v[140:143], v[136:139], v[68:83]
	v_mfma_f32_32x32x16_bf16 v[20:35], v[144:147], v[132:135], v[20:35]
	v_mfma_f32_32x32x16_bf16 v[84:99], v[144:147], v[136:139], v[84:99]
	v_mfma_f32_32x32x16_bf16 v[36:51], v[148:151], v[132:135], v[36:51]
	v_mfma_f32_32x32x16_bf16 v[100:115], v[148:151], v[136:139], v[100:115]
	v_mfma_f32_32x32x16_bf16 v[52:67], v[180:183], v[132:135], v[52:67]
	v_mfma_f32_32x32x16_bf16 v[116:131], v[180:183], v[136:139], v[116:131]
	s_mov_b32 m0, s46
	s_nop 0
	global_load_lds_dwordx4 v178, s[76:77]
	global_load_lds_dwordx4 v179, s[78:79] offset:1024
	global_load_lds_dwordx4 v178, s[80:81] offset:2048
	global_load_lds_dwordx4 v179, s[82:83] offset:3072
	v_add_u32_e32 v178, 0x80, v178
	v_add_u32_e32 v179, 0x80, v179
	ds_read_b128 v[132:135], v230 offset:32768
	ds_read_b128 v[136:139], v230 offset:36864
	ds_read_b128 v[140:143], v234 offset:32768
	ds_read_b128 v[144:147], v234 offset:36864
	ds_read_b128 v[148:151], v234 offset:49152
	ds_read_b128 v[180:183], v234 offset:53248
	s_waitcnt lgkmcnt(6)
	v_mfma_f32_32x32x16_bf16 v[4:19], v[212:215], v[184:187], v[4:19]
	v_mfma_f32_32x32x16_bf16 v[68:83], v[212:215], v[208:211], v[68:83]
	v_mfma_f32_32x32x16_bf16 v[20:35], v[216:219], v[184:187], v[20:35]
	v_mfma_f32_32x32x16_bf16 v[84:99], v[216:219], v[208:211], v[84:99]
	v_mfma_f32_32x32x16_bf16 v[36:51], v[220:223], v[184:187], v[36:51]
	v_mfma_f32_32x32x16_bf16 v[100:115], v[220:223], v[208:211], v[100:115]
	v_mfma_f32_32x32x16_bf16 v[52:67], v[224:227], v[184:187], v[52:67]
	v_mfma_f32_32x32x16_bf16 v[116:131], v[224:227], v[208:211], v[116:131]
	ds_read_b128 v[184:187], v231 offset:32768
	ds_read_b128 v[208:211], v231 offset:36864
	ds_read_b128 v[212:215], v235 offset:32768
	ds_read_b128 v[216:219], v235 offset:36864
	ds_read_b128 v[220:223], v235 offset:49152
	ds_read_b128 v[224:227], v235 offset:53248
	s_waitcnt lgkmcnt(6)
	v_mfma_f32_32x32x16_bf16 v[4:19], v[140:143], v[132:135], v[4:19]
	v_mfma_f32_32x32x16_bf16 v[68:83], v[140:143], v[136:139], v[68:83]
	v_mfma_f32_32x32x16_bf16 v[20:35], v[144:147], v[132:135], v[20:35]
	v_mfma_f32_32x32x16_bf16 v[84:99], v[144:147], v[136:139], v[84:99]
	v_mfma_f32_32x32x16_bf16 v[36:51], v[148:151], v[132:135], v[36:51]
	v_mfma_f32_32x32x16_bf16 v[100:115], v[148:151], v[136:139], v[100:115]
	v_mfma_f32_32x32x16_bf16 v[52:67], v[180:183], v[132:135], v[52:67]
	v_mfma_f32_32x32x16_bf16 v[116:131], v[180:183], v[136:139], v[116:131]
	s_waitcnt lgkmcnt(0)
	v_mfma_f32_32x32x16_bf16 v[4:19], v[212:215], v[184:187], v[4:19]
	v_mfma_f32_32x32x16_bf16 v[68:83], v[212:215], v[208:211], v[68:83]
	v_mfma_f32_32x32x16_bf16 v[20:35], v[216:219], v[184:187], v[20:35]
	v_mfma_f32_32x32x16_bf16 v[84:99], v[216:219], v[208:211], v[84:99]
	v_mfma_f32_32x32x16_bf16 v[36:51], v[220:223], v[184:187], v[36:51]
	v_mfma_f32_32x32x16_bf16 v[100:115], v[220:223], v[208:211], v[100:115]
	v_mfma_f32_32x32x16_bf16 v[52:67], v[224:227], v[184:187], v[52:67]
	v_mfma_f32_32x32x16_bf16 v[116:131], v[224:227], v[208:211], v[116:131]
	s_waitcnt vmcnt(0) lgkmcnt(0)
	s_barrier
	ds_read_b128 v[132:135], v228 offset:0
	ds_read_b128 v[136:139], v228 offset:4096
	ds_read_b128 v[140:143], v232 offset:0
	ds_read_b128 v[144:147], v232 offset:4096
	ds_read_b128 v[148:151], v232 offset:16384
	ds_read_b128 v[180:183], v232 offset:20480
	s_mov_b32 m0, s45
	s_nop 0
	global_load_lds_dwordx4 v178, s[68:69]
	global_load_lds_dwordx4 v179, s[70:71] offset:1024
	global_load_lds_dwordx4 v178, s[72:73] offset:2048
	global_load_lds_dwordx4 v179, s[74:75] offset:3072
	ds_read_b128 v[184:187], v229 offset:0
	ds_read_b128 v[208:211], v229 offset:4096
	ds_read_b128 v[212:215], v233 offset:0
	ds_read_b128 v[216:219], v233 offset:4096
	ds_read_b128 v[220:223], v233 offset:16384
	ds_read_b128 v[224:227], v233 offset:20480
	s_waitcnt lgkmcnt(6)
	v_mfma_f32_32x32x16_bf16 v[4:19], v[140:143], v[132:135], v[4:19]
	v_mfma_f32_32x32x16_bf16 v[68:83], v[140:143], v[136:139], v[68:83]
	v_mfma_f32_32x32x16_bf16 v[20:35], v[144:147], v[132:135], v[20:35]
	v_mfma_f32_32x32x16_bf16 v[84:99], v[144:147], v[136:139], v[84:99]
	v_mfma_f32_32x32x16_bf16 v[36:51], v[148:151], v[132:135], v[36:51]
	v_mfma_f32_32x32x16_bf16 v[100:115], v[148:151], v[136:139], v[100:115]
	v_mfma_f32_32x32x16_bf16 v[52:67], v[180:183], v[132:135], v[52:67]
	v_mfma_f32_32x32x16_bf16 v[116:131], v[180:183], v[136:139], v[116:131]
	s_mov_b32 m0, s47
	s_nop 0
	global_load_lds_dwordx4 v178, s[76:77]
	global_load_lds_dwordx4 v179, s[78:79] offset:1024
	global_load_lds_dwordx4 v178, s[80:81] offset:2048
	global_load_lds_dwordx4 v179, s[82:83] offset:3072
	v_add_u32_e32 v178, 0x80, v178
	v_add_u32_e32 v179, 0x80, v179
	ds_read_b128 v[132:135], v230 offset:0
	ds_read_b128 v[136:139], v230 offset:4096
	ds_read_b128 v[140:143], v234 offset:0
	ds_read_b128 v[144:147], v234 offset:4096
	ds_read_b128 v[148:151], v234 offset:16384
	ds_read_b128 v[180:183], v234 offset:20480
	s_waitcnt lgkmcnt(6)
; #define MFMA32(a, b, c) __builtin_amdgcn_mfma_f32_32x32x16_bf16((a), (b), (c), 0, 0, 0)
; template <bool SWAP, class Epi>
; DI void gemm_tile(const u16* __restrict__ A, int lda, const u16* __restrict__ Bw, int ldb, int K, char* lds, Epi epi) {
;     ...
;     for (int ks = 0; ks < 4; ++ks) {
;       bf16x8 af[2], bfr[2];
; #pragma unroll
;       for (int mi = 0; mi < 2; ++mi) af[mi] = *(const bf16x8*)(as + ((wm * 64 + mi * 32 + r) * 72 + ks * 16 + 8 * h) * 2);
; #pragma unroll
;       for (int ni = 0; ni < 2; ++ni) bfr[ni] = *(const bf16x8*)(bs + ((wn * 64 + ni * 32 + r) * 72 + ks * 16 + 8 * h) * 2);
; #pragma unroll
;       for (int mi = 0; mi < 2; ++mi)
; #pragma unroll
;         for (int ni = 0; ni < 2; ++ni) {
;           if (SWAP) acc[mi][ni] = MFMA32(bfr[ni], af[mi], acc[mi][ni]);
;           else acc[mi][ni] = MFMA32(af[mi], bfr[ni], acc[mi][ni]);
;         }
;     }
;   };
;   gload(0, ra0, rb0);
;   lstore(0, ra0, rb0);
;   gload(1, ra1, rb1);
;   __syncthreads();
;   for (int kt = 0; kt < nk; kt += 2) {
;     if (kt + 2 < nk) gload(kt + 2, ra0, rb0);
;     compute(0);
;     lstore(1, ra1, rb1);
;     __syncthreads();
;     if (kt + 3 < nk) gload(kt + 3, ra1, rb1);
;     compute(1);
;     if (kt + 2 < nk) lstore(0, ra0, rb0);
;     __syncthreads();
	v_mfma_f32_32x32x16_bf16 v[4:19], v[212:215], v[184:187], v[4:19]
	v_mfma_f32_32x32x16_bf16 v[68:83], v[212:215], v[208:211], v[68:83]
	v_mfma_f32_32x32x16_bf16 v[20:35], v[216:219], v[184:187], v[20:35]
	v_mfma_f32_32x32x16_bf16 v[84:99], v[216:219], v[208:211], v[84:99]
	v_mfma_f32_32x32x16_bf16 v[36:51], v[220:223], v[184:187], v[36:51]
	v_mfma_f32_32x32x16_bf16 v[100:115], v[220:223], v[208:211], v[100:115]
	v_mfma_f32_32x32x16_bf16 v[52:67], v[224:227], v[184:187], v[52:67]
	v_mfma_f32_32x32x16_bf16 v[116:131], v[224:227], v[208:211], v[116:131]
	ds_read_b128 v[184:187], v231 offset:0
	ds_read_b128 v[208:211], v231 offset:4096
	ds_read_b128 v[212:215], v235 offset:0
	ds_read_b128 v[216:219], v235 offset:4096
	ds_read_b128 v[220:223], v235 offset:16384
	ds_read_b128 v[224:227], v235 offset:20480
	s_waitcnt lgkmcnt(6)
	v_mfma_f32_32x32x16_bf16 v[4:19], v[140:143], v[132:135], v[4:19]
	v_mfma_f32_32x32x16_bf16 v[68:83], v[140:143], v[136:139], v[68:83]
	v_mfma_f32_32x32x16_bf16 v[20:35], v[144:147], v[132:135], v[20:35]
	v_mfma_f32_32x32x16_bf16 v[84:99], v[144:147], v[136:139], v[84:99]
	v_mfma_f32_32x32x16_bf16 v[36:51], v[148:151], v[132:135], v[36:51]
	v_mfma_f32_32x32x16_bf16 v[100:115], v[148:151], v[136:139], v[100:115]
	v_mfma_f32_32x32x16_bf16 v[52:67], v[180:183], v[132:135], v[52:67]
	v_mfma_f32_32x32x16_bf16 v[116:131], v[180:183], v[136:139], v[116:131]
	s_waitcnt lgkmcnt(0)
	v_mfma_f32_32x32x16_bf16 v[4:19], v[212:215], v[184:187], v[4:19]
	v_mfma_f32_32x32x16_bf16 v[68:83], v[212:215], v[208:211], v[68:83]
	v_mfma_f32_32x32x16_bf16 v[20:35], v[216:219], v[184:187], v[20:35]
	v_mfma_f32_32x32x16_bf16 v[84:99], v[216:219], v[208:211], v[84:99]
	v_mfma_f32_32x32x16_bf16 v[36:51], v[220:223], v[184:187], v[36:51]
	v_mfma_f32_32x32x16_bf16 v[100:115], v[220:223], v[208:211], v[100:115]
	v_mfma_f32_32x32x16_bf16 v[52:67], v[224:227], v[184:187], v[52:67]
	v_mfma_f32_32x32x16_bf16 v[116:131], v[224:227], v[208:211], v[116:131]
	s_waitcnt vmcnt(0) lgkmcnt(0)
	s_barrier
	ds_read_b128 v[132:135], v228 offset:32768
	ds_read_b128 v[136:139], v228 offset:36864
	ds_read_b128 v[140:143], v232 offset:32768
	ds_read_b128 v[144:147], v232 offset:36864
	ds_read_b128 v[148:151], v232 offset:49152
	ds_read_b128 v[180:183], v232 offset:53248
	ds_read_b128 v[184:187], v229 offset:32768
	ds_read_b128 v[208:211], v229 offset:36864
	ds_read_b128 v[212:215], v233 offset:32768
	ds_read_b128 v[216:219], v233 offset:36864
	ds_read_b128 v[220:223], v233 offset:49152
	ds_read_b128 v[224:227], v233 offset:53248
	s_waitcnt lgkmcnt(6)
	v_mfma_f32_32x32x16_bf16 v[4:19], v[140:143], v[132:135], v[4:19]
	v_mfma_f32_32x32x16_bf16 v[68:83], v[140:143], v[136:139], v[68:83]
	v_mfma_f32_32x32x16_bf16 v[20:35], v[144:147], v[132:135], v[20:35]
	v_mfma_f32_32x32x16_bf16 v[84:99], v[144:147], v[136:139], v[84:99]
	v_mfma_f32_32x32x16_bf16 v[36:51], v[148:151], v[132:135], v[36:51]
	v_mfma_f32_32x32x16_bf16 v[100:115], v[148:151], v[136:139], v[100:115]
	v_mfma_f32_32x32x16_bf16 v[52:67], v[180:183], v[132:135], v[52:67]
	v_mfma_f32_32x32x16_bf16 v[116:131], v[180:183], v[136:139], v[116:131]
	ds_read_b128 v[132:135], v230 offset:32768
	ds_read_b128 v[136:139], v230 offset:36864
	ds_read_b128 v[140:143], v234 offset:32768
	ds_read_b128 v[144:147], v234 offset:36864
	ds_read_b128 v[148:151], v234 offset:49152
	ds_read_b128 v[180:183], v234 offset:53248
	s_waitcnt lgkmcnt(6)
	v_mfma_f32_32x32x16_bf16 v[4:19], v[212:215], v[184:187], v[4:19]
	v_mfma_f32_32x32x16_bf16 v[68:83], v[212:215], v[208:211], v[68:83]
	v_mfma_f32_32x32x16_bf16 v[20:35], v[216:219], v[184:187], v[20:35]
	v_mfma_f32_32x32x16_bf16 v[84:99], v[216:219], v[208:211], v[84:99]
	v_mfma_f32_32x32x16_bf16 v[36:51], v[220:223], v[184:187], v[36:51]
	v_mfma_f32_32x32x16_bf16 v[100:115], v[220:223], v[208:211], v[100:115]
	v_mfma_f32_32x32x16_bf16 v[52:67], v[224:227], v[184:187], v[52:67]
	v_mfma_f32_32x32x16_bf16 v[116:131], v[224:227], v[208:211], v[116:131]
	ds_read_b128 v[184:187], v231 offset:32768
	ds_read_b128 v[208:211], v231 offset:36864
	ds_read_b128 v[212:215], v235 offset:32768
	ds_read_b128 v[216:219], v235 offset:36864
	ds_read_b128 v[220:223], v235 offset:49152
	ds_read_b128 v[224:227], v235 offset:53248
	s_waitcnt lgkmcnt(6)
	v_mfma_f32_32x32x16_bf16 v[4:19], v[140:143], v[132:135], v[4:19]
	v_mfma_f32_32x32x16_bf16 v[68:83], v[140:143], v[136:139], v[68:83]
	v_mfma_f32_32x32x16_bf16 v[20:35], v[144:147], v[132:135], v[20:35]
	v_mfma_f32_32x32x16_bf16 v[84:99], v[144:147], v[136:139], v[84:99]
	v_mfma_f32_32x32x16_bf16 v[36:51], v[148:151], v[132:135], v[36:51]
	v_mfma_f32_32x32x16_bf16 v[100:115], v[148:151], v[136:139], v[100:115]
	v_mfma_f32_32x32x16_bf16 v[52:67], v[180:183], v[132:135], v[52:67]
	v_mfma_f32_32x32x16_bf16 v[116:131], v[180:183], v[136:139], v[116:131]
	s_waitcnt lgkmcnt(0)
	v_mfma_f32_32x32x16_bf16 v[4:19], v[212:215], v[184:187], v[4:19]
	v_mfma_f32_32x32x16_bf16 v[68:83], v[212:215], v[208:211], v[68:83]
	v_mfma_f32_32x32x16_bf16 v[20:35], v[216:219], v[184:187], v[20:35]
	v_mfma_f32_32x32x16_bf16 v[84:99], v[216:219], v[208:211], v[84:99]
	v_mfma_f32_32x32x16_bf16 v[36:51], v[220:223], v[184:187], v[36:51]
	v_mfma_f32_32x32x16_bf16 v[100:115], v[220:223], v[208:211], v[100:115]
	v_mfma_f32_32x32x16_bf16 v[52:67], v[224:227], v[184:187], v[52:67]
	v_mfma_f32_32x32x16_bf16 v[116:131], v[224:227], v[208:211], v[116:131]
	s_waitcnt lgkmcnt(0)
	s_barrier
; DI void outproj_tile(const Params& p, int l, int mt, int nt, char* lds, int khalf) {
;     ...
;       const int tok = m0 + wm * 64 + mi * 32 + r;
;       float* rp = p.R + (size_t)tok * DM + nt * 128 + wn * 64 + ni * 32;
; #pragma unroll
;       for (int g = 0; g < 4; ++g) {
;         f32x4 v = *(const f32x4*)(rp + 8 * g + 4 * h);
; #pragma unroll
;         for (int e = 0; e < 4; ++e) v[e] = ALPHA * v[e] + a[4 * g + e];
;         *(f32x4*)(rp + 8 * g + 4 * h) = v;
;       }
	s_mov_b32 s16, 0x3fd744fd
	s_nop 7
	s_nop 7
	global_load_dwordx4 v[132:135], v242, s[24:25]
	global_load_dwordx4 v[136:139], v242, s[24:25] offset:32
	global_load_dwordx4 v[140:143], v242, s[24:25] offset:64
	global_load_dwordx4 v[144:147], v242, s[24:25] offset:96
	global_load_dwordx4 v[148:151], v242, s[24:25] offset:128
	global_load_dwordx4 v[180:183], v242, s[24:25] offset:160
	global_load_dwordx4 v[184:187], v242, s[24:25] offset:192
	global_load_dwordx4 v[208:211], v242, s[24:25] offset:224
	s_waitcnt vmcnt(7)
	v_pk_fma_f32 v[4:5], v[132:133], s[16:17], v[4:5] op_sel_hi:[1,0,1]
	v_pk_fma_f32 v[6:7], v[134:135], s[16:17], v[6:7] op_sel_hi:[1,0,1]
	global_store_dwordx4 v242, v[4:7], s[24:25]
	s_waitcnt vmcnt(7)
	v_pk_fma_f32 v[8:9], v[136:137], s[16:17], v[8:9] op_sel_hi:[1,0,1]
	v_pk_fma_f32 v[10:11], v[138:139], s[16:17], v[10:11] op_sel_hi:[1,0,1]
	global_store_dwordx4 v242, v[8:11], s[24:25] offset:32
	s_waitcnt vmcnt(7)
	v_pk_fma_f32 v[12:13], v[140:141], s[16:17], v[12:13] op_sel_hi:[1,0,1]
	v_pk_fma_f32 v[14:15], v[142:143], s[16:17], v[14:15] op_sel_hi:[1,0,1]
	global_store_dwordx4 v242, v[12:15], s[24:25] offset:64
	s_waitcnt vmcnt(7)
	v_pk_fma_f32 v[16:17], v[144:145], s[16:17], v[16:17] op_sel_hi:[1,0,1]
	v_pk_fma_f32 v[18:19], v[146:147], s[16:17], v[18:19] op_sel_hi:[1,0,1]
	global_store_dwordx4 v242, v[16:19], s[24:25] offset:96
	s_waitcnt vmcnt(7)
	v_pk_fma_f32 v[20:21], v[148:149], s[16:17], v[20:21] op_sel_hi:[1,0,1]
	v_pk_fma_f32 v[22:23], v[150:151], s[16:17], v[22:23] op_sel_hi:[1,0,1]
	global_store_dwordx4 v242, v[20:23], s[24:25] offset:128
	s_waitcnt vmcnt(7)
	v_pk_fma_f32 v[24:25], v[180:181], s[16:17], v[24:25] op_sel_hi:[1,0,1]
	v_pk_fma_f32 v[26:27], v[182:183], s[16:17], v[26:27] op_sel_hi:[1,0,1]
	global_store_dwordx4 v242, v[24:27], s[24:25] offset:160
	s_waitcnt vmcnt(7)
	v_pk_fma_f32 v[28:29], v[184:185], s[16:17], v[28:29] op_sel_hi:[1,0,1]
	v_pk_fma_f32 v[30:31], v[186:187], s[16:17], v[30:31] op_sel_hi:[1,0,1]
	global_store_dwordx4 v242, v[28:31], s[24:25] offset:192
	s_waitcnt vmcnt(7)
	v_pk_fma_f32 v[32:33], v[208:209], s[16:17], v[32:33] op_sel_hi:[1,0,1]
	v_pk_fma_f32 v[34:35], v[210:211], s[16:17], v[34:35] op_sel_hi:[1,0,1]
	global_store_dwordx4 v242, v[32:35], s[24:25] offset:224
	global_load_dwordx4 v[132:135], v242, s[24:25] offset:512
	global_load_dwordx4 v[136:139], v242, s[24:25] offset:544
	global_load_dwordx4 v[140:143], v242, s[24:25] offset:576
	global_load_dwordx4 v[144:147], v242, s[24:25] offset:608
	global_load_dwordx4 v[148:151], v242, s[24:25] offset:640
	global_load_dwordx4 v[180:183], v242, s[24:25] offset:672
	global_load_dwordx4 v[184:187], v242, s[24:25] offset:704
	global_load_dwordx4 v[208:211], v242, s[24:25] offset:736
	s_waitcnt vmcnt(7)
	v_pk_fma_f32 v[36:37], v[132:133], s[16:17], v[36:37] op_sel_hi:[1,0,1]
	v_pk_fma_f32 v[38:39], v[134:135], s[16:17], v[38:39] op_sel_hi:[1,0,1]
	global_store_dwordx4 v242, v[36:39], s[24:25] offset:512
	s_waitcnt vmcnt(7)
	v_pk_fma_f32 v[40:41], v[136:137], s[16:17], v[40:41] op_sel_hi:[1,0,1]
	v_pk_fma_f32 v[42:43], v[138:139], s[16:17], v[42:43] op_sel_hi:[1,0,1]
	global_store_dwordx4 v242, v[40:43], s[24:25] offset:544
	s_waitcnt vmcnt(7)
	v_pk_fma_f32 v[44:45], v[140:141], s[16:17], v[44:45] op_sel_hi:[1,0,1]
	v_pk_fma_f32 v[46:47], v[142:143], s[16:17], v[46:47] op_sel_hi:[1,0,1]
	global_store_dwordx4 v242, v[44:47], s[24:25] offset:576
	s_waitcnt vmcnt(7)
	v_pk_fma_f32 v[48:49], v[144:145], s[16:17], v[48:49] op_sel_hi:[1,0,1]
	v_pk_fma_f32 v[50:51], v[146:147], s[16:17], v[50:51] op_sel_hi:[1,0,1]
	global_store_dwordx4 v242, v[48:51], s[24:25] offset:608
	s_waitcnt vmcnt(7)
	v_pk_fma_f32 v[52:53], v[148:149], s[16:17], v[52:53] op_sel_hi:[1,0,1]
	v_pk_fma_f32 v[54:55], v[150:151], s[16:17], v[54:55] op_sel_hi:[1,0,1]
	global_store_dwordx4 v242, v[52:55], s[24:25] offset:640
	s_waitcnt vmcnt(7)
	v_pk_fma_f32 v[56:57], v[180:181], s[16:17], v[56:57] op_sel_hi:[1,0,1]
	v_pk_fma_f32 v[58:59], v[182:183], s[16:17], v[58:59] op_sel_hi:[1,0,1]
	global_store_dwordx4 v242, v[56:59], s[24:25] offset:672
	s_waitcnt vmcnt(7)
	v_pk_fma_f32 v[60:61], v[184:185], s[16:17], v[60:61] op_sel_hi:[1,0,1]
	v_pk_fma_f32 v[62:63], v[186:187], s[16:17], v[62:63] op_sel_hi:[1,0,1]
	global_store_dwordx4 v242, v[60:63], s[24:25] offset:704
	s_waitcnt vmcnt(7)
	v_pk_fma_f32 v[64:65], v[208:209], s[16:17], v[64:65] op_sel_hi:[1,0,1]
	v_pk_fma_f32 v[66:67], v[210:211], s[16:17], v[66:67] op_sel_hi:[1,0,1]
	global_store_dwordx4 v242, v[64:67], s[24:25] offset:736
	global_load_dwordx4 v[132:135], v243, s[24:25]
	global_load_dwordx4 v[136:139], v243, s[24:25] offset:32
	global_load_dwordx4 v[140:143], v243, s[24:25] offset:64
	global_load_dwordx4 v[144:147], v243, s[24:25] offset:96
	global_load_dwordx4 v[148:151], v243, s[24:25] offset:128
	global_load_dwordx4 v[180:183], v243, s[24:25] offset:160
	global_load_dwordx4 v[184:187], v243, s[24:25] offset:192
	global_load_dwordx4 v[208:211], v243, s[24:25] offset:224
	s_waitcnt vmcnt(7)
	v_pk_fma_f32 v[68:69], v[132:133], s[16:17], v[68:69] op_sel_hi:[1,0,1]
	v_pk_fma_f32 v[70:71], v[134:135], s[16:17], v[70:71] op_sel_hi:[1,0,1]
	global_store_dwordx4 v243, v[68:71], s[24:25]
	s_waitcnt vmcnt(7)
	v_pk_fma_f32 v[72:73], v[136:137], s[16:17], v[72:73] op_sel_hi:[1,0,1]
	v_pk_fma_f32 v[74:75], v[138:139], s[16:17], v[74:75] op_sel_hi:[1,0,1]
	global_store_dwordx4 v243, v[72:75], s[24:25] offset:32
	s_waitcnt vmcnt(7)
	v_pk_fma_f32 v[76:77], v[140:141], s[16:17], v[76:77] op_sel_hi:[1,0,1]
	v_pk_fma_f32 v[78:79], v[142:143], s[16:17], v[78:79] op_sel_hi:[1,0,1]
	global_store_dwordx4 v243, v[76:79], s[24:25] offset:64
	s_waitcnt vmcnt(7)
; DI void outproj_tile(const Params& p, int l, int mt, int nt, char* lds, int khalf) {
;     ...
;       const int tok = m0 + wm * 64 + mi * 32 + r;
;       float* rp = p.R + (size_t)tok * DM + nt * 128 + wn * 64 + ni * 32;
; #pragma unroll
;       for (int g = 0; g < 4; ++g) {
;         f32x4 v = *(const f32x4*)(rp + 8 * g + 4 * h);
; #pragma unroll
;         for (int e = 0; e < 4; ++e) v[e] = ALPHA * v[e] + a[4 * g + e];
;         *(f32x4*)(rp + 8 * g + 4 * h) = v;
;       }
; __global__ void __launch_bounds__(NTHREADS) mega(Params p) {
;     ...
;     for (int j = blockIdx.x; j < 512; j += gridDim.x) {
;       const int x = j & 7, a = j >> 3;
;       outproj_tile(p, l, 2 * (a >> 1) + (x >> 2), 2 * (x & 3) + (a & 1), lds, -1);
;     }
;     if (blockIdx.x < 64) {
;       const int j = 512 + (blockIdx.x >> 2), x = j & 7, a = j >> 3;
;       outproj_tile(p, l, 2 * (a >> 1) + (x >> 2), 2 * (x & 3) + (a & 1), lds, blockIdx.x & 3);
	v_pk_fma_f32 v[80:81], v[144:145], s[16:17], v[80:81] op_sel_hi:[1,0,1]
	v_pk_fma_f32 v[82:83], v[146:147], s[16:17], v[82:83] op_sel_hi:[1,0,1]
	global_store_dwordx4 v243, v[80:83], s[24:25] offset:96
	s_waitcnt vmcnt(7)
	v_pk_fma_f32 v[84:85], v[148:149], s[16:17], v[84:85] op_sel_hi:[1,0,1]
	v_pk_fma_f32 v[86:87], v[150:151], s[16:17], v[86:87] op_sel_hi:[1,0,1]
	global_store_dwordx4 v243, v[84:87], s[24:25] offset:128
	s_waitcnt vmcnt(7)
	v_pk_fma_f32 v[88:89], v[180:181], s[16:17], v[88:89] op_sel_hi:[1,0,1]
	v_pk_fma_f32 v[90:91], v[182:183], s[16:17], v[90:91] op_sel_hi:[1,0,1]
	global_store_dwordx4 v243, v[88:91], s[24:25] offset:160
	s_waitcnt vmcnt(7)
	v_pk_fma_f32 v[92:93], v[184:185], s[16:17], v[92:93] op_sel_hi:[1,0,1]
	v_pk_fma_f32 v[94:95], v[186:187], s[16:17], v[94:95] op_sel_hi:[1,0,1]
	global_store_dwordx4 v243, v[92:95], s[24:25] offset:192
	s_waitcnt vmcnt(7)
	v_pk_fma_f32 v[96:97], v[208:209], s[16:17], v[96:97] op_sel_hi:[1,0,1]
	v_pk_fma_f32 v[98:99], v[210:211], s[16:17], v[98:99] op_sel_hi:[1,0,1]
	global_store_dwordx4 v243, v[96:99], s[24:25] offset:224
	global_load_dwordx4 v[132:135], v243, s[24:25] offset:512
	global_load_dwordx4 v[136:139], v243, s[24:25] offset:544
	global_load_dwordx4 v[140:143], v243, s[24:25] offset:576
	global_load_dwordx4 v[144:147], v243, s[24:25] offset:608
	global_load_dwordx4 v[148:151], v243, s[24:25] offset:640
	global_load_dwordx4 v[180:183], v243, s[24:25] offset:672
	global_load_dwordx4 v[184:187], v243, s[24:25] offset:704
	global_load_dwordx4 v[208:211], v243, s[24:25] offset:736
	s_waitcnt vmcnt(7)
	v_pk_fma_f32 v[100:101], v[132:133], s[16:17], v[100:101] op_sel_hi:[1,0,1]
	v_pk_fma_f32 v[102:103], v[134:135], s[16:17], v[102:103] op_sel_hi:[1,0,1]
	global_store_dwordx4 v243, v[100:103], s[24:25] offset:512
	s_waitcnt vmcnt(7)
	v_pk_fma_f32 v[104:105], v[136:137], s[16:17], v[104:105] op_sel_hi:[1,0,1]
	v_pk_fma_f32 v[106:107], v[138:139], s[16:17], v[106:107] op_sel_hi:[1,0,1]
	global_store_dwordx4 v243, v[104:107], s[24:25] offset:544
	s_waitcnt vmcnt(7)
	v_pk_fma_f32 v[108:109], v[140:141], s[16:17], v[108:109] op_sel_hi:[1,0,1]
	v_pk_fma_f32 v[110:111], v[142:143], s[16:17], v[110:111] op_sel_hi:[1,0,1]
	global_store_dwordx4 v243, v[108:111], s[24:25] offset:576
	s_waitcnt vmcnt(7)
	v_pk_fma_f32 v[112:113], v[144:145], s[16:17], v[112:113] op_sel_hi:[1,0,1]
	v_pk_fma_f32 v[114:115], v[146:147], s[16:17], v[114:115] op_sel_hi:[1,0,1]
	global_store_dwordx4 v243, v[112:115], s[24:25] offset:608
	s_waitcnt vmcnt(7)
	v_pk_fma_f32 v[116:117], v[148:149], s[16:17], v[116:117] op_sel_hi:[1,0,1]
	v_pk_fma_f32 v[118:119], v[150:151], s[16:17], v[118:119] op_sel_hi:[1,0,1]
	global_store_dwordx4 v243, v[116:119], s[24:25] offset:640
	s_waitcnt vmcnt(7)
	v_pk_fma_f32 v[120:121], v[180:181], s[16:17], v[120:121] op_sel_hi:[1,0,1]
	v_pk_fma_f32 v[122:123], v[182:183], s[16:17], v[122:123] op_sel_hi:[1,0,1]
	global_store_dwordx4 v243, v[120:123], s[24:25] offset:672
	s_waitcnt vmcnt(7)
	v_pk_fma_f32 v[124:125], v[184:185], s[16:17], v[124:125] op_sel_hi:[1,0,1]
	v_pk_fma_f32 v[126:127], v[186:187], s[16:17], v[126:127] op_sel_hi:[1,0,1]
	global_store_dwordx4 v243, v[124:127], s[24:25] offset:704
	s_waitcnt vmcnt(7)
	v_pk_fma_f32 v[128:129], v[208:209], s[16:17], v[128:129] op_sel_hi:[1,0,1]
	v_pk_fma_f32 v[130:131], v[210:211], s[16:17], v[130:131] op_sel_hi:[1,0,1]
	global_store_dwordx4 v243, v[128:131], s[24:25] offset:736
	v_readlane_b32 s9, v238, 16
	s_bfe_u32 s1, s9, 0x10003
	s_bfe_u32 s0, s9, 0x10002
	s_lshl_b32 s11, s0, 8
	s_lshl_b32 s2, s9, 1
	s_and_b32 s2, s2, 6
	s_or_b32 s10, s2, s1
	s_addk_i32 s9, 0x200
	v_readlane_b32 s0, v238, 18
	s_lshl_b32 s0, s0, 1
	s_add_i32 s8, s8, s0
	v_readlane_b32 s27, v240, 16
	v_readlane_b32 s12, v241, 40
	v_readlane_b32 s20, v240, 9
	v_readlane_b32 s22, v240, 11
	v_readlane_b32 s23, v240, 12
	v_readlane_b32 s13, v241, 41
	v_readlane_b32 s17, v241, 45
	s_branch .LBB0_2492
.LBB0_2483:
.LBB0_2484:
.LBB0_2485:
.LBB0_2486:
.LBB0_2488:
.LBB0_2490:
.LBB0_2492:
	v_readlane_b32 s2, v239, 5
	v_readlane_b32 s3, v239, 6
	s_and_b64 vcc, exec, s[2:3]
	v_readlane_b32 s2, v238, 52
	v_readlane_b32 s3, v238, 53
	s_mov_b64 s[0:1], -1
	s_mov_b32 s60, 0x20000
	v_cndmask_b32_e64 v0, 0, 1, s[2:3]
	v_cmp_ne_u32_e64 s[62:63], 1, v0
	s_cbranch_vccz .LBB0_2748
	s_and_b64 vcc, exec, s[62:63]
	s_cbranch_vccnz .LBB0_2747
	v_readlane_b32 s2, v239, 8
	v_readlane_b32 s3, v239, 9
	s_waitcnt vmcnt(1)
	v_mov_b32_e32 v18, v152
	s_andn2_b64 vcc, exec, s[2:3]
	v_cndmask_b32_e64 v0, 0, 1, s[2:3]
	v_and_b32_e32 v28, 63, v18
	v_cmp_ne_u32_e64 s[0:1], 1, v0
	s_cbranch_vccnz .LBB0_2501
	v_readlane_b32 s2, v239, 10
	v_readlane_b32 s3, v239, 11
	s_andn2_b64 vcc, exec, s[2:3]
	s_cbranch_vccnz .LBB0_2502
	v_readlane_b32 s2, v239, 12
	v_readlane_b32 s3, v239, 13
	s_mov_b64 s[4:5], -1
	s_and_b64 vcc, exec, s[2:3]
	s_cbranch_vccz .LBB0_2505
	v_readlane_b32 s4, v239, 14
	v_readlane_b32 s5, v239, 15
	s_and_b64 vcc, exec, s[4:5]
	v_readlane_b32 s16, v241, 20
	v_readlane_b32 s17, v241, 21
	s_mov_b64 s[2:3], -1
	s_mov_b64 s[6:7], s[16:17]
	s_mov_b64 s[4:5], -1
	v_readlane_b32 s22, v241, 26
	v_readlane_b32 s23, v241, 27
	v_readlane_b32 s27, v241, 31
	s_cbranch_vccz .LBB0_2499
	v_readlane_b32 s4, v238, 50
	v_readlane_b32 s8, v241, 49
	s_mov_b32 s6, s4
	s_lshl_b32 s4, s4, 19
	v_readlane_b32 s12, v241, 53
	v_readlane_b32 s13, v241, 54
	s_add_u32 s4, s12, s4
	s_addc_u32 s5, s13, 0
	v_writelane_b32 v238, s4, 48
	s_lshl_b32 s60, s6, 7
	v_writelane_b32 v238, s5, 49
	s_lshl_b64 s[4:5], s[60:61], 2
	v_readlane_b32 s9, v241, 50
	s_add_u32 s10, s8, s4
	v_readlane_b32 s18, v241, 22
	v_readlane_b32 s19, v241, 23
	s_addc_u32 s11, s9, s5
	s_mov_b64 s[4:5], 0
	v_readlane_b32 s17, v241, 21
	v_readlane_b32 s22, v241, 26
	v_readlane_b32 s23, v241, 27
	v_readlane_b32 s27, v241, 31
	s_mov_b64 s[6:7], s[18:19]
